# on top of accumulate-chain order: deleted all s_setprio 1/0 pairs in the 8 GEMM K-loops
# speedup vs baseline: 1.0117x; 1.0027x over previous
; #define PG8_LDA(dst, b, h) do { _Pragma("unroll") for (int m = 0; m < 4; ++m) _Pragma("unroll") for (int k = 0; k < 2; ++k) dst[m][k] = *(const PG8_LAS bf16x8*)(lds + PG8_SA(b, h) + aoff + m * 2048 + k * 1024); } while (0)
; #define PG8_LDB(dst, b, h) do { _Pragma("unroll") for (int n = 0; n < 2; ++n) _Pragma("unroll") for (int k = 0; k < 2; ++k) dst[n][k] = *(const PG8_LAS bf16x8*)(lds + PG8_SB(b, h) + boff + n * 2048 + k * 1024); } while (0)
; #define PG8_MMA(ai, bj, At, Bt) do { __builtin_amdgcn_s_setprio(1); _Pragma("unroll") for (int m = 0; m < 4; ++m) _Pragma("unroll") for (int n = 0; n < 2; ++n) _Pragma("unroll") for (int k = 0; k < 2; ++k) \
;         acc[ai][bj][m][n] = __builtin_amdgcn_mfma_f32_16x16x32_bf16(Bt[n][k], At[m][k], acc[ai][bj][m][n], 0, 0, 0); __builtin_amdgcn_s_setprio(0); } while (0)
; #define PG8_WAIT_V(n) asm volatile("s_waitcnt vmcnt(" #n ")" ::: "memory")
; #define PG8_WAIT_L(n) asm volatile("s_waitcnt lgkmcnt(" #n ")" ::: "memory")
; #define PG8_BAR __builtin_amdgcn_s_barrier()
; #define PG8_SCHED __builtin_amdgcn_sched_barrier(0)
; template <class Epi, class Sched, bool ALIGN_EPI = false, bool SP2 = false>
; __device__ __forceinline__ void gemm_phase(PG8_LAS unsigned char* lds, const Gemm g, const Sched& S, const Epi& E, const int tid) {
;     ...
;             const char* a1 = cA + (size_t)(t + 1) * kstepA;
;             const char* a2 = last ? nA : cA + (size_t)(t + 2) * kstepA; const char* b2 = last ? nB : cB + (size_t)(t + 2) * kstepB;
;             const char* a3 = a2 + kstepA; const char* b3 = b2 + kstepB;
;             if (last && has_next) S.a_ready(nxt);
;             if constexpr (SP2) {
;             PG8_LDB(B0, 0, 0); PG8_LDB(B1, 0, 1); PG8_SCHED; PG8_LDA(At, 0, 0); PG8_STAGE(PG8_SA(1, 1), a1 + hstepA, voffA);
;             PG8_WAIT_V(8); PG8_WAIT_L(0); PG8_BAR; PG8_MMA(0, 0, At, B0); PG8_MMA(0, 1, At, B1); PG8_BAR; PG8_SCHED;
;             PG8_LDA(At, 0, 1); PG8_STAGE(PG8_SB(0, 0), b2, voffB); PG8_STAGE(PG8_SB(0, 1), b2 + hstepB, voffB); PG8_STAGE(PG8_SA(0, 0), a2, voffA);
;             PG8_WAIT_V(8); PG8_WAIT_L(0); PG8_BAR; PG8_MMA(1, 0, At, B0); PG8_MMA(1, 1, At, B1); PG8_BAR; PG8_SCHED;
.LBB0_380:
	s_or_b64 exec, exec, s[34:35]
	v_add_u32_e32 v145, 0x10000, v154
	ds_read_b128 v[156:159], v145
	ds_read_b128 v[160:163], v145 offset:1024
	ds_read_b128 v[164:167], v145 offset:2048
	ds_read_b128 v[168:171], v145 offset:3072
	v_add_u32_e32 v145, 0x14000, v154
	s_add_u32 s34, s28, 0x100
	ds_read_b128 v[172:175], v145
	ds_read_b128 v[176:179], v145 offset:1024
	ds_read_b128 v[180:183], v145 offset:2048
	ds_read_b128 v[184:187], v145 offset:3072
	s_addc_u32 s35, s29, 0
	s_and_b64 s[30:31], s[30:31], exec
	s_cselect_b32 s42, s91, s34
	s_cselect_b32 s43, s17, s35
	s_cselect_b32 s31, s15, s97
	s_cselect_b32 s30, s95, s96
	s_add_u32 s38, s42, 0x80
	s_addc_u32 s39, s43, 0
	s_add_u32 s40, s30, 0x80
	s_addc_u32 s41, s31, 0
	ds_read_b128 v[188:191], v155
	ds_read_b128 v[192:195], v155 offset:1024
	ds_read_b128 v[196:199], v155 offset:2048
	ds_read_b128 v[200:203], v155 offset:3072
	ds_read_b128 v[204:207], v155 offset:4096
	ds_read_b128 v[208:211], v155 offset:5120
	ds_read_b128 v[212:215], v155 offset:6144
	ds_read_b128 v[216:219], v155 offset:7168
	s_add_u32 s28, s28, 0x80080
	s_addc_u32 s29, s29, 0
	s_mov_b32 m0, s69
	s_nop 0
	global_load_lds_dwordx4 v149, s[28:29]
	s_nop 0
	s_mov_b32 m0, s58
	s_nop 0
	global_load_lds_dwordx4 v151, s[28:29]
	s_waitcnt vmcnt(8)
	s_waitcnt lgkmcnt(0)
	s_barrier
	v_mfma_f32_16x16x32_bf16 v[126:129], v[156:159], v[188:191], v[126:129]
	v_mfma_f32_16x16x32_bf16 v[126:129], v[160:163], v[192:195], v[126:129]
	v_mfma_f32_16x16x32_bf16 v[122:125], v[164:167], v[188:191], v[122:125]
	v_mfma_f32_16x16x32_bf16 v[122:125], v[168:171], v[192:195], v[122:125]
	v_mfma_f32_16x16x32_bf16 v[110:113], v[156:159], v[196:199], v[110:113]
	v_mfma_f32_16x16x32_bf16 v[110:113], v[160:163], v[200:203], v[110:113]
	v_mfma_f32_16x16x32_bf16 v[106:109], v[164:167], v[196:199], v[106:109]
	v_mfma_f32_16x16x32_bf16 v[106:109], v[168:171], v[200:203], v[106:109]
	v_mfma_f32_16x16x32_bf16 v[94:97], v[156:159], v[204:207], v[94:97]
	v_mfma_f32_16x16x32_bf16 v[94:97], v[160:163], v[208:211], v[94:97]
	v_mfma_f32_16x16x32_bf16 v[90:93], v[164:167], v[204:207], v[90:93]
	v_mfma_f32_16x16x32_bf16 v[90:93], v[168:171], v[208:211], v[90:93]
	v_mfma_f32_16x16x32_bf16 v[78:81], v[156:159], v[212:215], v[78:81]
	v_mfma_f32_16x16x32_bf16 v[78:81], v[160:163], v[216:219], v[78:81]
	v_mfma_f32_16x16x32_bf16 v[74:77], v[164:167], v[212:215], v[74:77]
	v_mfma_f32_16x16x32_bf16 v[74:77], v[168:171], v[216:219], v[74:77]
	v_mfma_f32_16x16x32_bf16 v[118:121], v[172:175], v[188:191], v[118:121]
	v_mfma_f32_16x16x32_bf16 v[118:121], v[176:179], v[192:195], v[118:121]
	v_mfma_f32_16x16x32_bf16 v[114:117], v[180:183], v[188:191], v[114:117]
	v_mfma_f32_16x16x32_bf16 v[114:117], v[184:187], v[192:195], v[114:117]
	v_mfma_f32_16x16x32_bf16 v[102:105], v[172:175], v[196:199], v[102:105]
	v_mfma_f32_16x16x32_bf16 v[102:105], v[176:179], v[200:203], v[102:105]
	v_mfma_f32_16x16x32_bf16 v[98:101], v[180:183], v[196:199], v[98:101]
	v_mfma_f32_16x16x32_bf16 v[98:101], v[184:187], v[200:203], v[98:101]
	v_mfma_f32_16x16x32_bf16 v[86:89], v[172:175], v[204:207], v[86:89]
	v_mfma_f32_16x16x32_bf16 v[86:89], v[176:179], v[208:211], v[86:89]
	v_mfma_f32_16x16x32_bf16 v[82:85], v[180:183], v[204:207], v[82:85]
	v_mfma_f32_16x16x32_bf16 v[82:85], v[184:187], v[208:211], v[82:85]
	v_mfma_f32_16x16x32_bf16 v[70:73], v[172:175], v[212:215], v[70:73]
	v_mfma_f32_16x16x32_bf16 v[70:73], v[176:179], v[216:219], v[70:73]
	v_mfma_f32_16x16x32_bf16 v[66:69], v[180:183], v[212:215], v[66:69]
	v_mfma_f32_16x16x32_bf16 v[66:69], v[184:187], v[216:219], v[66:69]
	s_barrier
	ds_read_b128 v[188:191], v155 offset:16384
	ds_read_b128 v[192:195], v155 offset:17408
	ds_read_b128 v[196:199], v155 offset:18432
	ds_read_b128 v[200:203], v155 offset:19456
	ds_read_b128 v[204:207], v155 offset:20480
	ds_read_b128 v[208:211], v155 offset:21504
	ds_read_b128 v[212:215], v155 offset:22528
	ds_read_b128 v[216:219], v155 offset:23552
	s_mov_b32 m0, s23
	s_nop 0
	global_load_lds_dwordx4 v150, s[30:31]
	s_add_u32 s28, s30, 0x80000
	s_mov_b32 m0, s25
	s_nop 0
	global_load_lds_dwordx4 v152, s[30:31]
	s_addc_u32 s29, s31, 0
	s_mov_b32 m0, s48
	s_nop 0
	global_load_lds_dwordx4 v150, s[28:29]
	s_nop 0
	s_mov_b32 m0, s49
	s_nop 0
	global_load_lds_dwordx4 v152, s[28:29]
	s_nop 0
	s_mov_b32 m0, s10
	s_nop 0
	global_load_lds_dwordx4 v149, s[42:43]
	s_nop 0
	s_mov_b32 m0, s50
	s_nop 0
	global_load_lds_dwordx4 v151, s[42:43]
	s_waitcnt vmcnt(8)
	s_waitcnt lgkmcnt(0)
	s_barrier
	v_mfma_f32_16x16x32_bf16 v[62:65], v[156:159], v[188:191], v[62:65]
	v_mfma_f32_16x16x32_bf16 v[62:65], v[160:163], v[192:195], v[62:65]
	v_mfma_f32_16x16x32_bf16 v[58:61], v[164:167], v[188:191], v[58:61]
	v_mfma_f32_16x16x32_bf16 v[58:61], v[168:171], v[192:195], v[58:61]
	v_mfma_f32_16x16x32_bf16 v[46:49], v[156:159], v[196:199], v[46:49]
	v_mfma_f32_16x16x32_bf16 v[46:49], v[160:163], v[200:203], v[46:49]
	v_mfma_f32_16x16x32_bf16 v[42:45], v[164:167], v[196:199], v[42:45]
	v_mfma_f32_16x16x32_bf16 v[42:45], v[168:171], v[200:203], v[42:45]
	v_mfma_f32_16x16x32_bf16 v[30:33], v[156:159], v[204:207], v[30:33]
	v_mfma_f32_16x16x32_bf16 v[30:33], v[160:163], v[208:211], v[30:33]
	v_mfma_f32_16x16x32_bf16 v[26:29], v[164:167], v[204:207], v[26:29]
	v_mfma_f32_16x16x32_bf16 v[26:29], v[168:171], v[208:211], v[26:29]
	v_mfma_f32_16x16x32_bf16 v[14:17], v[156:159], v[212:215], v[14:17]
	v_mfma_f32_16x16x32_bf16 v[14:17], v[160:163], v[216:219], v[14:17]
	v_mfma_f32_16x16x32_bf16 v[10:13], v[164:167], v[212:215], v[10:13]
	v_mfma_f32_16x16x32_bf16 v[10:13], v[168:171], v[216:219], v[10:13]
	v_mfma_f32_16x16x32_bf16 v[54:57], v[172:175], v[188:191], v[54:57]
	v_mfma_f32_16x16x32_bf16 v[54:57], v[176:179], v[192:195], v[54:57]
	v_mfma_f32_16x16x32_bf16 v[50:53], v[180:183], v[188:191], v[50:53]
	v_mfma_f32_16x16x32_bf16 v[50:53], v[184:187], v[192:195], v[50:53]
	v_mfma_f32_16x16x32_bf16 v[38:41], v[172:175], v[196:199], v[38:41]
	v_mfma_f32_16x16x32_bf16 v[38:41], v[176:179], v[200:203], v[38:41]
	v_mfma_f32_16x16x32_bf16 v[34:37], v[180:183], v[196:199], v[34:37]
	v_mfma_f32_16x16x32_bf16 v[34:37], v[184:187], v[200:203], v[34:37]
	v_mfma_f32_16x16x32_bf16 v[22:25], v[172:175], v[204:207], v[22:25]
	v_mfma_f32_16x16x32_bf16 v[22:25], v[176:179], v[208:211], v[22:25]
	v_mfma_f32_16x16x32_bf16 v[18:21], v[180:183], v[204:207], v[18:21]
	v_mfma_f32_16x16x32_bf16 v[18:21], v[184:187], v[208:211], v[18:21]
	v_mfma_f32_16x16x32_bf16 v[6:9], v[172:175], v[212:215], v[6:9]
	v_mfma_f32_16x16x32_bf16 v[6:9], v[176:179], v[216:219], v[6:9]
	v_mfma_f32_16x16x32_bf16 v[2:5], v[180:183], v[212:215], v[2:5]
	v_mfma_f32_16x16x32_bf16 v[2:5], v[184:187], v[216:219], v[2:5]
	s_barrier
; #define PG8_LDA(dst, b, h) do { _Pragma("unroll") for (int m = 0; m < 4; ++m) _Pragma("unroll") for (int k = 0; k < 2; ++k) dst[m][k] = *(const PG8_LAS bf16x8*)(lds + PG8_SA(b, h) + aoff + m * 2048 + k * 1024); } while (0)
; #define PG8_LDB(dst, b, h) do { _Pragma("unroll") for (int n = 0; n < 2; ++n) _Pragma("unroll") for (int k = 0; k < 2; ++k) dst[n][k] = *(const PG8_LAS bf16x8*)(lds + PG8_SB(b, h) + boff + n * 2048 + k * 1024); } while (0)
; #define PG8_MMA(ai, bj, At, Bt) do { __builtin_amdgcn_s_setprio(1); _Pragma("unroll") for (int m = 0; m < 4; ++m) _Pragma("unroll") for (int n = 0; n < 2; ++n) _Pragma("unroll") for (int k = 0; k < 2; ++k) \
;         acc[ai][bj][m][n] = __builtin_amdgcn_mfma_f32_16x16x32_bf16(Bt[n][k], At[m][k], acc[ai][bj][m][n], 0, 0, 0); __builtin_amdgcn_s_setprio(0); } while (0)
; #define PG8_WAIT_V(n) asm volatile("s_waitcnt vmcnt(" #n ")" ::: "memory")
; #define PG8_WAIT_L(n) asm volatile("s_waitcnt lgkmcnt(" #n ")" ::: "memory")
; #define PG8_BAR __builtin_amdgcn_s_barrier()
; #define PG8_SCHED __builtin_amdgcn_sched_barrier(0)
; template <class Epi, class Sched, bool ALIGN_EPI = false, bool SP2 = false>
; __device__ __forceinline__ void gemm_phase(PG8_LAS unsigned char* lds, const Gemm g, const Sched& S, const Epi& E, const int tid) {
;     ...
;             PG8_LDB(B0, 1, 0); PG8_LDB(B1, 1, 1); PG8_SCHED; PG8_LDA(At, 1, 0); PG8_STAGE(PG8_SA(0, 1), a2 + hstepA, voffA);
;             PG8_WAIT_V(8); PG8_WAIT_L(0); PG8_BAR; PG8_MMA(0, 0, At, B0); PG8_MMA(0, 1, At, B1); PG8_BAR; PG8_SCHED;
;             PG8_LDA(At, 1, 1); PG8_STAGE(PG8_SB(1, 0), b3, voffB); PG8_STAGE(PG8_SB(1, 1), b3 + hstepB, voffB); PG8_STAGE(PG8_SA(1, 0), a3, voffA);
;             PG8_WAIT_V(8); PG8_WAIT_L(0); PG8_BAR; PG8_MMA(1, 0, At, B0); PG8_MMA(1, 1, At, B1); PG8_BAR; PG8_SCHED;
	v_add_u32_e32 v145, 0x18000, v154
	ds_read_b128 v[156:159], v145
	ds_read_b128 v[160:163], v145 offset:1024
	ds_read_b128 v[164:167], v145 offset:2048
	ds_read_b128 v[168:171], v145 offset:3072
	v_add_u32_e32 v145, 0x1c000, v154
	ds_read_b128 v[172:175], v145
	ds_read_b128 v[176:179], v145 offset:1024
	ds_read_b128 v[180:183], v145 offset:2048
	ds_read_b128 v[184:187], v145 offset:3072
	ds_read_b128 v[188:191], v155 offset:32768
	ds_read_b128 v[192:195], v155 offset:33792
	ds_read_b128 v[196:199], v155 offset:34816
	ds_read_b128 v[200:203], v155 offset:35840
	ds_read_b128 v[204:207], v155 offset:36864
	ds_read_b128 v[208:211], v155 offset:37888
	ds_read_b128 v[212:215], v155 offset:38912
	ds_read_b128 v[216:219], v155 offset:39936
	s_add_u32 s28, s42, 0x80000
	s_addc_u32 s29, s43, 0
	s_mov_b32 m0, s51
	s_nop 0
	global_load_lds_dwordx4 v149, s[28:29]
	s_nop 0
	s_mov_b32 m0, s54
	s_nop 0
	global_load_lds_dwordx4 v151, s[28:29]
	s_waitcnt vmcnt(8)
	s_waitcnt lgkmcnt(0)
	s_barrier
	v_mfma_f32_16x16x32_bf16 v[126:129], v[156:159], v[188:191], v[126:129]
	v_mfma_f32_16x16x32_bf16 v[126:129], v[160:163], v[192:195], v[126:129]
	v_mfma_f32_16x16x32_bf16 v[122:125], v[164:167], v[188:191], v[122:125]
	v_mfma_f32_16x16x32_bf16 v[122:125], v[168:171], v[192:195], v[122:125]
	v_mfma_f32_16x16x32_bf16 v[110:113], v[156:159], v[196:199], v[110:113]
	v_mfma_f32_16x16x32_bf16 v[110:113], v[160:163], v[200:203], v[110:113]
	v_mfma_f32_16x16x32_bf16 v[106:109], v[164:167], v[196:199], v[106:109]
	v_mfma_f32_16x16x32_bf16 v[106:109], v[168:171], v[200:203], v[106:109]
	v_mfma_f32_16x16x32_bf16 v[94:97], v[156:159], v[204:207], v[94:97]
	v_mfma_f32_16x16x32_bf16 v[94:97], v[160:163], v[208:211], v[94:97]
	v_mfma_f32_16x16x32_bf16 v[90:93], v[164:167], v[204:207], v[90:93]
	v_mfma_f32_16x16x32_bf16 v[90:93], v[168:171], v[208:211], v[90:93]
	v_mfma_f32_16x16x32_bf16 v[78:81], v[156:159], v[212:215], v[78:81]
	v_mfma_f32_16x16x32_bf16 v[78:81], v[160:163], v[216:219], v[78:81]
	v_mfma_f32_16x16x32_bf16 v[74:77], v[164:167], v[212:215], v[74:77]
	v_mfma_f32_16x16x32_bf16 v[74:77], v[168:171], v[216:219], v[74:77]
	v_mfma_f32_16x16x32_bf16 v[118:121], v[172:175], v[188:191], v[118:121]
	v_mfma_f32_16x16x32_bf16 v[118:121], v[176:179], v[192:195], v[118:121]
	v_mfma_f32_16x16x32_bf16 v[114:117], v[180:183], v[188:191], v[114:117]
	v_mfma_f32_16x16x32_bf16 v[114:117], v[184:187], v[192:195], v[114:117]
	v_mfma_f32_16x16x32_bf16 v[102:105], v[172:175], v[196:199], v[102:105]
	v_mfma_f32_16x16x32_bf16 v[102:105], v[176:179], v[200:203], v[102:105]
	v_mfma_f32_16x16x32_bf16 v[98:101], v[180:183], v[196:199], v[98:101]
	v_mfma_f32_16x16x32_bf16 v[98:101], v[184:187], v[200:203], v[98:101]
	v_mfma_f32_16x16x32_bf16 v[86:89], v[172:175], v[204:207], v[86:89]
	v_mfma_f32_16x16x32_bf16 v[86:89], v[176:179], v[208:211], v[86:89]
	v_mfma_f32_16x16x32_bf16 v[82:85], v[180:183], v[204:207], v[82:85]
	v_mfma_f32_16x16x32_bf16 v[82:85], v[184:187], v[208:211], v[82:85]
	v_mfma_f32_16x16x32_bf16 v[70:73], v[172:175], v[212:215], v[70:73]
	v_mfma_f32_16x16x32_bf16 v[70:73], v[176:179], v[216:219], v[70:73]
	v_mfma_f32_16x16x32_bf16 v[66:69], v[180:183], v[212:215], v[66:69]
	v_mfma_f32_16x16x32_bf16 v[66:69], v[184:187], v[216:219], v[66:69]
	s_barrier
	ds_read_b128 v[188:191], v155 offset:49152
	ds_read_b128 v[192:195], v155 offset:50176
	ds_read_b128 v[196:199], v155 offset:51200
	ds_read_b128 v[200:203], v155 offset:52224
	ds_read_b128 v[204:207], v155 offset:53248
	ds_read_b128 v[208:211], v155 offset:54272
	ds_read_b128 v[212:215], v155 offset:55296
	ds_read_b128 v[216:219], v155 offset:56320
	s_mov_b32 m0, s55
	s_nop 0
	global_load_lds_dwordx4 v150, s[40:41]
	s_add_u32 s28, s30, 0x80080
	s_mov_b32 m0, s56
	s_nop 0
	global_load_lds_dwordx4 v152, s[40:41]
	s_addc_u32 s29, s31, 0
	s_mov_b32 m0, s64
	s_nop 0
	global_load_lds_dwordx4 v150, s[28:29]
	s_nop 0
	s_mov_b32 m0, s65
	s_nop 0
	global_load_lds_dwordx4 v152, s[28:29]
	s_nop 0
	s_mov_b32 m0, s57
	s_nop 0
	global_load_lds_dwordx4 v149, s[38:39]
	s_nop 0
	s_mov_b32 m0, s61
	s_nop 0
	global_load_lds_dwordx4 v151, s[38:39]
	s_waitcnt vmcnt(8)
	s_waitcnt lgkmcnt(0)
	s_barrier
	v_mfma_f32_16x16x32_bf16 v[62:65], v[156:159], v[188:191], v[62:65]
	v_mfma_f32_16x16x32_bf16 v[62:65], v[160:163], v[192:195], v[62:65]
	v_mfma_f32_16x16x32_bf16 v[58:61], v[164:167], v[188:191], v[58:61]
	v_mfma_f32_16x16x32_bf16 v[58:61], v[168:171], v[192:195], v[58:61]
	v_mfma_f32_16x16x32_bf16 v[46:49], v[156:159], v[196:199], v[46:49]
	v_mfma_f32_16x16x32_bf16 v[46:49], v[160:163], v[200:203], v[46:49]
	v_mfma_f32_16x16x32_bf16 v[42:45], v[164:167], v[196:199], v[42:45]
	v_mfma_f32_16x16x32_bf16 v[42:45], v[168:171], v[200:203], v[42:45]
	v_mfma_f32_16x16x32_bf16 v[30:33], v[156:159], v[204:207], v[30:33]
	v_mfma_f32_16x16x32_bf16 v[30:33], v[160:163], v[208:211], v[30:33]
	v_mfma_f32_16x16x32_bf16 v[26:29], v[164:167], v[204:207], v[26:29]
	v_mfma_f32_16x16x32_bf16 v[26:29], v[168:171], v[208:211], v[26:29]
	v_mfma_f32_16x16x32_bf16 v[14:17], v[156:159], v[212:215], v[14:17]
	v_mfma_f32_16x16x32_bf16 v[14:17], v[160:163], v[216:219], v[14:17]
	v_mfma_f32_16x16x32_bf16 v[10:13], v[164:167], v[212:215], v[10:13]
	v_mfma_f32_16x16x32_bf16 v[10:13], v[168:171], v[216:219], v[10:13]
	v_mfma_f32_16x16x32_bf16 v[54:57], v[172:175], v[188:191], v[54:57]
	v_mfma_f32_16x16x32_bf16 v[54:57], v[176:179], v[192:195], v[54:57]
	v_mfma_f32_16x16x32_bf16 v[50:53], v[180:183], v[188:191], v[50:53]
	v_mfma_f32_16x16x32_bf16 v[50:53], v[184:187], v[192:195], v[50:53]
	v_mfma_f32_16x16x32_bf16 v[38:41], v[172:175], v[196:199], v[38:41]
	v_mfma_f32_16x16x32_bf16 v[38:41], v[176:179], v[200:203], v[38:41]
	v_mfma_f32_16x16x32_bf16 v[34:37], v[180:183], v[196:199], v[34:37]
	v_mfma_f32_16x16x32_bf16 v[34:37], v[184:187], v[200:203], v[34:37]
	v_mfma_f32_16x16x32_bf16 v[22:25], v[172:175], v[204:207], v[22:25]
	v_mfma_f32_16x16x32_bf16 v[22:25], v[176:179], v[208:211], v[22:25]
	v_mfma_f32_16x16x32_bf16 v[18:21], v[180:183], v[204:207], v[18:21]
	v_mfma_f32_16x16x32_bf16 v[18:21], v[184:187], v[208:211], v[18:21]
	v_mfma_f32_16x16x32_bf16 v[6:9], v[172:175], v[212:215], v[6:9]
	v_mfma_f32_16x16x32_bf16 v[6:9], v[176:179], v[216:219], v[6:9]
	v_mfma_f32_16x16x32_bf16 v[2:5], v[180:183], v[212:215], v[2:5]
	v_mfma_f32_16x16x32_bf16 v[2:5], v[184:187], v[216:219], v[2:5]
	s_barrier
	s_add_i32 s59, s59, 2
	s_add_u32 s96, s96, 0x100
	s_addc_u32 s97, s97, 0
	s_cmp_gt_u32 s59, 29
	s_mov_b64 s[28:29], s[34:35]
	s_cbranch_scc1 .LBB0_383

; #define PG8_LDA(dst, b, h) do { _Pragma("unroll") for (int m = 0; m < 4; ++m) _Pragma("unroll") for (int k = 0; k < 2; ++k) dst[m][k] = *(const PG8_LAS bf16x8*)(lds + PG8_SA(b, h) + aoff + m * 2048 + k * 1024); } while (0)
; #define PG8_LDB(dst, b, h) do { _Pragma("unroll") for (int n = 0; n < 2; ++n) _Pragma("unroll") for (int k = 0; k < 2; ++k) dst[n][k] = *(const PG8_LAS bf16x8*)(lds + PG8_SB(b, h) + boff + n * 2048 + k * 1024); } while (0)
; #define PG8_MMA(ai, bj, At, Bt) do { __builtin_amdgcn_s_setprio(1); _Pragma("unroll") for (int m = 0; m < 4; ++m) _Pragma("unroll") for (int n = 0; n < 2; ++n) _Pragma("unroll") for (int k = 0; k < 2; ++k) \
;         acc[ai][bj][m][n] = __builtin_amdgcn_mfma_f32_16x16x32_bf16(Bt[n][k], At[m][k], acc[ai][bj][m][n], 0, 0, 0); __builtin_amdgcn_s_setprio(0); } while (0)
; #define PG8_WAIT_V(n) asm volatile("s_waitcnt vmcnt(" #n ")" ::: "memory")
; #define PG8_WAIT_L(n) asm volatile("s_waitcnt lgkmcnt(" #n ")" ::: "memory")
; #define PG8_BAR __builtin_amdgcn_s_barrier()
; #define PG8_SCHED __builtin_amdgcn_sched_barrier(0)
; template <class Epi, class Sched, bool ALIGN_EPI = false, bool SP2 = false>
; __device__ __forceinline__ void gemm_phase(PG8_LAS unsigned char* lds, const Gemm g, const Sched& S, const Epi& E, const int tid) {
;     ...
;             PG8_LDB(B0, 0, 0); PG8_LDB(B1, 0, 1); PG8_SCHED; PG8_LDA(At, 0, 0); PG8_STAGE(PG8_SA(1, 1), a1 + hstepA, voffA);
;             PG8_WAIT_V(8); PG8_WAIT_L(0); PG8_BAR; PG8_MMA(0, 0, At, B0); PG8_MMA(0, 1, At, B1); PG8_BAR; PG8_SCHED;
;             PG8_LDA(At, 0, 1); PG8_STAGE(PG8_SB(0, 0), b2, voffB); PG8_STAGE(PG8_SB(0, 1), b2 + hstepB, voffB); PG8_STAGE(PG8_SA(0, 0), a2, voffA);
;             PG8_WAIT_V(8); PG8_WAIT_L(0); PG8_BAR; PG8_MMA(1, 0, At, B0); PG8_MMA(1, 1, At, B1); PG8_BAR; PG8_SCHED;
.LBB0_462:
	v_add_u32_e32 v142, 0x10000, v181
	v_add_u32_e32 v158, 0x14000, v181
	ds_read_b128 v[130:133], v142
	ds_read_b128 v[134:137], v142 offset:1024
	ds_read_b128 v[138:141], v142 offset:2048
	ds_read_b128 v[142:145], v142 offset:3072
	ds_read_b128 v[146:149], v158
	ds_read_b128 v[150:153], v158 offset:1024
	ds_read_b128 v[154:157], v158 offset:2048
	ds_read_b128 v[158:161], v158 offset:3072
	s_cmpk_eq_i32 s67, 0x54
	s_cselect_b32 s26, s6, s64
	s_cselect_b32 s27, s7, s65
	s_cselect_b32 s24, s18, s11
	s_cselect_b32 s25, s19, s59
	s_add_u32 s22, s26, 0x8000
	s_addc_u32 s23, s27, 0
	ds_read_b128 v[162:165], v182
	ds_read_b128 v[166:169], v182 offset:1024
	ds_read_b128 v[170:173], v182 offset:2048
	ds_read_b128 v[184:187], v182 offset:3072
	ds_read_b128 v[188:191], v182 offset:4096
	ds_read_b128 v[192:195], v182 offset:5120
	ds_read_b128 v[196:199], v182 offset:6144
	ds_read_b128 v[200:203], v182 offset:7168
	s_mov_b32 m0, s50
	s_nop 0
	global_load_lds_dwordx4 v0, s[20:21]
	s_nop 0
	s_mov_b32 m0, s54
	s_nop 0
	global_load_lds_dwordx4 v177, s[20:21]
	s_waitcnt vmcnt(8)
	s_waitcnt lgkmcnt(0)
	s_barrier
	v_mfma_f32_16x16x32_bf16 v[126:129], v[130:133], v[162:165], v[126:129]
	v_mfma_f32_16x16x32_bf16 v[126:129], v[134:137], v[166:169], v[126:129]
	v_mfma_f32_16x16x32_bf16 v[122:125], v[138:141], v[162:165], v[122:125]
	v_mfma_f32_16x16x32_bf16 v[122:125], v[142:145], v[166:169], v[122:125]
	v_mfma_f32_16x16x32_bf16 v[110:113], v[130:133], v[170:173], v[110:113]
	v_mfma_f32_16x16x32_bf16 v[110:113], v[134:137], v[184:187], v[110:113]
	v_mfma_f32_16x16x32_bf16 v[106:109], v[138:141], v[170:173], v[106:109]
	v_mfma_f32_16x16x32_bf16 v[106:109], v[142:145], v[184:187], v[106:109]
	v_mfma_f32_16x16x32_bf16 v[94:97], v[130:133], v[188:191], v[94:97]
	v_mfma_f32_16x16x32_bf16 v[94:97], v[134:137], v[192:195], v[94:97]
	v_mfma_f32_16x16x32_bf16 v[90:93], v[138:141], v[188:191], v[90:93]
	v_mfma_f32_16x16x32_bf16 v[90:93], v[142:145], v[192:195], v[90:93]
	v_mfma_f32_16x16x32_bf16 v[78:81], v[130:133], v[196:199], v[78:81]
	v_mfma_f32_16x16x32_bf16 v[78:81], v[134:137], v[200:203], v[78:81]
	v_mfma_f32_16x16x32_bf16 v[74:77], v[138:141], v[196:199], v[74:77]
	v_mfma_f32_16x16x32_bf16 v[74:77], v[142:145], v[200:203], v[74:77]
	v_mfma_f32_16x16x32_bf16 v[118:121], v[146:149], v[162:165], v[118:121]
	v_mfma_f32_16x16x32_bf16 v[118:121], v[150:153], v[166:169], v[118:121]
	v_mfma_f32_16x16x32_bf16 v[114:117], v[154:157], v[162:165], v[114:117]
	v_mfma_f32_16x16x32_bf16 v[114:117], v[158:161], v[166:169], v[114:117]
	v_mfma_f32_16x16x32_bf16 v[102:105], v[146:149], v[170:173], v[102:105]
	v_mfma_f32_16x16x32_bf16 v[102:105], v[150:153], v[184:187], v[102:105]
	v_mfma_f32_16x16x32_bf16 v[98:101], v[154:157], v[170:173], v[98:101]
	v_mfma_f32_16x16x32_bf16 v[98:101], v[158:161], v[184:187], v[98:101]
	v_mfma_f32_16x16x32_bf16 v[86:89], v[146:149], v[188:191], v[86:89]
	v_mfma_f32_16x16x32_bf16 v[86:89], v[150:153], v[192:195], v[86:89]
	v_mfma_f32_16x16x32_bf16 v[82:85], v[154:157], v[188:191], v[82:85]
	v_mfma_f32_16x16x32_bf16 v[82:85], v[158:161], v[192:195], v[82:85]
	v_mfma_f32_16x16x32_bf16 v[70:73], v[146:149], v[196:199], v[70:73]
	v_mfma_f32_16x16x32_bf16 v[70:73], v[150:153], v[200:203], v[70:73]
	v_mfma_f32_16x16x32_bf16 v[66:69], v[154:157], v[196:199], v[66:69]
	v_mfma_f32_16x16x32_bf16 v[66:69], v[158:161], v[200:203], v[66:69]
	s_barrier
	ds_read_b128 v[162:165], v182 offset:16384
	ds_read_b128 v[166:169], v182 offset:17408
	ds_read_b128 v[170:173], v182 offset:18432
	ds_read_b128 v[184:187], v182 offset:19456
	ds_read_b128 v[188:191], v182 offset:20480
	ds_read_b128 v[192:195], v182 offset:21504
	ds_read_b128 v[196:199], v182 offset:22528
	ds_read_b128 v[200:203], v182 offset:23552
	s_mov_b32 m0, s35
	s_nop 0
	global_load_lds_dwordx4 v176, s[24:25]
	s_add_u32 s90, s24, 0x4000
	s_mov_b32 m0, s37
	s_nop 0
	global_load_lds_dwordx4 v178, s[24:25]
	s_addc_u32 s91, s25, 0
	s_mov_b32 m0, s38
	s_nop 0
	global_load_lds_dwordx4 v176, s[90:91]
	s_nop 0
	s_mov_b32 m0, s39
	s_nop 0
	global_load_lds_dwordx4 v178, s[90:91]
	s_nop 0
	s_mov_b32 m0, s10
	s_nop 0
	global_load_lds_dwordx4 v0, s[26:27]
	s_nop 0
	s_mov_b32 m0, s40
	s_nop 0
	global_load_lds_dwordx4 v177, s[26:27]
	s_waitcnt vmcnt(8)
	s_waitcnt lgkmcnt(0)
	s_barrier
	v_mfma_f32_16x16x32_bf16 v[62:65], v[130:133], v[162:165], v[62:65]
	v_mfma_f32_16x16x32_bf16 v[62:65], v[134:137], v[166:169], v[62:65]
	v_mfma_f32_16x16x32_bf16 v[58:61], v[138:141], v[162:165], v[58:61]
	v_mfma_f32_16x16x32_bf16 v[58:61], v[142:145], v[166:169], v[58:61]
	v_mfma_f32_16x16x32_bf16 v[46:49], v[130:133], v[170:173], v[46:49]
	v_mfma_f32_16x16x32_bf16 v[46:49], v[134:137], v[184:187], v[46:49]
	v_mfma_f32_16x16x32_bf16 v[42:45], v[138:141], v[170:173], v[42:45]
	v_mfma_f32_16x16x32_bf16 v[42:45], v[142:145], v[184:187], v[42:45]
	v_mfma_f32_16x16x32_bf16 v[30:33], v[130:133], v[188:191], v[30:33]
	v_mfma_f32_16x16x32_bf16 v[30:33], v[134:137], v[192:195], v[30:33]
	v_mfma_f32_16x16x32_bf16 v[26:29], v[138:141], v[188:191], v[26:29]
	v_mfma_f32_16x16x32_bf16 v[26:29], v[142:145], v[192:195], v[26:29]
	v_mfma_f32_16x16x32_bf16 v[14:17], v[130:133], v[196:199], v[14:17]
	v_mfma_f32_16x16x32_bf16 v[14:17], v[134:137], v[200:203], v[14:17]
	v_mfma_f32_16x16x32_bf16 v[10:13], v[138:141], v[196:199], v[10:13]
	v_mfma_f32_16x16x32_bf16 v[10:13], v[142:145], v[200:203], v[10:13]
	v_mfma_f32_16x16x32_bf16 v[54:57], v[146:149], v[162:165], v[54:57]
	v_mfma_f32_16x16x32_bf16 v[54:57], v[150:153], v[166:169], v[54:57]
	v_mfma_f32_16x16x32_bf16 v[50:53], v[154:157], v[162:165], v[50:53]
	v_mfma_f32_16x16x32_bf16 v[50:53], v[158:161], v[166:169], v[50:53]
	v_mfma_f32_16x16x32_bf16 v[38:41], v[146:149], v[170:173], v[38:41]
	v_mfma_f32_16x16x32_bf16 v[38:41], v[150:153], v[184:187], v[38:41]
	v_mfma_f32_16x16x32_bf16 v[34:37], v[154:157], v[170:173], v[34:37]
	v_mfma_f32_16x16x32_bf16 v[34:37], v[158:161], v[184:187], v[34:37]
	v_mfma_f32_16x16x32_bf16 v[22:25], v[146:149], v[188:191], v[22:25]
	v_mfma_f32_16x16x32_bf16 v[22:25], v[150:153], v[192:195], v[22:25]
	v_mfma_f32_16x16x32_bf16 v[18:21], v[154:157], v[188:191], v[18:21]
	v_mfma_f32_16x16x32_bf16 v[18:21], v[158:161], v[192:195], v[18:21]
	v_mfma_f32_16x16x32_bf16 v[6:9], v[146:149], v[196:199], v[6:9]
	v_mfma_f32_16x16x32_bf16 v[6:9], v[150:153], v[200:203], v[6:9]
	v_mfma_f32_16x16x32_bf16 v[2:5], v[154:157], v[196:199], v[2:5]
	v_mfma_f32_16x16x32_bf16 v[2:5], v[158:161], v[200:203], v[2:5]
	s_barrier
; #define PG8_LDA(dst, b, h) do { _Pragma("unroll") for (int m = 0; m < 4; ++m) _Pragma("unroll") for (int k = 0; k < 2; ++k) dst[m][k] = *(const PG8_LAS bf16x8*)(lds + PG8_SA(b, h) + aoff + m * 2048 + k * 1024); } while (0)
; #define PG8_LDB(dst, b, h) do { _Pragma("unroll") for (int n = 0; n < 2; ++n) _Pragma("unroll") for (int k = 0; k < 2; ++k) dst[n][k] = *(const PG8_LAS bf16x8*)(lds + PG8_SB(b, h) + boff + n * 2048 + k * 1024); } while (0)
; #define PG8_MMA(ai, bj, At, Bt) do { __builtin_amdgcn_s_setprio(1); _Pragma("unroll") for (int m = 0; m < 4; ++m) _Pragma("unroll") for (int n = 0; n < 2; ++n) _Pragma("unroll") for (int k = 0; k < 2; ++k) \
;         acc[ai][bj][m][n] = __builtin_amdgcn_mfma_f32_16x16x32_bf16(Bt[n][k], At[m][k], acc[ai][bj][m][n], 0, 0, 0); __builtin_amdgcn_s_setprio(0); } while (0)
; #define PG8_WAIT_V(n) asm volatile("s_waitcnt vmcnt(" #n ")" ::: "memory")
; #define PG8_WAIT_L(n) asm volatile("s_waitcnt lgkmcnt(" #n ")" ::: "memory")
; #define PG8_BAR __builtin_amdgcn_s_barrier()
; #define PG8_SCHED __builtin_amdgcn_sched_barrier(0)
; template <class Epi, class Sched, bool ALIGN_EPI = false, bool SP2 = false>
; __device__ __forceinline__ void gemm_phase(PG8_LAS unsigned char* lds, const Gemm g, const Sched& S, const Epi& E, const int tid) {
;     ...
;             PG8_LDB(B0, 1, 0); PG8_LDB(B1, 1, 1); PG8_SCHED; PG8_LDA(At, 1, 0); PG8_STAGE(PG8_SA(0, 1), a2 + hstepA, voffA);
;             PG8_WAIT_V(8); PG8_WAIT_L(0); PG8_BAR; PG8_MMA(0, 0, At, B0); PG8_MMA(0, 1, At, B1); PG8_BAR; PG8_SCHED;
;             PG8_LDA(At, 1, 1); PG8_STAGE(PG8_SB(1, 0), b3, voffB); PG8_STAGE(PG8_SB(1, 1), b3 + hstepB, voffB); PG8_STAGE(PG8_SA(1, 0), a3, voffA);
;             PG8_WAIT_V(8); PG8_WAIT_L(0); PG8_BAR; PG8_MMA(1, 0, At, B0); PG8_MMA(1, 1, At, B1); PG8_BAR; PG8_SCHED;
	v_add_u32_e32 v142, 0x18000, v181
	v_add_u32_e32 v158, 0x1c000, v181
	ds_read_b128 v[130:133], v142
	ds_read_b128 v[134:137], v142 offset:1024
	ds_read_b128 v[138:141], v142 offset:2048
	ds_read_b128 v[142:145], v142 offset:3072
	ds_read_b128 v[146:149], v158
	ds_read_b128 v[150:153], v158 offset:1024
	ds_read_b128 v[154:157], v158 offset:2048
	ds_read_b128 v[158:161], v158 offset:3072
	ds_read_b128 v[162:165], v182 offset:32768
	ds_read_b128 v[166:169], v182 offset:33792
	ds_read_b128 v[170:173], v182 offset:34816
	ds_read_b128 v[184:187], v182 offset:35840
	ds_read_b128 v[188:191], v182 offset:36864
	ds_read_b128 v[192:195], v182 offset:37888
	ds_read_b128 v[196:199], v182 offset:38912
	ds_read_b128 v[200:203], v182 offset:39936
	s_add_u32 s26, s26, 0x4000
	s_addc_u32 s27, s27, 0
	s_mov_b32 m0, s41
	s_nop 0
	global_load_lds_dwordx4 v0, s[26:27]
	s_nop 0
	s_mov_b32 m0, s42
	s_nop 0
	global_load_lds_dwordx4 v177, s[26:27]
	s_waitcnt vmcnt(8)
	s_waitcnt lgkmcnt(0)
	s_barrier
	v_mfma_f32_16x16x32_bf16 v[126:129], v[130:133], v[162:165], v[126:129]
	v_mfma_f32_16x16x32_bf16 v[126:129], v[134:137], v[166:169], v[126:129]
	v_mfma_f32_16x16x32_bf16 v[122:125], v[138:141], v[162:165], v[122:125]
	v_mfma_f32_16x16x32_bf16 v[122:125], v[142:145], v[166:169], v[122:125]
	v_mfma_f32_16x16x32_bf16 v[110:113], v[130:133], v[170:173], v[110:113]
	v_mfma_f32_16x16x32_bf16 v[110:113], v[134:137], v[184:187], v[110:113]
	v_mfma_f32_16x16x32_bf16 v[106:109], v[138:141], v[170:173], v[106:109]
	v_mfma_f32_16x16x32_bf16 v[106:109], v[142:145], v[184:187], v[106:109]
	v_mfma_f32_16x16x32_bf16 v[94:97], v[130:133], v[188:191], v[94:97]
	v_mfma_f32_16x16x32_bf16 v[94:97], v[134:137], v[192:195], v[94:97]
	v_mfma_f32_16x16x32_bf16 v[90:93], v[138:141], v[188:191], v[90:93]
	v_mfma_f32_16x16x32_bf16 v[90:93], v[142:145], v[192:195], v[90:93]
	v_mfma_f32_16x16x32_bf16 v[78:81], v[130:133], v[196:199], v[78:81]
	v_mfma_f32_16x16x32_bf16 v[78:81], v[134:137], v[200:203], v[78:81]
	v_mfma_f32_16x16x32_bf16 v[74:77], v[138:141], v[196:199], v[74:77]
	v_mfma_f32_16x16x32_bf16 v[74:77], v[142:145], v[200:203], v[74:77]
	v_mfma_f32_16x16x32_bf16 v[118:121], v[146:149], v[162:165], v[118:121]
	v_mfma_f32_16x16x32_bf16 v[118:121], v[150:153], v[166:169], v[118:121]
	v_mfma_f32_16x16x32_bf16 v[114:117], v[154:157], v[162:165], v[114:117]
	v_mfma_f32_16x16x32_bf16 v[114:117], v[158:161], v[166:169], v[114:117]
	v_mfma_f32_16x16x32_bf16 v[102:105], v[146:149], v[170:173], v[102:105]
	v_mfma_f32_16x16x32_bf16 v[102:105], v[150:153], v[184:187], v[102:105]
	v_mfma_f32_16x16x32_bf16 v[98:101], v[154:157], v[170:173], v[98:101]
	v_mfma_f32_16x16x32_bf16 v[98:101], v[158:161], v[184:187], v[98:101]
	v_mfma_f32_16x16x32_bf16 v[86:89], v[146:149], v[188:191], v[86:89]
	v_mfma_f32_16x16x32_bf16 v[86:89], v[150:153], v[192:195], v[86:89]
	v_mfma_f32_16x16x32_bf16 v[82:85], v[154:157], v[188:191], v[82:85]
	v_mfma_f32_16x16x32_bf16 v[82:85], v[158:161], v[192:195], v[82:85]
	v_mfma_f32_16x16x32_bf16 v[70:73], v[146:149], v[196:199], v[70:73]
	v_mfma_f32_16x16x32_bf16 v[70:73], v[150:153], v[200:203], v[70:73]
	v_mfma_f32_16x16x32_bf16 v[66:69], v[154:157], v[196:199], v[66:69]
	v_mfma_f32_16x16x32_bf16 v[66:69], v[158:161], v[200:203], v[66:69]
	s_barrier
	ds_read_b128 v[162:165], v182 offset:49152
	ds_read_b128 v[166:169], v182 offset:50176
	ds_read_b128 v[170:173], v182 offset:51200
	ds_read_b128 v[184:187], v182 offset:52224
	ds_read_b128 v[188:191], v182 offset:53248
	ds_read_b128 v[192:195], v182 offset:54272
	ds_read_b128 v[196:199], v182 offset:55296
	ds_read_b128 v[200:203], v182 offset:56320
	s_add_u32 s26, s24, 0x8000
	s_addc_u32 s27, s25, 0
	s_mov_b32 m0, s44
	s_nop 0
	global_load_lds_dwordx4 v176, s[26:27]
	s_add_u32 s24, s24, 0xc000
	s_mov_b32 m0, s45
	s_nop 0
	global_load_lds_dwordx4 v178, s[26:27]
	s_addc_u32 s25, s25, 0
	s_mov_b32 m0, s48
	s_nop 0
	global_load_lds_dwordx4 v176, s[24:25]
	s_nop 0
	s_mov_b32 m0, s49
	s_nop 0
	global_load_lds_dwordx4 v178, s[24:25]
	s_mov_b32 m0, s46
	s_nop 0
	global_load_lds_dwordx4 v0, s[22:23]
	s_nop 0
	s_mov_b32 m0, s47
	s_nop 0
	global_load_lds_dwordx4 v177, s[22:23]
	s_waitcnt vmcnt(8)
	s_waitcnt lgkmcnt(0)
	s_barrier
	v_mfma_f32_16x16x32_bf16 v[62:65], v[130:133], v[162:165], v[62:65]
	v_mfma_f32_16x16x32_bf16 v[62:65], v[134:137], v[166:169], v[62:65]
	v_mfma_f32_16x16x32_bf16 v[58:61], v[138:141], v[162:165], v[58:61]
	v_mfma_f32_16x16x32_bf16 v[58:61], v[142:145], v[166:169], v[58:61]
	v_mfma_f32_16x16x32_bf16 v[46:49], v[130:133], v[170:173], v[46:49]
	v_mfma_f32_16x16x32_bf16 v[46:49], v[134:137], v[184:187], v[46:49]
	v_mfma_f32_16x16x32_bf16 v[42:45], v[138:141], v[170:173], v[42:45]
	v_mfma_f32_16x16x32_bf16 v[42:45], v[142:145], v[184:187], v[42:45]
	v_mfma_f32_16x16x32_bf16 v[30:33], v[130:133], v[188:191], v[30:33]
	v_mfma_f32_16x16x32_bf16 v[30:33], v[134:137], v[192:195], v[30:33]
	v_mfma_f32_16x16x32_bf16 v[26:29], v[138:141], v[188:191], v[26:29]
	v_mfma_f32_16x16x32_bf16 v[26:29], v[142:145], v[192:195], v[26:29]
	v_mfma_f32_16x16x32_bf16 v[14:17], v[130:133], v[196:199], v[14:17]
	v_mfma_f32_16x16x32_bf16 v[14:17], v[134:137], v[200:203], v[14:17]
	v_mfma_f32_16x16x32_bf16 v[10:13], v[138:141], v[196:199], v[10:13]
	v_mfma_f32_16x16x32_bf16 v[10:13], v[142:145], v[200:203], v[10:13]
	v_mfma_f32_16x16x32_bf16 v[54:57], v[146:149], v[162:165], v[54:57]
	v_mfma_f32_16x16x32_bf16 v[54:57], v[150:153], v[166:169], v[54:57]
	v_mfma_f32_16x16x32_bf16 v[50:53], v[154:157], v[162:165], v[50:53]
	v_mfma_f32_16x16x32_bf16 v[50:53], v[158:161], v[166:169], v[50:53]
	v_mfma_f32_16x16x32_bf16 v[38:41], v[146:149], v[170:173], v[38:41]
	v_mfma_f32_16x16x32_bf16 v[38:41], v[150:153], v[184:187], v[38:41]
	v_mfma_f32_16x16x32_bf16 v[34:37], v[154:157], v[170:173], v[34:37]
	v_mfma_f32_16x16x32_bf16 v[34:37], v[158:161], v[184:187], v[34:37]
	v_mfma_f32_16x16x32_bf16 v[22:25], v[146:149], v[188:191], v[22:25]
	v_mfma_f32_16x16x32_bf16 v[22:25], v[150:153], v[192:195], v[22:25]
	v_mfma_f32_16x16x32_bf16 v[18:21], v[154:157], v[188:191], v[18:21]
	v_mfma_f32_16x16x32_bf16 v[18:21], v[158:161], v[192:195], v[18:21]
	v_mfma_f32_16x16x32_bf16 v[6:9], v[146:149], v[196:199], v[6:9]
	v_mfma_f32_16x16x32_bf16 v[6:9], v[150:153], v[200:203], v[6:9]
	v_mfma_f32_16x16x32_bf16 v[2:5], v[154:157], v[196:199], v[2:5]
	v_mfma_f32_16x16x32_bf16 v[2:5], v[158:161], v[200:203], v[2:5]
	s_barrier
	s_add_i32 s67, s67, 2
	s_add_u32 s11, s11, 0x10000
	s_addc_u32 s59, s59, 0
	s_add_u32 s64, s64, 0x10000
	s_addc_u32 s65, s65, 0
	s_add_u32 s20, s20, 0x10000
	s_addc_u32 s21, s21, 0
	s_cmpk_gt_u32 s67, 0x55
	s_cbranch_scc0 .LBB0_462
	s_and_b64 vcc, exec, s[16:17]
	s_cbranch_vccz .LBB0_465
	s_barrier

; #define PG8_LDA(dst, b, h) do { _Pragma("unroll") for (int m = 0; m < 4; ++m) _Pragma("unroll") for (int k = 0; k < 2; ++k) dst[m][k] = *(const PG8_LAS bf16x8*)(lds + PG8_SA(b, h) + aoff + m * 2048 + k * 1024); } while (0)
; #define PG8_LDB(dst, b, h) do { _Pragma("unroll") for (int n = 0; n < 2; ++n) _Pragma("unroll") for (int k = 0; k < 2; ++k) dst[n][k] = *(const PG8_LAS bf16x8*)(lds + PG8_SB(b, h) + boff + n * 2048 + k * 1024); } while (0)
; #define PG8_MMA(ai, bj, At, Bt) do { __builtin_amdgcn_s_setprio(1); _Pragma("unroll") for (int m = 0; m < 4; ++m) _Pragma("unroll") for (int n = 0; n < 2; ++n) _Pragma("unroll") for (int k = 0; k < 2; ++k) \
;         acc[ai][bj][m][n] = __builtin_amdgcn_mfma_f32_16x16x32_bf16(Bt[n][k], At[m][k], acc[ai][bj][m][n], 0, 0, 0); __builtin_amdgcn_s_setprio(0); } while (0)
; #define PG8_WAIT_V(n) asm volatile("s_waitcnt vmcnt(" #n ")" ::: "memory")
; #define PG8_WAIT_L(n) asm volatile("s_waitcnt lgkmcnt(" #n ")" ::: "memory")
; #define PG8_BAR __builtin_amdgcn_s_barrier()
; #define PG8_SCHED __builtin_amdgcn_sched_barrier(0)
; template <class Epi, class Sched, bool ALIGN_EPI = false, bool SP2 = false>
; __device__ __forceinline__ void gemm_phase(PG8_LAS unsigned char* lds, const Gemm g, const Sched& S, const Epi& E, const int tid) {
;     ...
;             const char* a1 = cA + (size_t)(t + 1) * kstepA;
;             const char* a2 = last ? nA : cA + (size_t)(t + 2) * kstepA; const char* b2 = last ? nB : cB + (size_t)(t + 2) * kstepB;
;             const char* a3 = a2 + kstepA; const char* b3 = b2 + kstepB;
;             if (last && has_next) S.a_ready(nxt);
;             if constexpr (SP2) {
;             PG8_LDB(B0, 0, 0); PG8_LDB(B1, 0, 1); PG8_SCHED; PG8_LDA(At, 0, 0); PG8_STAGE(PG8_SA(1, 1), a1 + hstepA, voffA);
;             PG8_WAIT_V(8); PG8_WAIT_L(0); PG8_BAR; PG8_MMA(0, 0, At, B0); PG8_MMA(0, 1, At, B1); PG8_BAR; PG8_SCHED;
;             PG8_LDA(At, 0, 1); PG8_STAGE(PG8_SB(0, 0), b2, voffB); PG8_STAGE(PG8_SB(0, 1), b2 + hstepB, voffB); PG8_STAGE(PG8_SA(0, 0), a2, voffA);
;             PG8_WAIT_V(8); PG8_WAIT_L(0); PG8_BAR; PG8_MMA(1, 0, At, B0); PG8_MMA(1, 1, At, B1); PG8_BAR; PG8_SCHED;
.LBB0_546:
	s_or_b64 exec, exec, s[34:35]
	v_add_u32_e32 v133, 0x10000, v144
	ds_read_b128 v[146:149], v133
	ds_read_b128 v[150:153], v133 offset:1024
	ds_read_b128 v[154:157], v133 offset:2048
	ds_read_b128 v[158:161], v133 offset:3072
	v_add_u32_e32 v133, 0x14000, v144
	s_add_u32 s34, s28, 0x100
	ds_read_b128 v[162:165], v133
	ds_read_b128 v[166:169], v133 offset:1024
	ds_read_b128 v[170:173], v133 offset:2048
	ds_read_b128 v[174:177], v133 offset:3072
	s_addc_u32 s35, s29, 0
	s_and_b64 s[30:31], s[30:31], exec
	s_cselect_b32 s42, s95, s34
	s_cselect_b32 s43, s21, s35
	s_cselect_b32 s31, s19, s59
	s_cselect_b32 s30, s96, s97
	s_add_u32 s38, s42, 0x80
	s_addc_u32 s39, s43, 0
	s_add_u32 s40, s30, 0x80
	s_addc_u32 s41, s31, 0
	ds_read_b128 v[178:181], v145
	ds_read_b128 v[182:185], v145 offset:1024
	ds_read_b128 v[186:189], v145 offset:2048
	ds_read_b128 v[190:193], v145 offset:3072
	ds_read_b128 v[194:197], v145 offset:4096
	ds_read_b128 v[198:201], v145 offset:5120
	ds_read_b128 v[202:205], v145 offset:6144
	ds_read_b128 v[206:209], v145 offset:7168
	s_add_u32 s28, s28, 0x80080
	s_addc_u32 s29, s29, 0
	s_mov_b32 m0, s70
	s_nop 0
	global_load_lds_dwordx4 v136, s[28:29]
	s_nop 0
	s_mov_b32 m0, s78
	s_nop 0
	global_load_lds_dwordx4 v138, s[28:29]
	s_waitcnt vmcnt(8)
	s_waitcnt lgkmcnt(0)
	s_barrier
	v_mfma_f32_16x16x32_bf16 v[126:129], v[146:149], v[178:181], v[126:129]
	v_mfma_f32_16x16x32_bf16 v[126:129], v[150:153], v[182:185], v[126:129]
	v_mfma_f32_16x16x32_bf16 v[122:125], v[154:157], v[178:181], v[122:125]
	v_mfma_f32_16x16x32_bf16 v[122:125], v[158:161], v[182:185], v[122:125]
	v_mfma_f32_16x16x32_bf16 v[118:121], v[146:149], v[186:189], v[118:121]
	v_mfma_f32_16x16x32_bf16 v[118:121], v[150:153], v[190:193], v[118:121]
	v_mfma_f32_16x16x32_bf16 v[110:113], v[154:157], v[186:189], v[110:113]
	v_mfma_f32_16x16x32_bf16 v[110:113], v[158:161], v[190:193], v[110:113]
	v_mfma_f32_16x16x32_bf16 v[102:105], v[146:149], v[194:197], v[102:105]
	v_mfma_f32_16x16x32_bf16 v[102:105], v[150:153], v[198:201], v[102:105]
	v_mfma_f32_16x16x32_bf16 v[94:97], v[154:157], v[194:197], v[94:97]
	v_mfma_f32_16x16x32_bf16 v[94:97], v[158:161], v[198:201], v[94:97]
	v_mfma_f32_16x16x32_bf16 v[86:89], v[146:149], v[202:205], v[86:89]
	v_mfma_f32_16x16x32_bf16 v[86:89], v[150:153], v[206:209], v[86:89]
	v_mfma_f32_16x16x32_bf16 v[78:81], v[154:157], v[202:205], v[78:81]
	v_mfma_f32_16x16x32_bf16 v[78:81], v[158:161], v[206:209], v[78:81]
	v_mfma_f32_16x16x32_bf16 v[114:117], v[162:165], v[178:181], v[114:117]
	v_mfma_f32_16x16x32_bf16 v[114:117], v[166:169], v[182:185], v[114:117]
	v_mfma_f32_16x16x32_bf16 v[106:109], v[170:173], v[178:181], v[106:109]
	v_mfma_f32_16x16x32_bf16 v[106:109], v[174:177], v[182:185], v[106:109]
	v_mfma_f32_16x16x32_bf16 v[98:101], v[162:165], v[186:189], v[98:101]
	v_mfma_f32_16x16x32_bf16 v[98:101], v[166:169], v[190:193], v[98:101]
	v_mfma_f32_16x16x32_bf16 v[90:93], v[170:173], v[186:189], v[90:93]
	v_mfma_f32_16x16x32_bf16 v[90:93], v[174:177], v[190:193], v[90:93]
	v_mfma_f32_16x16x32_bf16 v[82:85], v[162:165], v[194:197], v[82:85]
	v_mfma_f32_16x16x32_bf16 v[82:85], v[166:169], v[198:201], v[82:85]
	v_mfma_f32_16x16x32_bf16 v[74:77], v[170:173], v[194:197], v[74:77]
	v_mfma_f32_16x16x32_bf16 v[74:77], v[174:177], v[198:201], v[74:77]
	v_mfma_f32_16x16x32_bf16 v[70:73], v[162:165], v[202:205], v[70:73]
	v_mfma_f32_16x16x32_bf16 v[70:73], v[166:169], v[206:209], v[70:73]
	v_mfma_f32_16x16x32_bf16 v[66:69], v[170:173], v[202:205], v[66:69]
	v_mfma_f32_16x16x32_bf16 v[66:69], v[174:177], v[206:209], v[66:69]
	s_barrier
	ds_read_b128 v[178:181], v145 offset:16384
	ds_read_b128 v[182:185], v145 offset:17408
	ds_read_b128 v[186:189], v145 offset:18432
	ds_read_b128 v[190:193], v145 offset:19456
	ds_read_b128 v[194:197], v145 offset:20480
	ds_read_b128 v[198:201], v145 offset:21504
	ds_read_b128 v[202:205], v145 offset:22528
	ds_read_b128 v[206:209], v145 offset:23552
	s_mov_b32 m0, s9
	s_nop 0
	global_load_lds_dwordx4 v137, s[30:31]
	s_add_u32 s28, s30, 0x80000
	s_mov_b32 m0, s49
	s_nop 0
	global_load_lds_dwordx4 v139, s[30:31]
	s_addc_u32 s29, s31, 0
	s_mov_b32 m0, s50
	s_nop 0
	global_load_lds_dwordx4 v137, s[28:29]
	s_nop 0
	s_mov_b32 m0, s51
	s_nop 0
	global_load_lds_dwordx4 v139, s[28:29]
	s_nop 0
	s_mov_b32 m0, s10
	s_nop 0
	global_load_lds_dwordx4 v136, s[42:43]
	s_nop 0
	s_mov_b32 m0, s54
	s_nop 0
	global_load_lds_dwordx4 v138, s[42:43]
	s_waitcnt vmcnt(8)
	s_waitcnt lgkmcnt(0)
	s_barrier
	v_mfma_f32_16x16x32_bf16 v[62:65], v[146:149], v[178:181], v[62:65]
	v_mfma_f32_16x16x32_bf16 v[62:65], v[150:153], v[182:185], v[62:65]
	v_mfma_f32_16x16x32_bf16 v[58:61], v[154:157], v[178:181], v[58:61]
	v_mfma_f32_16x16x32_bf16 v[58:61], v[158:161], v[182:185], v[58:61]
	v_mfma_f32_16x16x32_bf16 v[54:57], v[146:149], v[186:189], v[54:57]
	v_mfma_f32_16x16x32_bf16 v[54:57], v[150:153], v[190:193], v[54:57]
	v_mfma_f32_16x16x32_bf16 v[46:49], v[154:157], v[186:189], v[46:49]
	v_mfma_f32_16x16x32_bf16 v[46:49], v[158:161], v[190:193], v[46:49]
	v_mfma_f32_16x16x32_bf16 v[38:41], v[146:149], v[194:197], v[38:41]
	v_mfma_f32_16x16x32_bf16 v[38:41], v[150:153], v[198:201], v[38:41]
	v_mfma_f32_16x16x32_bf16 v[30:33], v[154:157], v[194:197], v[30:33]
	v_mfma_f32_16x16x32_bf16 v[30:33], v[158:161], v[198:201], v[30:33]
	v_mfma_f32_16x16x32_bf16 v[22:25], v[146:149], v[202:205], v[22:25]
	v_mfma_f32_16x16x32_bf16 v[22:25], v[150:153], v[206:209], v[22:25]
	v_mfma_f32_16x16x32_bf16 v[14:17], v[154:157], v[202:205], v[14:17]
	v_mfma_f32_16x16x32_bf16 v[14:17], v[158:161], v[206:209], v[14:17]
	v_mfma_f32_16x16x32_bf16 v[50:53], v[162:165], v[178:181], v[50:53]
	v_mfma_f32_16x16x32_bf16 v[50:53], v[166:169], v[182:185], v[50:53]
	v_mfma_f32_16x16x32_bf16 v[42:45], v[170:173], v[178:181], v[42:45]
	v_mfma_f32_16x16x32_bf16 v[42:45], v[174:177], v[182:185], v[42:45]
	v_mfma_f32_16x16x32_bf16 v[34:37], v[162:165], v[186:189], v[34:37]
	v_mfma_f32_16x16x32_bf16 v[34:37], v[166:169], v[190:193], v[34:37]
	v_mfma_f32_16x16x32_bf16 v[26:29], v[170:173], v[186:189], v[26:29]
	v_mfma_f32_16x16x32_bf16 v[26:29], v[174:177], v[190:193], v[26:29]
	v_mfma_f32_16x16x32_bf16 v[18:21], v[162:165], v[194:197], v[18:21]
	v_mfma_f32_16x16x32_bf16 v[18:21], v[166:169], v[198:201], v[18:21]
	v_mfma_f32_16x16x32_bf16 v[10:13], v[170:173], v[194:197], v[10:13]
	v_mfma_f32_16x16x32_bf16 v[10:13], v[174:177], v[198:201], v[10:13]
	v_mfma_f32_16x16x32_bf16 v[6:9], v[162:165], v[202:205], v[6:9]
	v_mfma_f32_16x16x32_bf16 v[6:9], v[166:169], v[206:209], v[6:9]
	v_mfma_f32_16x16x32_bf16 v[2:5], v[170:173], v[202:205], v[2:5]
	v_mfma_f32_16x16x32_bf16 v[2:5], v[174:177], v[206:209], v[2:5]
	s_barrier
; #define PG8_LDA(dst, b, h) do { _Pragma("unroll") for (int m = 0; m < 4; ++m) _Pragma("unroll") for (int k = 0; k < 2; ++k) dst[m][k] = *(const PG8_LAS bf16x8*)(lds + PG8_SA(b, h) + aoff + m * 2048 + k * 1024); } while (0)
; #define PG8_LDB(dst, b, h) do { _Pragma("unroll") for (int n = 0; n < 2; ++n) _Pragma("unroll") for (int k = 0; k < 2; ++k) dst[n][k] = *(const PG8_LAS bf16x8*)(lds + PG8_SB(b, h) + boff + n * 2048 + k * 1024); } while (0)
; #define PG8_MMA(ai, bj, At, Bt) do { __builtin_amdgcn_s_setprio(1); _Pragma("unroll") for (int m = 0; m < 4; ++m) _Pragma("unroll") for (int n = 0; n < 2; ++n) _Pragma("unroll") for (int k = 0; k < 2; ++k) \
;         acc[ai][bj][m][n] = __builtin_amdgcn_mfma_f32_16x16x32_bf16(Bt[n][k], At[m][k], acc[ai][bj][m][n], 0, 0, 0); __builtin_amdgcn_s_setprio(0); } while (0)
; #define PG8_WAIT_V(n) asm volatile("s_waitcnt vmcnt(" #n ")" ::: "memory")
; #define PG8_WAIT_L(n) asm volatile("s_waitcnt lgkmcnt(" #n ")" ::: "memory")
; #define PG8_BAR __builtin_amdgcn_s_barrier()
; #define PG8_SCHED __builtin_amdgcn_sched_barrier(0)
; template <class Epi, class Sched, bool ALIGN_EPI = false, bool SP2 = false>
; __device__ __forceinline__ void gemm_phase(PG8_LAS unsigned char* lds, const Gemm g, const Sched& S, const Epi& E, const int tid) {
;     ...
;             PG8_LDB(B0, 1, 0); PG8_LDB(B1, 1, 1); PG8_SCHED; PG8_LDA(At, 1, 0); PG8_STAGE(PG8_SA(0, 1), a2 + hstepA, voffA);
;             PG8_WAIT_V(8); PG8_WAIT_L(0); PG8_BAR; PG8_MMA(0, 0, At, B0); PG8_MMA(0, 1, At, B1); PG8_BAR; PG8_SCHED;
;             PG8_LDA(At, 1, 1); PG8_STAGE(PG8_SB(1, 0), b3, voffB); PG8_STAGE(PG8_SB(1, 1), b3 + hstepB, voffB); PG8_STAGE(PG8_SA(1, 0), a3, voffA);
;             PG8_WAIT_V(8); PG8_WAIT_L(0); PG8_BAR; PG8_MMA(1, 0, At, B0); PG8_MMA(1, 1, At, B1); PG8_BAR; PG8_SCHED;
	v_add_u32_e32 v133, 0x18000, v144
	ds_read_b128 v[146:149], v133
	ds_read_b128 v[150:153], v133 offset:1024
	ds_read_b128 v[154:157], v133 offset:2048
	ds_read_b128 v[158:161], v133 offset:3072
	v_add_u32_e32 v133, 0x1c000, v144
	ds_read_b128 v[162:165], v133
	ds_read_b128 v[166:169], v133 offset:1024
	ds_read_b128 v[170:173], v133 offset:2048
	ds_read_b128 v[174:177], v133 offset:3072
	ds_read_b128 v[178:181], v145 offset:32768
	ds_read_b128 v[182:185], v145 offset:33792
	ds_read_b128 v[186:189], v145 offset:34816
	ds_read_b128 v[190:193], v145 offset:35840
	ds_read_b128 v[194:197], v145 offset:36864
	ds_read_b128 v[198:201], v145 offset:37888
	ds_read_b128 v[202:205], v145 offset:38912
	ds_read_b128 v[206:209], v145 offset:39936
	s_add_u32 s28, s42, 0x80000
	s_addc_u32 s29, s43, 0
	s_mov_b32 m0, s55
	s_nop 0
	global_load_lds_dwordx4 v136, s[28:29]
	s_nop 0
	s_mov_b32 m0, s56
	s_nop 0
	global_load_lds_dwordx4 v138, s[28:29]
	s_waitcnt vmcnt(8)
	s_waitcnt lgkmcnt(0)
	s_barrier
	v_mfma_f32_16x16x32_bf16 v[126:129], v[146:149], v[178:181], v[126:129]
	v_mfma_f32_16x16x32_bf16 v[126:129], v[150:153], v[182:185], v[126:129]
	v_mfma_f32_16x16x32_bf16 v[122:125], v[154:157], v[178:181], v[122:125]
	v_mfma_f32_16x16x32_bf16 v[122:125], v[158:161], v[182:185], v[122:125]
	v_mfma_f32_16x16x32_bf16 v[118:121], v[146:149], v[186:189], v[118:121]
	v_mfma_f32_16x16x32_bf16 v[118:121], v[150:153], v[190:193], v[118:121]
	v_mfma_f32_16x16x32_bf16 v[110:113], v[154:157], v[186:189], v[110:113]
	v_mfma_f32_16x16x32_bf16 v[110:113], v[158:161], v[190:193], v[110:113]
	v_mfma_f32_16x16x32_bf16 v[102:105], v[146:149], v[194:197], v[102:105]
	v_mfma_f32_16x16x32_bf16 v[102:105], v[150:153], v[198:201], v[102:105]
	v_mfma_f32_16x16x32_bf16 v[94:97], v[154:157], v[194:197], v[94:97]
	v_mfma_f32_16x16x32_bf16 v[94:97], v[158:161], v[198:201], v[94:97]
	v_mfma_f32_16x16x32_bf16 v[86:89], v[146:149], v[202:205], v[86:89]
	v_mfma_f32_16x16x32_bf16 v[86:89], v[150:153], v[206:209], v[86:89]
	v_mfma_f32_16x16x32_bf16 v[78:81], v[154:157], v[202:205], v[78:81]
	v_mfma_f32_16x16x32_bf16 v[78:81], v[158:161], v[206:209], v[78:81]
	v_mfma_f32_16x16x32_bf16 v[114:117], v[162:165], v[178:181], v[114:117]
	v_mfma_f32_16x16x32_bf16 v[114:117], v[166:169], v[182:185], v[114:117]
	v_mfma_f32_16x16x32_bf16 v[106:109], v[170:173], v[178:181], v[106:109]
	v_mfma_f32_16x16x32_bf16 v[106:109], v[174:177], v[182:185], v[106:109]
	v_mfma_f32_16x16x32_bf16 v[98:101], v[162:165], v[186:189], v[98:101]
	v_mfma_f32_16x16x32_bf16 v[98:101], v[166:169], v[190:193], v[98:101]
	v_mfma_f32_16x16x32_bf16 v[90:93], v[170:173], v[186:189], v[90:93]
	v_mfma_f32_16x16x32_bf16 v[90:93], v[174:177], v[190:193], v[90:93]
	v_mfma_f32_16x16x32_bf16 v[82:85], v[162:165], v[194:197], v[82:85]
	v_mfma_f32_16x16x32_bf16 v[82:85], v[166:169], v[198:201], v[82:85]
	v_mfma_f32_16x16x32_bf16 v[74:77], v[170:173], v[194:197], v[74:77]
	v_mfma_f32_16x16x32_bf16 v[74:77], v[174:177], v[198:201], v[74:77]
	v_mfma_f32_16x16x32_bf16 v[70:73], v[162:165], v[202:205], v[70:73]
	v_mfma_f32_16x16x32_bf16 v[70:73], v[166:169], v[206:209], v[70:73]
	v_mfma_f32_16x16x32_bf16 v[66:69], v[170:173], v[202:205], v[66:69]
	v_mfma_f32_16x16x32_bf16 v[66:69], v[174:177], v[206:209], v[66:69]
	s_barrier
	ds_read_b128 v[178:181], v145 offset:49152
	ds_read_b128 v[182:185], v145 offset:50176
	ds_read_b128 v[186:189], v145 offset:51200
	ds_read_b128 v[190:193], v145 offset:52224
	ds_read_b128 v[194:197], v145 offset:53248
	ds_read_b128 v[198:201], v145 offset:54272
	ds_read_b128 v[202:205], v145 offset:55296
	ds_read_b128 v[206:209], v145 offset:56320
	s_mov_b32 m0, s57
	s_nop 0
	global_load_lds_dwordx4 v137, s[40:41]
	s_add_u32 s28, s30, 0x80080
	s_mov_b32 m0, s58
	s_nop 0
	global_load_lds_dwordx4 v139, s[40:41]
	s_addc_u32 s29, s31, 0
	s_mov_b32 m0, s65
	s_nop 0
	global_load_lds_dwordx4 v137, s[28:29]
	s_nop 0
	s_mov_b32 m0, s69
	s_nop 0
	global_load_lds_dwordx4 v139, s[28:29]
	s_nop 0
	s_mov_b32 m0, s61
	s_nop 0
	global_load_lds_dwordx4 v136, s[38:39]
	s_nop 0
	s_mov_b32 m0, s64
	s_nop 0
	global_load_lds_dwordx4 v138, s[38:39]
	s_waitcnt vmcnt(8)
	s_waitcnt lgkmcnt(0)
	s_barrier
	v_mfma_f32_16x16x32_bf16 v[62:65], v[146:149], v[178:181], v[62:65]
	v_mfma_f32_16x16x32_bf16 v[62:65], v[150:153], v[182:185], v[62:65]
	v_mfma_f32_16x16x32_bf16 v[58:61], v[154:157], v[178:181], v[58:61]
	v_mfma_f32_16x16x32_bf16 v[58:61], v[158:161], v[182:185], v[58:61]
	v_mfma_f32_16x16x32_bf16 v[54:57], v[146:149], v[186:189], v[54:57]
	v_mfma_f32_16x16x32_bf16 v[54:57], v[150:153], v[190:193], v[54:57]
	v_mfma_f32_16x16x32_bf16 v[46:49], v[154:157], v[186:189], v[46:49]
	v_mfma_f32_16x16x32_bf16 v[46:49], v[158:161], v[190:193], v[46:49]
	v_mfma_f32_16x16x32_bf16 v[38:41], v[146:149], v[194:197], v[38:41]
	v_mfma_f32_16x16x32_bf16 v[38:41], v[150:153], v[198:201], v[38:41]
	v_mfma_f32_16x16x32_bf16 v[30:33], v[154:157], v[194:197], v[30:33]
	v_mfma_f32_16x16x32_bf16 v[30:33], v[158:161], v[198:201], v[30:33]
	v_mfma_f32_16x16x32_bf16 v[22:25], v[146:149], v[202:205], v[22:25]
	v_mfma_f32_16x16x32_bf16 v[22:25], v[150:153], v[206:209], v[22:25]
	v_mfma_f32_16x16x32_bf16 v[14:17], v[154:157], v[202:205], v[14:17]
	v_mfma_f32_16x16x32_bf16 v[14:17], v[158:161], v[206:209], v[14:17]
	v_mfma_f32_16x16x32_bf16 v[50:53], v[162:165], v[178:181], v[50:53]
	v_mfma_f32_16x16x32_bf16 v[50:53], v[166:169], v[182:185], v[50:53]
	v_mfma_f32_16x16x32_bf16 v[42:45], v[170:173], v[178:181], v[42:45]
	v_mfma_f32_16x16x32_bf16 v[42:45], v[174:177], v[182:185], v[42:45]
	v_mfma_f32_16x16x32_bf16 v[34:37], v[162:165], v[186:189], v[34:37]
	v_mfma_f32_16x16x32_bf16 v[34:37], v[166:169], v[190:193], v[34:37]
	v_mfma_f32_16x16x32_bf16 v[26:29], v[170:173], v[186:189], v[26:29]
	v_mfma_f32_16x16x32_bf16 v[26:29], v[174:177], v[190:193], v[26:29]
	v_mfma_f32_16x16x32_bf16 v[18:21], v[162:165], v[194:197], v[18:21]
	v_mfma_f32_16x16x32_bf16 v[18:21], v[166:169], v[198:201], v[18:21]
	v_mfma_f32_16x16x32_bf16 v[10:13], v[170:173], v[194:197], v[10:13]
	v_mfma_f32_16x16x32_bf16 v[10:13], v[174:177], v[198:201], v[10:13]
	v_mfma_f32_16x16x32_bf16 v[6:9], v[162:165], v[202:205], v[6:9]
	v_mfma_f32_16x16x32_bf16 v[6:9], v[166:169], v[206:209], v[6:9]
	v_mfma_f32_16x16x32_bf16 v[2:5], v[170:173], v[202:205], v[2:5]
	v_mfma_f32_16x16x32_bf16 v[2:5], v[174:177], v[206:209], v[2:5]
	s_barrier
	s_add_i32 s67, s67, 2
	s_add_u32 s97, s97, 0x100
	s_addc_u32 s59, s59, 0
	s_cmp_gt_u32 s67, 29
	s_mov_b64 s[28:29], s[34:35]
	s_cbranch_scc1 .LBB0_549

; #define PG8_LDA(dst, b, h) do { _Pragma("unroll") for (int m = 0; m < 4; ++m) _Pragma("unroll") for (int k = 0; k < 2; ++k) dst[m][k] = *(const PG8_LAS bf16x8*)(lds + PG8_SA(b, h) + aoff + m * 2048 + k * 1024); } while (0)
; #define PG8_LDB(dst, b, h) do { _Pragma("unroll") for (int n = 0; n < 2; ++n) _Pragma("unroll") for (int k = 0; k < 2; ++k) dst[n][k] = *(const PG8_LAS bf16x8*)(lds + PG8_SB(b, h) + boff + n * 2048 + k * 1024); } while (0)
; #define PG8_MMA(ai, bj, At, Bt) do { __builtin_amdgcn_s_setprio(1); _Pragma("unroll") for (int m = 0; m < 4; ++m) _Pragma("unroll") for (int n = 0; n < 2; ++n) _Pragma("unroll") for (int k = 0; k < 2; ++k) \
;         acc[ai][bj][m][n] = __builtin_amdgcn_mfma_f32_16x16x32_bf16(Bt[n][k], At[m][k], acc[ai][bj][m][n], 0, 0, 0); __builtin_amdgcn_s_setprio(0); } while (0)
; #define PG8_WAIT_V(n) asm volatile("s_waitcnt vmcnt(" #n ")" ::: "memory")
; #define PG8_WAIT_L(n) asm volatile("s_waitcnt lgkmcnt(" #n ")" ::: "memory")
; #define PG8_BAR __builtin_amdgcn_s_barrier()
; #define PG8_SCHED __builtin_amdgcn_sched_barrier(0)
; template <class Epi, class Sched, bool ALIGN_EPI = false, bool SP2 = false>
; __device__ __forceinline__ void gemm_phase(PG8_LAS unsigned char* lds, const Gemm g, const Sched& S, const Epi& E, const int tid) {
;     ...
;             const char* a1 = cA + (size_t)(t + 1) * kstepA;
;             const char* a2 = last ? nA : cA + (size_t)(t + 2) * kstepA; const char* b2 = last ? nB : cB + (size_t)(t + 2) * kstepB;
;             const char* a3 = a2 + kstepA; const char* b3 = b2 + kstepB;
;             if (last && has_next) S.a_ready(nxt);
;             if constexpr (SP2) {
;             PG8_LDB(B0, 0, 0); PG8_LDB(B1, 0, 1); PG8_SCHED; PG8_LDA(At, 0, 0); PG8_STAGE(PG8_SA(1, 1), a1 + hstepA, voffA);
;             PG8_WAIT_V(8); PG8_WAIT_L(0); PG8_BAR; PG8_MMA(0, 0, At, B0); PG8_MMA(0, 1, At, B1); PG8_BAR; PG8_SCHED;
;             PG8_LDA(At, 0, 1); PG8_STAGE(PG8_SB(0, 0), b2, voffB); PG8_STAGE(PG8_SB(0, 1), b2 + hstepB, voffB); PG8_STAGE(PG8_SA(0, 0), a2, voffA);
;             PG8_WAIT_V(8); PG8_WAIT_L(0); PG8_BAR; PG8_MMA(1, 0, At, B0); PG8_MMA(1, 1, At, B1); PG8_BAR; PG8_SCHED;
.LBB0_813:
	v_add_u32_e32 v0, 0x10000, v135
	ds_read_b128 v[138:141], v0
	ds_read_b128 v[142:145], v0 offset:1024
	ds_read_b128 v[146:149], v0 offset:2048
	ds_read_b128 v[150:153], v0 offset:3072
	v_add_u32_e32 v0, 0x14000, v135
	ds_read_b128 v[154:157], v0
	ds_read_b128 v[158:161], v0 offset:1024
	ds_read_b128 v[162:165], v0 offset:2048
	ds_read_b128 v[166:169], v0 offset:3072
	s_add_u32 s4, s18, 0x100
	s_addc_u32 s5, s19, 0
	s_cmp_eq_u32 s61, 12
	s_cselect_b32 s24, s14, s4
	s_cselect_b32 s25, s15, s5
	s_cselect_b32 s22, s57, s58
	s_cselect_b32 s23, s13, s59
	s_add_u32 s20, s24, 0x80
	s_addc_u32 s21, s25, 0
	ds_read_b128 v[170:173], v136
	ds_read_b128 v[174:177], v136 offset:1024
	ds_read_b128 v[178:181], v136 offset:2048
	ds_read_b128 v[182:185], v136 offset:3072
	ds_read_b128 v[186:189], v136 offset:4096
	ds_read_b128 v[190:193], v136 offset:5120
	ds_read_b128 v[194:197], v136 offset:6144
	ds_read_b128 v[198:201], v136 offset:7168
	s_add_u32 s18, s18, 0xc0080
	s_addc_u32 s19, s19, 0
	s_mov_b32 m0, s49
	s_nop 0
	global_load_lds_dwordx4 v131, s[18:19]
	s_nop 0
	s_mov_b32 m0, s50
	s_nop 0
	global_load_lds_dwordx4 v133, s[18:19]
	s_waitcnt vmcnt(8)
	s_waitcnt lgkmcnt(0)
	s_barrier
	v_mfma_f32_16x16x32_bf16 v[126:129], v[138:141], v[170:173], v[126:129]
	v_mfma_f32_16x16x32_bf16 v[126:129], v[142:145], v[174:177], v[126:129]
	v_mfma_f32_16x16x32_bf16 v[122:125], v[146:149], v[170:173], v[122:125]
	v_mfma_f32_16x16x32_bf16 v[122:125], v[150:153], v[174:177], v[122:125]
	v_mfma_f32_16x16x32_bf16 v[118:121], v[138:141], v[178:181], v[118:121]
	v_mfma_f32_16x16x32_bf16 v[118:121], v[142:145], v[182:185], v[118:121]
	v_mfma_f32_16x16x32_bf16 v[114:117], v[146:149], v[178:181], v[114:117]
	v_mfma_f32_16x16x32_bf16 v[114:117], v[150:153], v[182:185], v[114:117]
	v_mfma_f32_16x16x32_bf16 v[102:105], v[138:141], v[186:189], v[102:105]
	v_mfma_f32_16x16x32_bf16 v[102:105], v[142:145], v[190:193], v[102:105]
	v_mfma_f32_16x16x32_bf16 v[98:101], v[146:149], v[186:189], v[98:101]
	v_mfma_f32_16x16x32_bf16 v[98:101], v[150:153], v[190:193], v[98:101]
	v_mfma_f32_16x16x32_bf16 v[86:89], v[138:141], v[194:197], v[86:89]
	v_mfma_f32_16x16x32_bf16 v[86:89], v[142:145], v[198:201], v[86:89]
	v_mfma_f32_16x16x32_bf16 v[82:85], v[146:149], v[194:197], v[82:85]
	v_mfma_f32_16x16x32_bf16 v[82:85], v[150:153], v[198:201], v[82:85]
	v_mfma_f32_16x16x32_bf16 v[110:113], v[154:157], v[170:173], v[110:113]
	v_mfma_f32_16x16x32_bf16 v[110:113], v[158:161], v[174:177], v[110:113]
	v_mfma_f32_16x16x32_bf16 v[106:109], v[162:165], v[170:173], v[106:109]
	v_mfma_f32_16x16x32_bf16 v[106:109], v[166:169], v[174:177], v[106:109]
	v_mfma_f32_16x16x32_bf16 v[94:97], v[154:157], v[178:181], v[94:97]
	v_mfma_f32_16x16x32_bf16 v[94:97], v[158:161], v[182:185], v[94:97]
	v_mfma_f32_16x16x32_bf16 v[90:93], v[162:165], v[178:181], v[90:93]
	v_mfma_f32_16x16x32_bf16 v[90:93], v[166:169], v[182:185], v[90:93]
	v_mfma_f32_16x16x32_bf16 v[78:81], v[154:157], v[186:189], v[78:81]
	v_mfma_f32_16x16x32_bf16 v[78:81], v[158:161], v[190:193], v[78:81]
	v_mfma_f32_16x16x32_bf16 v[74:77], v[162:165], v[186:189], v[74:77]
	v_mfma_f32_16x16x32_bf16 v[74:77], v[166:169], v[190:193], v[74:77]
	v_mfma_f32_16x16x32_bf16 v[70:73], v[154:157], v[194:197], v[70:73]
	v_mfma_f32_16x16x32_bf16 v[70:73], v[158:161], v[198:201], v[70:73]
	v_mfma_f32_16x16x32_bf16 v[66:69], v[162:165], v[194:197], v[66:69]
	v_mfma_f32_16x16x32_bf16 v[66:69], v[166:169], v[198:201], v[66:69]
	s_barrier
	ds_read_b128 v[170:173], v136 offset:16384
	ds_read_b128 v[174:177], v136 offset:17408
	ds_read_b128 v[178:181], v136 offset:18432
	ds_read_b128 v[182:185], v136 offset:19456
	ds_read_b128 v[186:189], v136 offset:20480
	ds_read_b128 v[190:193], v136 offset:21504
	ds_read_b128 v[194:197], v136 offset:22528
	ds_read_b128 v[198:201], v136 offset:23552
	s_mov_b32 m0, s31
	s_nop 0
	global_load_lds_dwordx4 v132, s[22:23]
	s_nop 0
	s_mov_b32 m0, s34
	s_nop 0
	global_load_lds_dwordx4 v134, s[22:23]
	s_add_u32 s18, s22, 0x40000
	s_addc_u32 s19, s23, 0
	s_mov_b32 m0, s35
	s_nop 0
	global_load_lds_dwordx4 v132, s[18:19]
	s_nop 0
	s_mov_b32 m0, s37
	s_nop 0
	global_load_lds_dwordx4 v134, s[18:19]
	s_mov_b32 m0, s10
	s_nop 0
	global_load_lds_dwordx4 v131, s[24:25]
	s_nop 0
	s_mov_b32 m0, s38
	s_nop 0
	global_load_lds_dwordx4 v133, s[24:25]
	s_waitcnt vmcnt(8)
	s_waitcnt lgkmcnt(0)
	s_barrier
	v_mfma_f32_16x16x32_bf16 v[62:65], v[138:141], v[170:173], v[62:65]
	v_mfma_f32_16x16x32_bf16 v[62:65], v[142:145], v[174:177], v[62:65]
	v_mfma_f32_16x16x32_bf16 v[58:61], v[146:149], v[170:173], v[58:61]
	v_mfma_f32_16x16x32_bf16 v[58:61], v[150:153], v[174:177], v[58:61]
	v_mfma_f32_16x16x32_bf16 v[54:57], v[138:141], v[178:181], v[54:57]
	v_mfma_f32_16x16x32_bf16 v[54:57], v[142:145], v[182:185], v[54:57]
	v_mfma_f32_16x16x32_bf16 v[50:53], v[146:149], v[178:181], v[50:53]
	v_mfma_f32_16x16x32_bf16 v[50:53], v[150:153], v[182:185], v[50:53]
	v_mfma_f32_16x16x32_bf16 v[38:41], v[138:141], v[186:189], v[38:41]
	v_mfma_f32_16x16x32_bf16 v[38:41], v[142:145], v[190:193], v[38:41]
	v_mfma_f32_16x16x32_bf16 v[34:37], v[146:149], v[186:189], v[34:37]
	v_mfma_f32_16x16x32_bf16 v[34:37], v[150:153], v[190:193], v[34:37]
	v_mfma_f32_16x16x32_bf16 v[22:25], v[138:141], v[194:197], v[22:25]
	v_mfma_f32_16x16x32_bf16 v[22:25], v[142:145], v[198:201], v[22:25]
	v_mfma_f32_16x16x32_bf16 v[18:21], v[146:149], v[194:197], v[18:21]
	v_mfma_f32_16x16x32_bf16 v[18:21], v[150:153], v[198:201], v[18:21]
	v_mfma_f32_16x16x32_bf16 v[46:49], v[154:157], v[170:173], v[46:49]
	v_mfma_f32_16x16x32_bf16 v[46:49], v[158:161], v[174:177], v[46:49]
	v_mfma_f32_16x16x32_bf16 v[42:45], v[162:165], v[170:173], v[42:45]
	v_mfma_f32_16x16x32_bf16 v[42:45], v[166:169], v[174:177], v[42:45]
	v_mfma_f32_16x16x32_bf16 v[30:33], v[154:157], v[178:181], v[30:33]
	v_mfma_f32_16x16x32_bf16 v[30:33], v[158:161], v[182:185], v[30:33]
	v_mfma_f32_16x16x32_bf16 v[26:29], v[162:165], v[178:181], v[26:29]
	v_mfma_f32_16x16x32_bf16 v[26:29], v[166:169], v[182:185], v[26:29]
	v_mfma_f32_16x16x32_bf16 v[14:17], v[154:157], v[186:189], v[14:17]
	v_mfma_f32_16x16x32_bf16 v[14:17], v[158:161], v[190:193], v[14:17]
	v_mfma_f32_16x16x32_bf16 v[10:13], v[162:165], v[186:189], v[10:13]
	v_mfma_f32_16x16x32_bf16 v[10:13], v[166:169], v[190:193], v[10:13]
	v_mfma_f32_16x16x32_bf16 v[6:9], v[154:157], v[194:197], v[6:9]
	v_mfma_f32_16x16x32_bf16 v[6:9], v[158:161], v[198:201], v[6:9]
	v_mfma_f32_16x16x32_bf16 v[2:5], v[162:165], v[194:197], v[2:5]
	v_mfma_f32_16x16x32_bf16 v[2:5], v[166:169], v[198:201], v[2:5]
	s_barrier
; #define PG8_LDA(dst, b, h) do { _Pragma("unroll") for (int m = 0; m < 4; ++m) _Pragma("unroll") for (int k = 0; k < 2; ++k) dst[m][k] = *(const PG8_LAS bf16x8*)(lds + PG8_SA(b, h) + aoff + m * 2048 + k * 1024); } while (0)
; #define PG8_LDB(dst, b, h) do { _Pragma("unroll") for (int n = 0; n < 2; ++n) _Pragma("unroll") for (int k = 0; k < 2; ++k) dst[n][k] = *(const PG8_LAS bf16x8*)(lds + PG8_SB(b, h) + boff + n * 2048 + k * 1024); } while (0)
; #define PG8_MMA(ai, bj, At, Bt) do { __builtin_amdgcn_s_setprio(1); _Pragma("unroll") for (int m = 0; m < 4; ++m) _Pragma("unroll") for (int n = 0; n < 2; ++n) _Pragma("unroll") for (int k = 0; k < 2; ++k) \
;         acc[ai][bj][m][n] = __builtin_amdgcn_mfma_f32_16x16x32_bf16(Bt[n][k], At[m][k], acc[ai][bj][m][n], 0, 0, 0); __builtin_amdgcn_s_setprio(0); } while (0)
; #define PG8_WAIT_V(n) asm volatile("s_waitcnt vmcnt(" #n ")" ::: "memory")
; #define PG8_WAIT_L(n) asm volatile("s_waitcnt lgkmcnt(" #n ")" ::: "memory")
; #define PG8_BAR __builtin_amdgcn_s_barrier()
; #define PG8_SCHED __builtin_amdgcn_sched_barrier(0)
; template <class Epi, class Sched, bool ALIGN_EPI = false, bool SP2 = false>
; __device__ __forceinline__ void gemm_phase(PG8_LAS unsigned char* lds, const Gemm g, const Sched& S, const Epi& E, const int tid) {
;     ...
;             PG8_LDB(B0, 1, 0); PG8_LDB(B1, 1, 1); PG8_SCHED; PG8_LDA(At, 1, 0); PG8_STAGE(PG8_SA(0, 1), a2 + hstepA, voffA);
;             PG8_WAIT_V(8); PG8_WAIT_L(0); PG8_BAR; PG8_MMA(0, 0, At, B0); PG8_MMA(0, 1, At, B1); PG8_BAR; PG8_SCHED;
;             PG8_LDA(At, 1, 1); PG8_STAGE(PG8_SB(1, 0), b3, voffB); PG8_STAGE(PG8_SB(1, 1), b3 + hstepB, voffB); PG8_STAGE(PG8_SA(1, 0), a3, voffA);
;             PG8_WAIT_V(8); PG8_WAIT_L(0); PG8_BAR; PG8_MMA(1, 0, At, B0); PG8_MMA(1, 1, At, B1); PG8_BAR; PG8_SCHED;
	v_add_u32_e32 v0, 0x18000, v135
	ds_read_b128 v[138:141], v0
	ds_read_b128 v[142:145], v0 offset:1024
	ds_read_b128 v[146:149], v0 offset:2048
	ds_read_b128 v[150:153], v0 offset:3072
	v_add_u32_e32 v0, 0x1c000, v135
	ds_read_b128 v[154:157], v0
	ds_read_b128 v[158:161], v0 offset:1024
	ds_read_b128 v[162:165], v0 offset:2048
	ds_read_b128 v[166:169], v0 offset:3072
	ds_read_b128 v[170:173], v136 offset:32768
	ds_read_b128 v[174:177], v136 offset:33792
	ds_read_b128 v[178:181], v136 offset:34816
	ds_read_b128 v[182:185], v136 offset:35840
	ds_read_b128 v[186:189], v136 offset:36864
	ds_read_b128 v[190:193], v136 offset:37888
	ds_read_b128 v[194:197], v136 offset:38912
	ds_read_b128 v[198:201], v136 offset:39936
	s_add_u32 s18, s24, 0xc0000
	s_addc_u32 s19, s25, 0
	s_mov_b32 m0, s39
	s_nop 0
	global_load_lds_dwordx4 v131, s[18:19]
	s_nop 0
	s_mov_b32 m0, s40
	s_nop 0
	global_load_lds_dwordx4 v133, s[18:19]
	s_waitcnt vmcnt(8)
	s_waitcnt lgkmcnt(0)
	s_barrier
	v_mfma_f32_16x16x32_bf16 v[126:129], v[138:141], v[170:173], v[126:129]
	v_mfma_f32_16x16x32_bf16 v[126:129], v[142:145], v[174:177], v[126:129]
	v_mfma_f32_16x16x32_bf16 v[122:125], v[146:149], v[170:173], v[122:125]
	v_mfma_f32_16x16x32_bf16 v[122:125], v[150:153], v[174:177], v[122:125]
	v_mfma_f32_16x16x32_bf16 v[118:121], v[138:141], v[178:181], v[118:121]
	v_mfma_f32_16x16x32_bf16 v[118:121], v[142:145], v[182:185], v[118:121]
	v_mfma_f32_16x16x32_bf16 v[114:117], v[146:149], v[178:181], v[114:117]
	v_mfma_f32_16x16x32_bf16 v[114:117], v[150:153], v[182:185], v[114:117]
	v_mfma_f32_16x16x32_bf16 v[102:105], v[138:141], v[186:189], v[102:105]
	v_mfma_f32_16x16x32_bf16 v[102:105], v[142:145], v[190:193], v[102:105]
	v_mfma_f32_16x16x32_bf16 v[98:101], v[146:149], v[186:189], v[98:101]
	v_mfma_f32_16x16x32_bf16 v[98:101], v[150:153], v[190:193], v[98:101]
	v_mfma_f32_16x16x32_bf16 v[86:89], v[138:141], v[194:197], v[86:89]
	v_mfma_f32_16x16x32_bf16 v[86:89], v[142:145], v[198:201], v[86:89]
	v_mfma_f32_16x16x32_bf16 v[82:85], v[146:149], v[194:197], v[82:85]
	v_mfma_f32_16x16x32_bf16 v[82:85], v[150:153], v[198:201], v[82:85]
	v_mfma_f32_16x16x32_bf16 v[110:113], v[154:157], v[170:173], v[110:113]
	v_mfma_f32_16x16x32_bf16 v[110:113], v[158:161], v[174:177], v[110:113]
	v_mfma_f32_16x16x32_bf16 v[106:109], v[162:165], v[170:173], v[106:109]
	v_mfma_f32_16x16x32_bf16 v[106:109], v[166:169], v[174:177], v[106:109]
	v_mfma_f32_16x16x32_bf16 v[94:97], v[154:157], v[178:181], v[94:97]
	v_mfma_f32_16x16x32_bf16 v[94:97], v[158:161], v[182:185], v[94:97]
	v_mfma_f32_16x16x32_bf16 v[90:93], v[162:165], v[178:181], v[90:93]
	v_mfma_f32_16x16x32_bf16 v[90:93], v[166:169], v[182:185], v[90:93]
	v_mfma_f32_16x16x32_bf16 v[78:81], v[154:157], v[186:189], v[78:81]
	v_mfma_f32_16x16x32_bf16 v[78:81], v[158:161], v[190:193], v[78:81]
	v_mfma_f32_16x16x32_bf16 v[74:77], v[162:165], v[186:189], v[74:77]
	v_mfma_f32_16x16x32_bf16 v[74:77], v[166:169], v[190:193], v[74:77]
	v_mfma_f32_16x16x32_bf16 v[70:73], v[154:157], v[194:197], v[70:73]
	v_mfma_f32_16x16x32_bf16 v[70:73], v[158:161], v[198:201], v[70:73]
	v_mfma_f32_16x16x32_bf16 v[66:69], v[162:165], v[194:197], v[66:69]
	v_mfma_f32_16x16x32_bf16 v[66:69], v[166:169], v[198:201], v[66:69]
	s_barrier
	ds_read_b128 v[170:173], v136 offset:49152
	ds_read_b128 v[174:177], v136 offset:50176
	ds_read_b128 v[178:181], v136 offset:51200
	ds_read_b128 v[182:185], v136 offset:52224
	ds_read_b128 v[186:189], v136 offset:53248
	ds_read_b128 v[190:193], v136 offset:54272
	ds_read_b128 v[194:197], v136 offset:55296
	ds_read_b128 v[198:201], v136 offset:56320
	s_add_u32 s18, s22, 0x80
	s_addc_u32 s19, s23, 0
	s_mov_b32 m0, s43
	s_nop 0
	global_load_lds_dwordx4 v132, s[18:19]
	s_nop 0
	s_mov_b32 m0, s44
	s_nop 0
	global_load_lds_dwordx4 v134, s[18:19]
	s_add_u32 s18, s22, 0x40080
	s_addc_u32 s19, s23, 0
	s_mov_b32 m0, s47
	s_nop 0
	global_load_lds_dwordx4 v132, s[18:19]
	s_nop 0
	s_mov_b32 m0, s48
	s_nop 0
	global_load_lds_dwordx4 v134, s[18:19]
	s_mov_b32 m0, s45
	s_nop 0
	global_load_lds_dwordx4 v131, s[20:21]
	s_nop 0
	s_mov_b32 m0, s46
	s_nop 0
	global_load_lds_dwordx4 v133, s[20:21]
	s_waitcnt vmcnt(8)
	s_waitcnt lgkmcnt(0)
	s_barrier
	v_mfma_f32_16x16x32_bf16 v[62:65], v[138:141], v[170:173], v[62:65]
	v_mfma_f32_16x16x32_bf16 v[62:65], v[142:145], v[174:177], v[62:65]
	v_mfma_f32_16x16x32_bf16 v[58:61], v[146:149], v[170:173], v[58:61]
	v_mfma_f32_16x16x32_bf16 v[58:61], v[150:153], v[174:177], v[58:61]
	v_mfma_f32_16x16x32_bf16 v[54:57], v[138:141], v[178:181], v[54:57]
	v_mfma_f32_16x16x32_bf16 v[54:57], v[142:145], v[182:185], v[54:57]
	v_mfma_f32_16x16x32_bf16 v[50:53], v[146:149], v[178:181], v[50:53]
	v_mfma_f32_16x16x32_bf16 v[50:53], v[150:153], v[182:185], v[50:53]
	v_mfma_f32_16x16x32_bf16 v[38:41], v[138:141], v[186:189], v[38:41]
	v_mfma_f32_16x16x32_bf16 v[38:41], v[142:145], v[190:193], v[38:41]
	v_mfma_f32_16x16x32_bf16 v[34:37], v[146:149], v[186:189], v[34:37]
	v_mfma_f32_16x16x32_bf16 v[34:37], v[150:153], v[190:193], v[34:37]
	v_mfma_f32_16x16x32_bf16 v[22:25], v[138:141], v[194:197], v[22:25]
	v_mfma_f32_16x16x32_bf16 v[22:25], v[142:145], v[198:201], v[22:25]
	v_mfma_f32_16x16x32_bf16 v[18:21], v[146:149], v[194:197], v[18:21]
	v_mfma_f32_16x16x32_bf16 v[18:21], v[150:153], v[198:201], v[18:21]
	v_mfma_f32_16x16x32_bf16 v[46:49], v[154:157], v[170:173], v[46:49]
	v_mfma_f32_16x16x32_bf16 v[46:49], v[158:161], v[174:177], v[46:49]
	v_mfma_f32_16x16x32_bf16 v[42:45], v[162:165], v[170:173], v[42:45]
	v_mfma_f32_16x16x32_bf16 v[42:45], v[166:169], v[174:177], v[42:45]
	v_mfma_f32_16x16x32_bf16 v[30:33], v[154:157], v[178:181], v[30:33]
	v_mfma_f32_16x16x32_bf16 v[30:33], v[158:161], v[182:185], v[30:33]
	v_mfma_f32_16x16x32_bf16 v[26:29], v[162:165], v[178:181], v[26:29]
	v_mfma_f32_16x16x32_bf16 v[26:29], v[166:169], v[182:185], v[26:29]
	v_mfma_f32_16x16x32_bf16 v[14:17], v[154:157], v[186:189], v[14:17]
	v_mfma_f32_16x16x32_bf16 v[14:17], v[158:161], v[190:193], v[14:17]
	v_mfma_f32_16x16x32_bf16 v[10:13], v[162:165], v[186:189], v[10:13]
	v_mfma_f32_16x16x32_bf16 v[10:13], v[166:169], v[190:193], v[10:13]
	v_mfma_f32_16x16x32_bf16 v[6:9], v[154:157], v[194:197], v[6:9]
	v_mfma_f32_16x16x32_bf16 v[6:9], v[158:161], v[198:201], v[6:9]
	v_mfma_f32_16x16x32_bf16 v[2:5], v[162:165], v[194:197], v[2:5]
	v_mfma_f32_16x16x32_bf16 v[2:5], v[166:169], v[198:201], v[2:5]
	s_barrier
	s_add_i32 s61, s61, 2
	s_add_u32 s58, s58, 0x100
	s_addc_u32 s59, s59, 0
	s_cmp_gt_u32 s61, 13
	s_mov_b64 s[18:19], s[4:5]
	s_cbranch_scc0 .LBB0_813
	s_and_b64 vcc, exec, s[8:9]
	s_cbranch_vccz .LBB0_816
	s_barrier

; #define PG8_LDA(dst, b, h) do { _Pragma("unroll") for (int m = 0; m < 4; ++m) _Pragma("unroll") for (int k = 0; k < 2; ++k) dst[m][k] = *(const PG8_LAS bf16x8*)(lds + PG8_SA(b, h) + aoff + m * 2048 + k * 1024); } while (0)
; #define PG8_LDB(dst, b, h) do { _Pragma("unroll") for (int n = 0; n < 2; ++n) _Pragma("unroll") for (int k = 0; k < 2; ++k) dst[n][k] = *(const PG8_LAS bf16x8*)(lds + PG8_SB(b, h) + boff + n * 2048 + k * 1024); } while (0)
; #define PG8_MMA(ai, bj, At, Bt) do { __builtin_amdgcn_s_setprio(1); _Pragma("unroll") for (int m = 0; m < 4; ++m) _Pragma("unroll") for (int n = 0; n < 2; ++n) _Pragma("unroll") for (int k = 0; k < 2; ++k) \
;         acc[ai][bj][m][n] = __builtin_amdgcn_mfma_f32_16x16x32_bf16(Bt[n][k], At[m][k], acc[ai][bj][m][n], 0, 0, 0); __builtin_amdgcn_s_setprio(0); } while (0)
; #define PG8_WAIT_V(n) asm volatile("s_waitcnt vmcnt(" #n ")" ::: "memory")
; #define PG8_WAIT_L(n) asm volatile("s_waitcnt lgkmcnt(" #n ")" ::: "memory")
; #define PG8_BAR __builtin_amdgcn_s_barrier()
; #define PG8_SCHED __builtin_amdgcn_sched_barrier(0)
; template <class Epi, class Sched, bool ALIGN_EPI = false, bool SP2 = false>
; __device__ __forceinline__ void gemm_phase(PG8_LAS unsigned char* lds, const Gemm g, const Sched& S, const Epi& E, const int tid) {
;     ...
;             const char* a1 = cA + (size_t)(t + 1) * kstepA;
;             const char* a2 = last ? nA : cA + (size_t)(t + 2) * kstepA; const char* b2 = last ? nB : cB + (size_t)(t + 2) * kstepB;
;             const char* a3 = a2 + kstepA; const char* b3 = b2 + kstepB;
;             if (last && has_next) S.a_ready(nxt);
;             if constexpr (SP2) {
;             PG8_LDB(B0, 0, 0); PG8_LDB(B1, 0, 1); PG8_SCHED; PG8_LDA(At, 0, 0); PG8_STAGE(PG8_SA(1, 1), a1 + hstepA, voffA);
;             PG8_WAIT_V(8); PG8_WAIT_L(0); PG8_BAR; PG8_MMA(0, 0, At, B0); PG8_MMA(0, 1, At, B1); PG8_BAR; PG8_SCHED;
;             PG8_LDA(At, 0, 1); PG8_STAGE(PG8_SB(0, 0), b2, voffB); PG8_STAGE(PG8_SB(0, 1), b2 + hstepB, voffB); PG8_STAGE(PG8_SA(0, 0), a2, voffA);
;             PG8_WAIT_V(8); PG8_WAIT_L(0); PG8_BAR; PG8_MMA(1, 0, At, B0); PG8_MMA(1, 1, At, B1); PG8_BAR; PG8_SCHED;
.LBB0_899:
	s_or_b64 exec, exec, s[42:43]
	v_add_u32_e32 v144, 0x10000, v200
	v_add_u32_e32 v160, 0x14000, v200
	s_add_u32 s42, s34, 0x100
	ds_read_b128 v[132:135], v144
	ds_read_b128 v[136:139], v144 offset:1024
	ds_read_b128 v[140:143], v144 offset:2048
	ds_read_b128 v[144:147], v144 offset:3072
	ds_read_b128 v[148:151], v160
	ds_read_b128 v[152:155], v160 offset:1024
	ds_read_b128 v[156:159], v160 offset:2048
	ds_read_b128 v[160:163], v160 offset:3072
	s_addc_u32 s43, s35, 0
	s_and_b64 s[40:41], s[40:41], exec
	s_cselect_b32 s48, vcc_lo, s42
	s_cselect_b32 s49, s21, s43
	s_cselect_b32 s41, s23, s67
	s_cselect_b32 s40, vcc_hi, s59
	s_add_u32 s44, s48, 0x80
	s_addc_u32 s45, s49, 0
	s_add_u32 s46, s40, 0x80
	s_addc_u32 s47, s41, 0
	ds_read_b128 v[164:167], v201
	ds_read_b128 v[168:171], v201 offset:1024
	ds_read_b128 v[172:175], v201 offset:2048
	ds_read_b128 v[176:179], v201 offset:3072
	ds_read_b128 v[180:183], v201 offset:4096
	ds_read_b128 v[184:187], v201 offset:5120
	ds_read_b128 v[202:205], v201 offset:6144
	ds_read_b128 v[206:209], v201 offset:7168
	s_add_u32 s34, s34, 0x80080
	s_addc_u32 s35, s35, 0
	s_mov_b32 m0, s96
	s_nop 0
	global_load_lds_dwordx4 v192, s[34:35]
	s_nop 0
	s_mov_b32 m0, s97
	s_nop 0
	global_load_lds_dwordx4 v194, s[34:35]
	s_waitcnt vmcnt(8)
	s_waitcnt lgkmcnt(0)
	s_barrier
	v_mfma_f32_16x16x32_bf16 v[126:129], v[132:135], v[164:167], v[126:129]
	v_mfma_f32_16x16x32_bf16 v[126:129], v[136:139], v[168:171], v[126:129]
	v_mfma_f32_16x16x32_bf16 v[122:125], v[140:143], v[164:167], v[122:125]
	v_mfma_f32_16x16x32_bf16 v[122:125], v[144:147], v[168:171], v[122:125]
	v_mfma_f32_16x16x32_bf16 v[118:121], v[132:135], v[172:175], v[118:121]
	v_mfma_f32_16x16x32_bf16 v[118:121], v[136:139], v[176:179], v[118:121]
	v_mfma_f32_16x16x32_bf16 v[114:117], v[140:143], v[172:175], v[114:117]
	v_mfma_f32_16x16x32_bf16 v[114:117], v[144:147], v[176:179], v[114:117]
	v_mfma_f32_16x16x32_bf16 v[94:97], v[132:135], v[180:183], v[94:97]
	v_mfma_f32_16x16x32_bf16 v[94:97], v[136:139], v[184:187], v[94:97]
	v_mfma_f32_16x16x32_bf16 v[90:93], v[140:143], v[180:183], v[90:93]
	v_mfma_f32_16x16x32_bf16 v[90:93], v[144:147], v[184:187], v[90:93]
	v_mfma_f32_16x16x32_bf16 v[78:81], v[132:135], v[202:205], v[78:81]
	v_mfma_f32_16x16x32_bf16 v[78:81], v[136:139], v[206:209], v[78:81]
	v_mfma_f32_16x16x32_bf16 v[74:77], v[140:143], v[202:205], v[74:77]
	v_mfma_f32_16x16x32_bf16 v[74:77], v[144:147], v[206:209], v[74:77]
	v_mfma_f32_16x16x32_bf16 v[110:113], v[148:151], v[164:167], v[110:113]
	v_mfma_f32_16x16x32_bf16 v[110:113], v[152:155], v[168:171], v[110:113]
	v_mfma_f32_16x16x32_bf16 v[106:109], v[156:159], v[164:167], v[106:109]
	v_mfma_f32_16x16x32_bf16 v[106:109], v[160:163], v[168:171], v[106:109]
	v_mfma_f32_16x16x32_bf16 v[102:105], v[148:151], v[172:175], v[102:105]
	v_mfma_f32_16x16x32_bf16 v[102:105], v[152:155], v[176:179], v[102:105]
	v_mfma_f32_16x16x32_bf16 v[98:101], v[156:159], v[172:175], v[98:101]
	v_mfma_f32_16x16x32_bf16 v[98:101], v[160:163], v[176:179], v[98:101]
	v_mfma_f32_16x16x32_bf16 v[86:89], v[148:151], v[180:183], v[86:89]
	v_mfma_f32_16x16x32_bf16 v[86:89], v[152:155], v[184:187], v[86:89]
	v_mfma_f32_16x16x32_bf16 v[82:85], v[156:159], v[180:183], v[82:85]
	v_mfma_f32_16x16x32_bf16 v[82:85], v[160:163], v[184:187], v[82:85]
	v_mfma_f32_16x16x32_bf16 v[70:73], v[148:151], v[202:205], v[70:73]
	v_mfma_f32_16x16x32_bf16 v[70:73], v[152:155], v[206:209], v[70:73]
	v_mfma_f32_16x16x32_bf16 v[66:69], v[156:159], v[202:205], v[66:69]
	v_mfma_f32_16x16x32_bf16 v[66:69], v[160:163], v[206:209], v[66:69]
	s_barrier
	ds_read_b128 v[164:167], v201 offset:16384
	ds_read_b128 v[168:171], v201 offset:17408
	ds_read_b128 v[172:175], v201 offset:18432
	ds_read_b128 v[176:179], v201 offset:19456
	ds_read_b128 v[180:183], v201 offset:20480
	ds_read_b128 v[184:187], v201 offset:21504
	ds_read_b128 v[202:205], v201 offset:22528
	ds_read_b128 v[206:209], v201 offset:23552
	s_mov_b32 m0, s29
	s_nop 0
	global_load_lds_dwordx4 v193, s[40:41]
	s_nop 0
	s_mov_b32 m0, s31
	s_nop 0
	global_load_lds_dwordx4 v195, s[40:41]
	s_add_u32 s34, s40, 0x80000
	s_addc_u32 s35, s41, 0
	s_mov_b32 m0, s54
	s_nop 0
	global_load_lds_dwordx4 v193, s[34:35]
	s_nop 0
	s_mov_b32 m0, s55
	s_nop 0
	global_load_lds_dwordx4 v195, s[34:35]
	s_mov_b32 m0, s10
	s_nop 0
	global_load_lds_dwordx4 v192, s[48:49]
	s_nop 0
	s_mov_b32 m0, s56
	s_nop 0
	global_load_lds_dwordx4 v194, s[48:49]
	s_waitcnt vmcnt(8)
	s_waitcnt lgkmcnt(0)
	s_barrier
	v_mfma_f32_16x16x32_bf16 v[62:65], v[132:135], v[164:167], v[62:65]
	v_mfma_f32_16x16x32_bf16 v[62:65], v[136:139], v[168:171], v[62:65]
	v_mfma_f32_16x16x32_bf16 v[58:61], v[140:143], v[164:167], v[58:61]
	v_mfma_f32_16x16x32_bf16 v[58:61], v[144:147], v[168:171], v[58:61]
	v_mfma_f32_16x16x32_bf16 v[46:49], v[132:135], v[172:175], v[46:49]
	v_mfma_f32_16x16x32_bf16 v[46:49], v[136:139], v[176:179], v[46:49]
	v_mfma_f32_16x16x32_bf16 v[42:45], v[140:143], v[172:175], v[42:45]
	v_mfma_f32_16x16x32_bf16 v[42:45], v[144:147], v[176:179], v[42:45]
	v_mfma_f32_16x16x32_bf16 v[30:33], v[132:135], v[180:183], v[30:33]
	v_mfma_f32_16x16x32_bf16 v[30:33], v[136:139], v[184:187], v[30:33]
	v_mfma_f32_16x16x32_bf16 v[26:29], v[140:143], v[180:183], v[26:29]
	v_mfma_f32_16x16x32_bf16 v[26:29], v[144:147], v[184:187], v[26:29]
	v_mfma_f32_16x16x32_bf16 v[14:17], v[132:135], v[202:205], v[14:17]
	v_mfma_f32_16x16x32_bf16 v[14:17], v[136:139], v[206:209], v[14:17]
	v_mfma_f32_16x16x32_bf16 v[10:13], v[140:143], v[202:205], v[10:13]
	v_mfma_f32_16x16x32_bf16 v[10:13], v[144:147], v[206:209], v[10:13]
	v_mfma_f32_16x16x32_bf16 v[54:57], v[148:151], v[164:167], v[54:57]
	v_mfma_f32_16x16x32_bf16 v[54:57], v[152:155], v[168:171], v[54:57]
	v_mfma_f32_16x16x32_bf16 v[50:53], v[156:159], v[164:167], v[50:53]
	v_mfma_f32_16x16x32_bf16 v[50:53], v[160:163], v[168:171], v[50:53]
	v_mfma_f32_16x16x32_bf16 v[38:41], v[148:151], v[172:175], v[38:41]
	v_mfma_f32_16x16x32_bf16 v[38:41], v[152:155], v[176:179], v[38:41]
	v_mfma_f32_16x16x32_bf16 v[34:37], v[156:159], v[172:175], v[34:37]
	v_mfma_f32_16x16x32_bf16 v[34:37], v[160:163], v[176:179], v[34:37]
	v_mfma_f32_16x16x32_bf16 v[22:25], v[148:151], v[180:183], v[22:25]
	v_mfma_f32_16x16x32_bf16 v[22:25], v[152:155], v[184:187], v[22:25]
	v_mfma_f32_16x16x32_bf16 v[18:21], v[156:159], v[180:183], v[18:21]
	v_mfma_f32_16x16x32_bf16 v[18:21], v[160:163], v[184:187], v[18:21]
	v_mfma_f32_16x16x32_bf16 v[6:9], v[148:151], v[202:205], v[6:9]
	v_mfma_f32_16x16x32_bf16 v[6:9], v[152:155], v[206:209], v[6:9]
	v_mfma_f32_16x16x32_bf16 v[2:5], v[156:159], v[202:205], v[2:5]
	v_mfma_f32_16x16x32_bf16 v[2:5], v[160:163], v[206:209], v[2:5]
	s_barrier
; #define PG8_LDA(dst, b, h) do { _Pragma("unroll") for (int m = 0; m < 4; ++m) _Pragma("unroll") for (int k = 0; k < 2; ++k) dst[m][k] = *(const PG8_LAS bf16x8*)(lds + PG8_SA(b, h) + aoff + m * 2048 + k * 1024); } while (0)
; #define PG8_LDB(dst, b, h) do { _Pragma("unroll") for (int n = 0; n < 2; ++n) _Pragma("unroll") for (int k = 0; k < 2; ++k) dst[n][k] = *(const PG8_LAS bf16x8*)(lds + PG8_SB(b, h) + boff + n * 2048 + k * 1024); } while (0)
; #define PG8_MMA(ai, bj, At, Bt) do { __builtin_amdgcn_s_setprio(1); _Pragma("unroll") for (int m = 0; m < 4; ++m) _Pragma("unroll") for (int n = 0; n < 2; ++n) _Pragma("unroll") for (int k = 0; k < 2; ++k) \
;         acc[ai][bj][m][n] = __builtin_amdgcn_mfma_f32_16x16x32_bf16(Bt[n][k], At[m][k], acc[ai][bj][m][n], 0, 0, 0); __builtin_amdgcn_s_setprio(0); } while (0)
; #define PG8_WAIT_V(n) asm volatile("s_waitcnt vmcnt(" #n ")" ::: "memory")
; #define PG8_WAIT_L(n) asm volatile("s_waitcnt lgkmcnt(" #n ")" ::: "memory")
; #define PG8_BAR __builtin_amdgcn_s_barrier()
; #define PG8_SCHED __builtin_amdgcn_sched_barrier(0)
; template <class Epi, class Sched, bool ALIGN_EPI = false, bool SP2 = false>
; __device__ __forceinline__ void gemm_phase(PG8_LAS unsigned char* lds, const Gemm g, const Sched& S, const Epi& E, const int tid) {
;     ...
;             PG8_LDB(B0, 1, 0); PG8_LDB(B1, 1, 1); PG8_SCHED; PG8_LDA(At, 1, 0); PG8_STAGE(PG8_SA(0, 1), a2 + hstepA, voffA);
;             PG8_WAIT_V(8); PG8_WAIT_L(0); PG8_BAR; PG8_MMA(0, 0, At, B0); PG8_MMA(0, 1, At, B1); PG8_BAR; PG8_SCHED;
;             PG8_LDA(At, 1, 1); PG8_STAGE(PG8_SB(1, 0), b3, voffB); PG8_STAGE(PG8_SB(1, 1), b3 + hstepB, voffB); PG8_STAGE(PG8_SA(1, 0), a3, voffA);
;             PG8_WAIT_V(8); PG8_WAIT_L(0); PG8_BAR; PG8_MMA(1, 0, At, B0); PG8_MMA(1, 1, At, B1); PG8_BAR; PG8_SCHED;
	v_add_u32_e32 v144, 0x18000, v200
	v_add_u32_e32 v160, 0x1c000, v200
	ds_read_b128 v[132:135], v144
	ds_read_b128 v[136:139], v144 offset:1024
	ds_read_b128 v[140:143], v144 offset:2048
	ds_read_b128 v[144:147], v144 offset:3072
	ds_read_b128 v[148:151], v160
	ds_read_b128 v[152:155], v160 offset:1024
	ds_read_b128 v[156:159], v160 offset:2048
	ds_read_b128 v[160:163], v160 offset:3072
	ds_read_b128 v[164:167], v201 offset:32768
	ds_read_b128 v[168:171], v201 offset:33792
	ds_read_b128 v[172:175], v201 offset:34816
	ds_read_b128 v[176:179], v201 offset:35840
	ds_read_b128 v[180:183], v201 offset:36864
	ds_read_b128 v[184:187], v201 offset:37888
	ds_read_b128 v[202:205], v201 offset:38912
	ds_read_b128 v[206:209], v201 offset:39936
	s_add_u32 s34, s48, 0x80000
	s_addc_u32 s35, s49, 0
	s_mov_b32 m0, s57
	s_nop 0
	global_load_lds_dwordx4 v192, s[34:35]
	s_nop 0
	s_mov_b32 m0, s64
	s_nop 0
	global_load_lds_dwordx4 v194, s[34:35]
	s_waitcnt vmcnt(8)
	s_waitcnt lgkmcnt(0)
	s_barrier
	v_mfma_f32_16x16x32_bf16 v[126:129], v[132:135], v[164:167], v[126:129]
	v_mfma_f32_16x16x32_bf16 v[126:129], v[136:139], v[168:171], v[126:129]
	v_mfma_f32_16x16x32_bf16 v[122:125], v[140:143], v[164:167], v[122:125]
	v_mfma_f32_16x16x32_bf16 v[122:125], v[144:147], v[168:171], v[122:125]
	v_mfma_f32_16x16x32_bf16 v[118:121], v[132:135], v[172:175], v[118:121]
	v_mfma_f32_16x16x32_bf16 v[118:121], v[136:139], v[176:179], v[118:121]
	v_mfma_f32_16x16x32_bf16 v[114:117], v[140:143], v[172:175], v[114:117]
	v_mfma_f32_16x16x32_bf16 v[114:117], v[144:147], v[176:179], v[114:117]
	v_mfma_f32_16x16x32_bf16 v[94:97], v[132:135], v[180:183], v[94:97]
	v_mfma_f32_16x16x32_bf16 v[94:97], v[136:139], v[184:187], v[94:97]
	v_mfma_f32_16x16x32_bf16 v[90:93], v[140:143], v[180:183], v[90:93]
	v_mfma_f32_16x16x32_bf16 v[90:93], v[144:147], v[184:187], v[90:93]
	v_mfma_f32_16x16x32_bf16 v[78:81], v[132:135], v[202:205], v[78:81]
	v_mfma_f32_16x16x32_bf16 v[78:81], v[136:139], v[206:209], v[78:81]
	v_mfma_f32_16x16x32_bf16 v[74:77], v[140:143], v[202:205], v[74:77]
	v_mfma_f32_16x16x32_bf16 v[74:77], v[144:147], v[206:209], v[74:77]
	v_mfma_f32_16x16x32_bf16 v[110:113], v[148:151], v[164:167], v[110:113]
	v_mfma_f32_16x16x32_bf16 v[110:113], v[152:155], v[168:171], v[110:113]
	v_mfma_f32_16x16x32_bf16 v[106:109], v[156:159], v[164:167], v[106:109]
	v_mfma_f32_16x16x32_bf16 v[106:109], v[160:163], v[168:171], v[106:109]
	v_mfma_f32_16x16x32_bf16 v[102:105], v[148:151], v[172:175], v[102:105]
	v_mfma_f32_16x16x32_bf16 v[102:105], v[152:155], v[176:179], v[102:105]
	v_mfma_f32_16x16x32_bf16 v[98:101], v[156:159], v[172:175], v[98:101]
	v_mfma_f32_16x16x32_bf16 v[98:101], v[160:163], v[176:179], v[98:101]
	v_mfma_f32_16x16x32_bf16 v[86:89], v[148:151], v[180:183], v[86:89]
	v_mfma_f32_16x16x32_bf16 v[86:89], v[152:155], v[184:187], v[86:89]
	v_mfma_f32_16x16x32_bf16 v[82:85], v[156:159], v[180:183], v[82:85]
	v_mfma_f32_16x16x32_bf16 v[82:85], v[160:163], v[184:187], v[82:85]
	v_mfma_f32_16x16x32_bf16 v[70:73], v[148:151], v[202:205], v[70:73]
	v_mfma_f32_16x16x32_bf16 v[70:73], v[152:155], v[206:209], v[70:73]
	v_mfma_f32_16x16x32_bf16 v[66:69], v[156:159], v[202:205], v[66:69]
	v_mfma_f32_16x16x32_bf16 v[66:69], v[160:163], v[206:209], v[66:69]
	s_barrier
	ds_read_b128 v[164:167], v201 offset:49152
	ds_read_b128 v[168:171], v201 offset:50176
	ds_read_b128 v[172:175], v201 offset:51200
	ds_read_b128 v[176:179], v201 offset:52224
	ds_read_b128 v[180:183], v201 offset:53248
	ds_read_b128 v[184:187], v201 offset:54272
	ds_read_b128 v[202:205], v201 offset:55296
	ds_read_b128 v[206:209], v201 offset:56320
	s_mov_b32 m0, s87
	s_nop 0
	global_load_lds_dwordx4 v193, s[46:47]
	s_nop 0
	s_mov_b32 m0, s89
	s_nop 0
	global_load_lds_dwordx4 v195, s[46:47]
	s_add_u32 s34, s40, 0x80080
	s_addc_u32 s35, s41, 0
	s_mov_b32 m0, s83
	s_nop 0
	global_load_lds_dwordx4 v193, s[34:35]
	s_nop 0
	s_mov_b32 m0, s95
	s_nop 0
	global_load_lds_dwordx4 v195, s[34:35]
	s_mov_b32 m0, s90
	s_nop 0
	global_load_lds_dwordx4 v192, s[44:45]
	s_nop 0
	s_mov_b32 m0, s91
	s_nop 0
	global_load_lds_dwordx4 v194, s[44:45]
	s_waitcnt vmcnt(8)
	s_waitcnt lgkmcnt(0)
	s_barrier
	v_mfma_f32_16x16x32_bf16 v[62:65], v[132:135], v[164:167], v[62:65]
	v_mfma_f32_16x16x32_bf16 v[62:65], v[136:139], v[168:171], v[62:65]
	v_mfma_f32_16x16x32_bf16 v[58:61], v[140:143], v[164:167], v[58:61]
	v_mfma_f32_16x16x32_bf16 v[58:61], v[144:147], v[168:171], v[58:61]
	v_mfma_f32_16x16x32_bf16 v[46:49], v[132:135], v[172:175], v[46:49]
	v_mfma_f32_16x16x32_bf16 v[46:49], v[136:139], v[176:179], v[46:49]
	v_mfma_f32_16x16x32_bf16 v[42:45], v[140:143], v[172:175], v[42:45]
	v_mfma_f32_16x16x32_bf16 v[42:45], v[144:147], v[176:179], v[42:45]
	v_mfma_f32_16x16x32_bf16 v[30:33], v[132:135], v[180:183], v[30:33]
	v_mfma_f32_16x16x32_bf16 v[30:33], v[136:139], v[184:187], v[30:33]
	v_mfma_f32_16x16x32_bf16 v[26:29], v[140:143], v[180:183], v[26:29]
	v_mfma_f32_16x16x32_bf16 v[26:29], v[144:147], v[184:187], v[26:29]
	v_mfma_f32_16x16x32_bf16 v[14:17], v[132:135], v[202:205], v[14:17]
	v_mfma_f32_16x16x32_bf16 v[14:17], v[136:139], v[206:209], v[14:17]
	v_mfma_f32_16x16x32_bf16 v[10:13], v[140:143], v[202:205], v[10:13]
	v_mfma_f32_16x16x32_bf16 v[10:13], v[144:147], v[206:209], v[10:13]
	v_mfma_f32_16x16x32_bf16 v[54:57], v[148:151], v[164:167], v[54:57]
	v_mfma_f32_16x16x32_bf16 v[54:57], v[152:155], v[168:171], v[54:57]
	v_mfma_f32_16x16x32_bf16 v[50:53], v[156:159], v[164:167], v[50:53]
	v_mfma_f32_16x16x32_bf16 v[50:53], v[160:163], v[168:171], v[50:53]
	v_mfma_f32_16x16x32_bf16 v[38:41], v[148:151], v[172:175], v[38:41]
	v_mfma_f32_16x16x32_bf16 v[38:41], v[152:155], v[176:179], v[38:41]
	v_mfma_f32_16x16x32_bf16 v[34:37], v[156:159], v[172:175], v[34:37]
	v_mfma_f32_16x16x32_bf16 v[34:37], v[160:163], v[176:179], v[34:37]
	v_mfma_f32_16x16x32_bf16 v[22:25], v[148:151], v[180:183], v[22:25]
	v_mfma_f32_16x16x32_bf16 v[22:25], v[152:155], v[184:187], v[22:25]
	v_mfma_f32_16x16x32_bf16 v[18:21], v[156:159], v[180:183], v[18:21]
	v_mfma_f32_16x16x32_bf16 v[18:21], v[160:163], v[184:187], v[18:21]
	v_mfma_f32_16x16x32_bf16 v[6:9], v[148:151], v[202:205], v[6:9]
	v_mfma_f32_16x16x32_bf16 v[6:9], v[152:155], v[206:209], v[6:9]
	v_mfma_f32_16x16x32_bf16 v[2:5], v[156:159], v[202:205], v[2:5]
	v_mfma_f32_16x16x32_bf16 v[2:5], v[160:163], v[206:209], v[2:5]
	s_barrier
	s_add_i32 s11, s11, 2
	s_add_u32 s59, s59, 0x100
	s_addc_u32 s67, s67, 0
	s_cmp_gt_u32 s11, 29
	s_mov_b64 s[34:35], s[42:43]
	s_cbranch_scc1 .LBB0_902

; #define PG8_LDA(dst, b, h) do { _Pragma("unroll") for (int m = 0; m < 4; ++m) _Pragma("unroll") for (int k = 0; k < 2; ++k) dst[m][k] = *(const PG8_LAS bf16x8*)(lds + PG8_SA(b, h) + aoff + m * 2048 + k * 1024); } while (0)
; #define PG8_LDB(dst, b, h) do { _Pragma("unroll") for (int n = 0; n < 2; ++n) _Pragma("unroll") for (int k = 0; k < 2; ++k) dst[n][k] = *(const PG8_LAS bf16x8*)(lds + PG8_SB(b, h) + boff + n * 2048 + k * 1024); } while (0)
; #define PG8_MMA(ai, bj, At, Bt) do { __builtin_amdgcn_s_setprio(1); _Pragma("unroll") for (int m = 0; m < 4; ++m) _Pragma("unroll") for (int n = 0; n < 2; ++n) _Pragma("unroll") for (int k = 0; k < 2; ++k) \
;         acc[ai][bj][m][n] = __builtin_amdgcn_mfma_f32_16x16x32_bf16(Bt[n][k], At[m][k], acc[ai][bj][m][n], 0, 0, 0); __builtin_amdgcn_s_setprio(0); } while (0)
; #define PG8_WAIT_V(n) asm volatile("s_waitcnt vmcnt(" #n ")" ::: "memory")
; #define PG8_WAIT_L(n) asm volatile("s_waitcnt lgkmcnt(" #n ")" ::: "memory")
; #define PG8_BAR __builtin_amdgcn_s_barrier()
; #define PG8_SCHED __builtin_amdgcn_sched_barrier(0)
; template <class Epi, class Sched, bool ALIGN_EPI = false, bool SP2 = false>
; __device__ __forceinline__ void gemm_phase(PG8_LAS unsigned char* lds, const Gemm g, const Sched& S, const Epi& E, const int tid) {
;     ...
;             const char* a1 = cA + (size_t)(t + 1) * kstepA;
;             const char* a2 = last ? nA : cA + (size_t)(t + 2) * kstepA; const char* b2 = last ? nB : cB + (size_t)(t + 2) * kstepB;
;             const char* a3 = a2 + kstepA; const char* b3 = b2 + kstepB;
;             if (last && has_next) S.a_ready(nxt);
;             if constexpr (SP2) {
;             PG8_LDB(B0, 0, 0); PG8_LDB(B1, 0, 1); PG8_SCHED; PG8_LDA(At, 0, 0); PG8_STAGE(PG8_SA(1, 1), a1 + hstepA, voffA);
;             PG8_WAIT_V(8); PG8_WAIT_L(0); PG8_BAR; PG8_MMA(0, 0, At, B0); PG8_MMA(0, 1, At, B1); PG8_BAR; PG8_SCHED;
;             PG8_LDA(At, 0, 1); PG8_STAGE(PG8_SB(0, 0), b2, voffB); PG8_STAGE(PG8_SB(0, 1), b2 + hstepB, voffB); PG8_STAGE(PG8_SA(0, 0), a2, voffA);
;             PG8_WAIT_V(8); PG8_WAIT_L(0); PG8_BAR; PG8_MMA(1, 0, At, B0); PG8_MMA(1, 1, At, B1); PG8_BAR; PG8_SCHED;
.LBB0_986:
	v_add_u32_e32 v142, 0x10000, v181
	v_add_u32_e32 v158, 0x14000, v181
	ds_read_b128 v[130:133], v142
	ds_read_b128 v[134:137], v142 offset:1024
	ds_read_b128 v[138:141], v142 offset:2048
	ds_read_b128 v[142:145], v142 offset:3072
	ds_read_b128 v[146:149], v158
	ds_read_b128 v[150:153], v158 offset:1024
	ds_read_b128 v[154:157], v158 offset:2048
	ds_read_b128 v[158:161], v158 offset:3072
	s_cmp_eq_u32 s83, 28
	s_cselect_b32 s38, s21, s67
	s_cselect_b32 s39, s11, s78
	s_cselect_b32 s34, s27, s58
	s_cselect_b32 s35, s19, s59
	s_add_u32 s30, s38, 0x80
	s_addc_u32 s31, s39, 0
	ds_read_b128 v[162:165], v182
	ds_read_b128 v[166:169], v182 offset:1024
	ds_read_b128 v[170:173], v182 offset:2048
	ds_read_b128 v[184:187], v182 offset:3072
	ds_read_b128 v[188:191], v182 offset:4096
	ds_read_b128 v[192:195], v182 offset:5120
	ds_read_b128 v[196:199], v182 offset:6144
	ds_read_b128 v[200:203], v182 offset:7168
	s_mov_b32 m0, s61
	s_nop 0
	global_load_lds_dwordx4 v0, s[28:29]
	s_nop 0
	s_mov_b32 m0, s65
	s_nop 0
	global_load_lds_dwordx4 v177, s[28:29]
	s_waitcnt vmcnt(8)
	s_waitcnt lgkmcnt(0)
	s_barrier
	v_mfma_f32_16x16x32_bf16 v[126:129], v[130:133], v[162:165], v[126:129]
	v_mfma_f32_16x16x32_bf16 v[126:129], v[134:137], v[166:169], v[126:129]
	v_mfma_f32_16x16x32_bf16 v[122:125], v[138:141], v[162:165], v[122:125]
	v_mfma_f32_16x16x32_bf16 v[122:125], v[142:145], v[166:169], v[122:125]
	v_mfma_f32_16x16x32_bf16 v[110:113], v[130:133], v[170:173], v[110:113]
	v_mfma_f32_16x16x32_bf16 v[110:113], v[134:137], v[184:187], v[110:113]
	v_mfma_f32_16x16x32_bf16 v[106:109], v[138:141], v[170:173], v[106:109]
	v_mfma_f32_16x16x32_bf16 v[106:109], v[142:145], v[184:187], v[106:109]
	v_mfma_f32_16x16x32_bf16 v[94:97], v[130:133], v[188:191], v[94:97]
	v_mfma_f32_16x16x32_bf16 v[94:97], v[134:137], v[192:195], v[94:97]
	v_mfma_f32_16x16x32_bf16 v[90:93], v[138:141], v[188:191], v[90:93]
	v_mfma_f32_16x16x32_bf16 v[90:93], v[142:145], v[192:195], v[90:93]
	v_mfma_f32_16x16x32_bf16 v[78:81], v[130:133], v[196:199], v[78:81]
	v_mfma_f32_16x16x32_bf16 v[78:81], v[134:137], v[200:203], v[78:81]
	v_mfma_f32_16x16x32_bf16 v[74:77], v[138:141], v[196:199], v[74:77]
	v_mfma_f32_16x16x32_bf16 v[74:77], v[142:145], v[200:203], v[74:77]
	v_mfma_f32_16x16x32_bf16 v[118:121], v[146:149], v[162:165], v[118:121]
	v_mfma_f32_16x16x32_bf16 v[118:121], v[150:153], v[166:169], v[118:121]
	v_mfma_f32_16x16x32_bf16 v[114:117], v[154:157], v[162:165], v[114:117]
	v_mfma_f32_16x16x32_bf16 v[114:117], v[158:161], v[166:169], v[114:117]
	v_mfma_f32_16x16x32_bf16 v[102:105], v[146:149], v[170:173], v[102:105]
	v_mfma_f32_16x16x32_bf16 v[102:105], v[150:153], v[184:187], v[102:105]
	v_mfma_f32_16x16x32_bf16 v[98:101], v[154:157], v[170:173], v[98:101]
	v_mfma_f32_16x16x32_bf16 v[98:101], v[158:161], v[184:187], v[98:101]
	v_mfma_f32_16x16x32_bf16 v[86:89], v[146:149], v[188:191], v[86:89]
	v_mfma_f32_16x16x32_bf16 v[86:89], v[150:153], v[192:195], v[86:89]
	v_mfma_f32_16x16x32_bf16 v[82:85], v[154:157], v[188:191], v[82:85]
	v_mfma_f32_16x16x32_bf16 v[82:85], v[158:161], v[192:195], v[82:85]
	v_mfma_f32_16x16x32_bf16 v[70:73], v[146:149], v[196:199], v[70:73]
	v_mfma_f32_16x16x32_bf16 v[70:73], v[150:153], v[200:203], v[70:73]
	v_mfma_f32_16x16x32_bf16 v[66:69], v[154:157], v[196:199], v[66:69]
	v_mfma_f32_16x16x32_bf16 v[66:69], v[158:161], v[200:203], v[66:69]
	s_barrier
	ds_read_b128 v[162:165], v182 offset:16384
	ds_read_b128 v[166:169], v182 offset:17408
	ds_read_b128 v[170:173], v182 offset:18432
	ds_read_b128 v[184:187], v182 offset:19456
	ds_read_b128 v[188:191], v182 offset:20480
	ds_read_b128 v[192:195], v182 offset:21504
	ds_read_b128 v[196:199], v182 offset:22528
	ds_read_b128 v[200:203], v182 offset:23552
	s_mov_b32 m0, s7
	s_nop 0
	global_load_lds_dwordx4 v176, s[34:35]
	s_add_u32 s90, s34, 0x80000
	s_mov_b32 m0, s43
	s_nop 0
	global_load_lds_dwordx4 v178, s[34:35]
	s_addc_u32 s91, s35, 0
	s_mov_b32 m0, s44
	s_nop 0
	global_load_lds_dwordx4 v176, s[90:91]
	s_nop 0
	s_mov_b32 m0, s45
	s_nop 0
	global_load_lds_dwordx4 v178, s[90:91]
	s_nop 0
	s_mov_b32 m0, s10
	s_nop 0
	global_load_lds_dwordx4 v0, s[38:39]
	s_nop 0
	s_mov_b32 m0, s46
	s_nop 0
	global_load_lds_dwordx4 v177, s[38:39]
	s_waitcnt vmcnt(8)
	s_waitcnt lgkmcnt(0)
	s_barrier
	v_mfma_f32_16x16x32_bf16 v[62:65], v[130:133], v[162:165], v[62:65]
	v_mfma_f32_16x16x32_bf16 v[62:65], v[134:137], v[166:169], v[62:65]
	v_mfma_f32_16x16x32_bf16 v[58:61], v[138:141], v[162:165], v[58:61]
	v_mfma_f32_16x16x32_bf16 v[58:61], v[142:145], v[166:169], v[58:61]
	v_mfma_f32_16x16x32_bf16 v[46:49], v[130:133], v[170:173], v[46:49]
	v_mfma_f32_16x16x32_bf16 v[46:49], v[134:137], v[184:187], v[46:49]
	v_mfma_f32_16x16x32_bf16 v[42:45], v[138:141], v[170:173], v[42:45]
	v_mfma_f32_16x16x32_bf16 v[42:45], v[142:145], v[184:187], v[42:45]
	v_mfma_f32_16x16x32_bf16 v[30:33], v[130:133], v[188:191], v[30:33]
	v_mfma_f32_16x16x32_bf16 v[30:33], v[134:137], v[192:195], v[30:33]
	v_mfma_f32_16x16x32_bf16 v[26:29], v[138:141], v[188:191], v[26:29]
	v_mfma_f32_16x16x32_bf16 v[26:29], v[142:145], v[192:195], v[26:29]
	v_mfma_f32_16x16x32_bf16 v[14:17], v[130:133], v[196:199], v[14:17]
	v_mfma_f32_16x16x32_bf16 v[14:17], v[134:137], v[200:203], v[14:17]
	v_mfma_f32_16x16x32_bf16 v[10:13], v[138:141], v[196:199], v[10:13]
	v_mfma_f32_16x16x32_bf16 v[10:13], v[142:145], v[200:203], v[10:13]
	v_mfma_f32_16x16x32_bf16 v[54:57], v[146:149], v[162:165], v[54:57]
	v_mfma_f32_16x16x32_bf16 v[54:57], v[150:153], v[166:169], v[54:57]
	v_mfma_f32_16x16x32_bf16 v[50:53], v[154:157], v[162:165], v[50:53]
	v_mfma_f32_16x16x32_bf16 v[50:53], v[158:161], v[166:169], v[50:53]
	v_mfma_f32_16x16x32_bf16 v[38:41], v[146:149], v[170:173], v[38:41]
	v_mfma_f32_16x16x32_bf16 v[38:41], v[150:153], v[184:187], v[38:41]
	v_mfma_f32_16x16x32_bf16 v[34:37], v[154:157], v[170:173], v[34:37]
	v_mfma_f32_16x16x32_bf16 v[34:37], v[158:161], v[184:187], v[34:37]
	v_mfma_f32_16x16x32_bf16 v[22:25], v[146:149], v[188:191], v[22:25]
	v_mfma_f32_16x16x32_bf16 v[22:25], v[150:153], v[192:195], v[22:25]
	v_mfma_f32_16x16x32_bf16 v[18:21], v[154:157], v[188:191], v[18:21]
	v_mfma_f32_16x16x32_bf16 v[18:21], v[158:161], v[192:195], v[18:21]
	v_mfma_f32_16x16x32_bf16 v[6:9], v[146:149], v[196:199], v[6:9]
	v_mfma_f32_16x16x32_bf16 v[6:9], v[150:153], v[200:203], v[6:9]
	v_mfma_f32_16x16x32_bf16 v[2:5], v[154:157], v[196:199], v[2:5]
	v_mfma_f32_16x16x32_bf16 v[2:5], v[158:161], v[200:203], v[2:5]
	s_barrier
; #define PG8_LDA(dst, b, h) do { _Pragma("unroll") for (int m = 0; m < 4; ++m) _Pragma("unroll") for (int k = 0; k < 2; ++k) dst[m][k] = *(const PG8_LAS bf16x8*)(lds + PG8_SA(b, h) + aoff + m * 2048 + k * 1024); } while (0)
; #define PG8_LDB(dst, b, h) do { _Pragma("unroll") for (int n = 0; n < 2; ++n) _Pragma("unroll") for (int k = 0; k < 2; ++k) dst[n][k] = *(const PG8_LAS bf16x8*)(lds + PG8_SB(b, h) + boff + n * 2048 + k * 1024); } while (0)
; #define PG8_MMA(ai, bj, At, Bt) do { __builtin_amdgcn_s_setprio(1); _Pragma("unroll") for (int m = 0; m < 4; ++m) _Pragma("unroll") for (int n = 0; n < 2; ++n) _Pragma("unroll") for (int k = 0; k < 2; ++k) \
;         acc[ai][bj][m][n] = __builtin_amdgcn_mfma_f32_16x16x32_bf16(Bt[n][k], At[m][k], acc[ai][bj][m][n], 0, 0, 0); __builtin_amdgcn_s_setprio(0); } while (0)
; #define PG8_WAIT_V(n) asm volatile("s_waitcnt vmcnt(" #n ")" ::: "memory")
; #define PG8_WAIT_L(n) asm volatile("s_waitcnt lgkmcnt(" #n ")" ::: "memory")
; #define PG8_BAR __builtin_amdgcn_s_barrier()
; #define PG8_SCHED __builtin_amdgcn_sched_barrier(0)
; template <class Epi, class Sched, bool ALIGN_EPI = false, bool SP2 = false>
; __device__ __forceinline__ void gemm_phase(PG8_LAS unsigned char* lds, const Gemm g, const Sched& S, const Epi& E, const int tid) {
;     ...
;             PG8_LDB(B0, 1, 0); PG8_LDB(B1, 1, 1); PG8_SCHED; PG8_LDA(At, 1, 0); PG8_STAGE(PG8_SA(0, 1), a2 + hstepA, voffA);
;             PG8_WAIT_V(8); PG8_WAIT_L(0); PG8_BAR; PG8_MMA(0, 0, At, B0); PG8_MMA(0, 1, At, B1); PG8_BAR; PG8_SCHED;
;             PG8_LDA(At, 1, 1); PG8_STAGE(PG8_SB(1, 0), b3, voffB); PG8_STAGE(PG8_SB(1, 1), b3 + hstepB, voffB); PG8_STAGE(PG8_SA(1, 0), a3, voffA);
;             PG8_WAIT_V(8); PG8_WAIT_L(0); PG8_BAR; PG8_MMA(1, 0, At, B0); PG8_MMA(1, 1, At, B1); PG8_BAR; PG8_SCHED;
	v_add_u32_e32 v142, 0x18000, v181
	v_add_u32_e32 v158, 0x1c000, v181
	ds_read_b128 v[130:133], v142
	ds_read_b128 v[134:137], v142 offset:1024
	ds_read_b128 v[138:141], v142 offset:2048
	ds_read_b128 v[142:145], v142 offset:3072
	ds_read_b128 v[146:149], v158
	ds_read_b128 v[150:153], v158 offset:1024
	ds_read_b128 v[154:157], v158 offset:2048
	ds_read_b128 v[158:161], v158 offset:3072
	ds_read_b128 v[162:165], v182 offset:32768
	ds_read_b128 v[166:169], v182 offset:33792
	ds_read_b128 v[170:173], v182 offset:34816
	ds_read_b128 v[184:187], v182 offset:35840
	ds_read_b128 v[188:191], v182 offset:36864
	ds_read_b128 v[192:195], v182 offset:37888
	ds_read_b128 v[196:199], v182 offset:38912
	ds_read_b128 v[200:203], v182 offset:39936
	s_add_u32 s38, s38, 0x80000
	s_addc_u32 s39, s39, 0
	s_mov_b32 m0, s47
	s_nop 0
	global_load_lds_dwordx4 v0, s[38:39]
	s_nop 0
	s_mov_b32 m0, s48
	s_nop 0
	global_load_lds_dwordx4 v177, s[38:39]
	s_waitcnt vmcnt(8)
	s_waitcnt lgkmcnt(0)
	s_barrier
	v_mfma_f32_16x16x32_bf16 v[126:129], v[130:133], v[162:165], v[126:129]
	v_mfma_f32_16x16x32_bf16 v[126:129], v[134:137], v[166:169], v[126:129]
	v_mfma_f32_16x16x32_bf16 v[122:125], v[138:141], v[162:165], v[122:125]
	v_mfma_f32_16x16x32_bf16 v[122:125], v[142:145], v[166:169], v[122:125]
	v_mfma_f32_16x16x32_bf16 v[110:113], v[130:133], v[170:173], v[110:113]
	v_mfma_f32_16x16x32_bf16 v[110:113], v[134:137], v[184:187], v[110:113]
	v_mfma_f32_16x16x32_bf16 v[106:109], v[138:141], v[170:173], v[106:109]
	v_mfma_f32_16x16x32_bf16 v[106:109], v[142:145], v[184:187], v[106:109]
	v_mfma_f32_16x16x32_bf16 v[94:97], v[130:133], v[188:191], v[94:97]
	v_mfma_f32_16x16x32_bf16 v[94:97], v[134:137], v[192:195], v[94:97]
	v_mfma_f32_16x16x32_bf16 v[90:93], v[138:141], v[188:191], v[90:93]
	v_mfma_f32_16x16x32_bf16 v[90:93], v[142:145], v[192:195], v[90:93]
	v_mfma_f32_16x16x32_bf16 v[78:81], v[130:133], v[196:199], v[78:81]
	v_mfma_f32_16x16x32_bf16 v[78:81], v[134:137], v[200:203], v[78:81]
	v_mfma_f32_16x16x32_bf16 v[74:77], v[138:141], v[196:199], v[74:77]
	v_mfma_f32_16x16x32_bf16 v[74:77], v[142:145], v[200:203], v[74:77]
	v_mfma_f32_16x16x32_bf16 v[118:121], v[146:149], v[162:165], v[118:121]
	v_mfma_f32_16x16x32_bf16 v[118:121], v[150:153], v[166:169], v[118:121]
	v_mfma_f32_16x16x32_bf16 v[114:117], v[154:157], v[162:165], v[114:117]
	v_mfma_f32_16x16x32_bf16 v[114:117], v[158:161], v[166:169], v[114:117]
	v_mfma_f32_16x16x32_bf16 v[102:105], v[146:149], v[170:173], v[102:105]
	v_mfma_f32_16x16x32_bf16 v[102:105], v[150:153], v[184:187], v[102:105]
	v_mfma_f32_16x16x32_bf16 v[98:101], v[154:157], v[170:173], v[98:101]
	v_mfma_f32_16x16x32_bf16 v[98:101], v[158:161], v[184:187], v[98:101]
	v_mfma_f32_16x16x32_bf16 v[86:89], v[146:149], v[188:191], v[86:89]
	v_mfma_f32_16x16x32_bf16 v[86:89], v[150:153], v[192:195], v[86:89]
	v_mfma_f32_16x16x32_bf16 v[82:85], v[154:157], v[188:191], v[82:85]
	v_mfma_f32_16x16x32_bf16 v[82:85], v[158:161], v[192:195], v[82:85]
	v_mfma_f32_16x16x32_bf16 v[70:73], v[146:149], v[196:199], v[70:73]
	v_mfma_f32_16x16x32_bf16 v[70:73], v[150:153], v[200:203], v[70:73]
	v_mfma_f32_16x16x32_bf16 v[66:69], v[154:157], v[196:199], v[66:69]
	v_mfma_f32_16x16x32_bf16 v[66:69], v[158:161], v[200:203], v[66:69]
	s_barrier
	ds_read_b128 v[162:165], v182 offset:49152
	ds_read_b128 v[166:169], v182 offset:50176
	ds_read_b128 v[170:173], v182 offset:51200
	ds_read_b128 v[184:187], v182 offset:52224
	ds_read_b128 v[188:191], v182 offset:53248
	ds_read_b128 v[192:195], v182 offset:54272
	ds_read_b128 v[196:199], v182 offset:55296
	ds_read_b128 v[200:203], v182 offset:56320
	s_add_u32 s38, s34, 0x80
	s_addc_u32 s39, s35, 0
	s_mov_b32 m0, s50
	s_nop 0
	global_load_lds_dwordx4 v176, s[38:39]
	s_add_u32 s34, s34, 0x80080
	s_mov_b32 m0, s51
	s_nop 0
	global_load_lds_dwordx4 v178, s[38:39]
	s_addc_u32 s35, s35, 0
	s_mov_b32 m0, s56
	s_nop 0
	global_load_lds_dwordx4 v176, s[34:35]
	s_nop 0
	s_mov_b32 m0, s57
	s_nop 0
	global_load_lds_dwordx4 v178, s[34:35]
	s_mov_b32 m0, s54
	s_nop 0
	global_load_lds_dwordx4 v0, s[30:31]
	s_nop 0
	s_mov_b32 m0, s55
	s_nop 0
	global_load_lds_dwordx4 v177, s[30:31]
	s_waitcnt vmcnt(8)
	s_waitcnt lgkmcnt(0)
	s_barrier
	v_mfma_f32_16x16x32_bf16 v[62:65], v[130:133], v[162:165], v[62:65]
	v_mfma_f32_16x16x32_bf16 v[62:65], v[134:137], v[166:169], v[62:65]
	v_mfma_f32_16x16x32_bf16 v[58:61], v[138:141], v[162:165], v[58:61]
	v_mfma_f32_16x16x32_bf16 v[58:61], v[142:145], v[166:169], v[58:61]
	v_mfma_f32_16x16x32_bf16 v[46:49], v[130:133], v[170:173], v[46:49]
	v_mfma_f32_16x16x32_bf16 v[46:49], v[134:137], v[184:187], v[46:49]
	v_mfma_f32_16x16x32_bf16 v[42:45], v[138:141], v[170:173], v[42:45]
	v_mfma_f32_16x16x32_bf16 v[42:45], v[142:145], v[184:187], v[42:45]
	v_mfma_f32_16x16x32_bf16 v[30:33], v[130:133], v[188:191], v[30:33]
	v_mfma_f32_16x16x32_bf16 v[30:33], v[134:137], v[192:195], v[30:33]
	v_mfma_f32_16x16x32_bf16 v[26:29], v[138:141], v[188:191], v[26:29]
	v_mfma_f32_16x16x32_bf16 v[26:29], v[142:145], v[192:195], v[26:29]
	v_mfma_f32_16x16x32_bf16 v[14:17], v[130:133], v[196:199], v[14:17]
	v_mfma_f32_16x16x32_bf16 v[14:17], v[134:137], v[200:203], v[14:17]
	v_mfma_f32_16x16x32_bf16 v[10:13], v[138:141], v[196:199], v[10:13]
	v_mfma_f32_16x16x32_bf16 v[10:13], v[142:145], v[200:203], v[10:13]
	v_mfma_f32_16x16x32_bf16 v[54:57], v[146:149], v[162:165], v[54:57]
	v_mfma_f32_16x16x32_bf16 v[54:57], v[150:153], v[166:169], v[54:57]
	v_mfma_f32_16x16x32_bf16 v[50:53], v[154:157], v[162:165], v[50:53]
	v_mfma_f32_16x16x32_bf16 v[50:53], v[158:161], v[166:169], v[50:53]
	v_mfma_f32_16x16x32_bf16 v[38:41], v[146:149], v[170:173], v[38:41]
	v_mfma_f32_16x16x32_bf16 v[38:41], v[150:153], v[184:187], v[38:41]
	v_mfma_f32_16x16x32_bf16 v[34:37], v[154:157], v[170:173], v[34:37]
	v_mfma_f32_16x16x32_bf16 v[34:37], v[158:161], v[184:187], v[34:37]
	v_mfma_f32_16x16x32_bf16 v[22:25], v[146:149], v[188:191], v[22:25]
	v_mfma_f32_16x16x32_bf16 v[22:25], v[150:153], v[192:195], v[22:25]
	v_mfma_f32_16x16x32_bf16 v[18:21], v[154:157], v[188:191], v[18:21]
	v_mfma_f32_16x16x32_bf16 v[18:21], v[158:161], v[192:195], v[18:21]
	v_mfma_f32_16x16x32_bf16 v[6:9], v[146:149], v[196:199], v[6:9]
	v_mfma_f32_16x16x32_bf16 v[6:9], v[150:153], v[200:203], v[6:9]
	v_mfma_f32_16x16x32_bf16 v[2:5], v[154:157], v[196:199], v[2:5]
	v_mfma_f32_16x16x32_bf16 v[2:5], v[158:161], v[200:203], v[2:5]
	s_barrier
	s_add_i32 s83, s83, 2
	s_add_u32 s58, s58, 0x100
	s_addc_u32 s59, s59, 0
	s_add_u32 s67, s67, 0x100
	s_addc_u32 s78, s78, 0
	s_add_u32 s28, s28, 0x100
	s_addc_u32 s29, s29, 0
	s_cmp_gt_u32 s83, 29
	s_cbranch_scc0 .LBB0_986
	s_and_b64 vcc, exec, s[16:17]
	s_cbranch_vccz .LBB0_989
	s_barrier

; #define PG8_LDA(dst, b, h) do { _Pragma("unroll") for (int m = 0; m < 4; ++m) _Pragma("unroll") for (int k = 0; k < 2; ++k) dst[m][k] = *(const PG8_LAS bf16x8*)(lds + PG8_SA(b, h) + aoff + m * 2048 + k * 1024); } while (0)
; #define PG8_LDB(dst, b, h) do { _Pragma("unroll") for (int n = 0; n < 2; ++n) _Pragma("unroll") for (int k = 0; k < 2; ++k) dst[n][k] = *(const PG8_LAS bf16x8*)(lds + PG8_SB(b, h) + boff + n * 2048 + k * 1024); } while (0)
; #define PG8_MMA(ai, bj, At, Bt) do { __builtin_amdgcn_s_setprio(1); _Pragma("unroll") for (int m = 0; m < 4; ++m) _Pragma("unroll") for (int n = 0; n < 2; ++n) _Pragma("unroll") for (int k = 0; k < 2; ++k) \
;         acc[ai][bj][m][n] = __builtin_amdgcn_mfma_f32_16x16x32_bf16(Bt[n][k], At[m][k], acc[ai][bj][m][n], 0, 0, 0); __builtin_amdgcn_s_setprio(0); } while (0)
; #define PG8_WAIT_V(n) asm volatile("s_waitcnt vmcnt(" #n ")" ::: "memory")
; #define PG8_WAIT_L(n) asm volatile("s_waitcnt lgkmcnt(" #n ")" ::: "memory")
; #define PG8_BAR __builtin_amdgcn_s_barrier()
; #define PG8_SCHED __builtin_amdgcn_sched_barrier(0)
; template <class Epi, class Sched, bool ALIGN_EPI = false, bool SP2 = false>
; __device__ __forceinline__ void gemm_phase(PG8_LAS unsigned char* lds, const Gemm g, const Sched& S, const Epi& E, const int tid) {
;     ...
;             const char* a1 = cA + (size_t)(t + 1) * kstepA;
;             const char* a2 = last ? nA : cA + (size_t)(t + 2) * kstepA; const char* b2 = last ? nB : cB + (size_t)(t + 2) * kstepB;
;             const char* a3 = a2 + kstepA; const char* b3 = b2 + kstepB;
;             if (last && has_next) S.a_ready(nxt);
;             if constexpr (SP2) {
;             PG8_LDB(B0, 0, 0); PG8_LDB(B1, 0, 1); PG8_SCHED; PG8_LDA(At, 0, 0); PG8_STAGE(PG8_SA(1, 1), a1 + hstepA, voffA);
;             PG8_WAIT_V(8); PG8_WAIT_L(0); PG8_BAR; PG8_MMA(0, 0, At, B0); PG8_MMA(0, 1, At, B1); PG8_BAR; PG8_SCHED;
;             PG8_LDA(At, 0, 1); PG8_STAGE(PG8_SB(0, 0), b2, voffB); PG8_STAGE(PG8_SB(0, 1), b2 + hstepB, voffB); PG8_STAGE(PG8_SA(0, 0), a2, voffA);
;             PG8_WAIT_V(8); PG8_WAIT_L(0); PG8_BAR; PG8_MMA(1, 0, At, B0); PG8_MMA(1, 1, At, B1); PG8_BAR; PG8_SCHED;
.LBB0_1070:
	s_or_b64 exec, exec, s[34:35]
	v_add_u32_e32 v145, 0x10000, v154
	ds_read_b128 v[156:159], v145
	ds_read_b128 v[160:163], v145 offset:1024
	ds_read_b128 v[164:167], v145 offset:2048
	ds_read_b128 v[168:171], v145 offset:3072
	v_add_u32_e32 v145, 0x14000, v154
	s_add_u32 s34, s26, 0x100
	ds_read_b128 v[172:175], v145
	ds_read_b128 v[176:179], v145 offset:1024
	ds_read_b128 v[180:183], v145 offset:2048
	ds_read_b128 v[184:187], v145 offset:3072
	s_addc_u32 s35, s27, 0
	s_and_b64 s[30:31], s[30:31], exec
	s_cselect_b32 s42, s91, s34
	s_cselect_b32 s43, s19, s35
	s_cselect_b32 s31, s17, s67
	s_cselect_b32 s30, s95, s59
	s_add_u32 s38, s42, 0x80
	s_addc_u32 s39, s43, 0
	s_add_u32 s40, s30, 0x80
	s_addc_u32 s41, s31, 0
	ds_read_b128 v[188:191], v155
	ds_read_b128 v[192:195], v155 offset:1024
	ds_read_b128 v[196:199], v155 offset:2048
	ds_read_b128 v[200:203], v155 offset:3072
	ds_read_b128 v[204:207], v155 offset:4096
	ds_read_b128 v[208:211], v155 offset:5120
	ds_read_b128 v[212:215], v155 offset:6144
	ds_read_b128 v[216:219], v155 offset:7168
	s_add_u32 s26, s26, 0x80080
	s_addc_u32 s27, s27, 0
	s_mov_b32 m0, s69
	s_nop 0
	global_load_lds_dwordx4 v149, s[26:27]
	s_nop 0
	s_mov_b32 m0, s58
	s_nop 0
	global_load_lds_dwordx4 v151, s[26:27]
	s_waitcnt vmcnt(8)
	s_waitcnt lgkmcnt(0)
	s_barrier
	v_mfma_f32_16x16x32_bf16 v[126:129], v[156:159], v[188:191], v[126:129]
	v_mfma_f32_16x16x32_bf16 v[126:129], v[160:163], v[192:195], v[126:129]
	v_mfma_f32_16x16x32_bf16 v[122:125], v[164:167], v[188:191], v[122:125]
	v_mfma_f32_16x16x32_bf16 v[122:125], v[168:171], v[192:195], v[122:125]
	v_mfma_f32_16x16x32_bf16 v[110:113], v[156:159], v[196:199], v[110:113]
	v_mfma_f32_16x16x32_bf16 v[110:113], v[160:163], v[200:203], v[110:113]
	v_mfma_f32_16x16x32_bf16 v[106:109], v[164:167], v[196:199], v[106:109]
	v_mfma_f32_16x16x32_bf16 v[106:109], v[168:171], v[200:203], v[106:109]
	v_mfma_f32_16x16x32_bf16 v[94:97], v[156:159], v[204:207], v[94:97]
	v_mfma_f32_16x16x32_bf16 v[94:97], v[160:163], v[208:211], v[94:97]
	v_mfma_f32_16x16x32_bf16 v[90:93], v[164:167], v[204:207], v[90:93]
	v_mfma_f32_16x16x32_bf16 v[90:93], v[168:171], v[208:211], v[90:93]
	v_mfma_f32_16x16x32_bf16 v[78:81], v[156:159], v[212:215], v[78:81]
	v_mfma_f32_16x16x32_bf16 v[78:81], v[160:163], v[216:219], v[78:81]
	v_mfma_f32_16x16x32_bf16 v[74:77], v[164:167], v[212:215], v[74:77]
	v_mfma_f32_16x16x32_bf16 v[74:77], v[168:171], v[216:219], v[74:77]
	v_mfma_f32_16x16x32_bf16 v[118:121], v[172:175], v[188:191], v[118:121]
	v_mfma_f32_16x16x32_bf16 v[118:121], v[176:179], v[192:195], v[118:121]
	v_mfma_f32_16x16x32_bf16 v[114:117], v[180:183], v[188:191], v[114:117]
	v_mfma_f32_16x16x32_bf16 v[114:117], v[184:187], v[192:195], v[114:117]
	v_mfma_f32_16x16x32_bf16 v[102:105], v[172:175], v[196:199], v[102:105]
	v_mfma_f32_16x16x32_bf16 v[102:105], v[176:179], v[200:203], v[102:105]
	v_mfma_f32_16x16x32_bf16 v[98:101], v[180:183], v[196:199], v[98:101]
	v_mfma_f32_16x16x32_bf16 v[98:101], v[184:187], v[200:203], v[98:101]
	v_mfma_f32_16x16x32_bf16 v[86:89], v[172:175], v[204:207], v[86:89]
	v_mfma_f32_16x16x32_bf16 v[86:89], v[176:179], v[208:211], v[86:89]
	v_mfma_f32_16x16x32_bf16 v[82:85], v[180:183], v[204:207], v[82:85]
	v_mfma_f32_16x16x32_bf16 v[82:85], v[184:187], v[208:211], v[82:85]
	v_mfma_f32_16x16x32_bf16 v[70:73], v[172:175], v[212:215], v[70:73]
	v_mfma_f32_16x16x32_bf16 v[70:73], v[176:179], v[216:219], v[70:73]
	v_mfma_f32_16x16x32_bf16 v[66:69], v[180:183], v[212:215], v[66:69]
	v_mfma_f32_16x16x32_bf16 v[66:69], v[184:187], v[216:219], v[66:69]
	s_barrier
	ds_read_b128 v[188:191], v155 offset:16384
	ds_read_b128 v[192:195], v155 offset:17408
	ds_read_b128 v[196:199], v155 offset:18432
	ds_read_b128 v[200:203], v155 offset:19456
	ds_read_b128 v[204:207], v155 offset:20480
	ds_read_b128 v[208:211], v155 offset:21504
	ds_read_b128 v[212:215], v155 offset:22528
	ds_read_b128 v[216:219], v155 offset:23552
	s_mov_b32 m0, s15
	s_nop 0
	global_load_lds_dwordx4 v150, s[30:31]
	s_nop 0
	s_mov_b32 m0, s25
	s_nop 0
	global_load_lds_dwordx4 v152, s[30:31]
	s_add_u32 s26, s30, 0x80000
	s_addc_u32 s27, s31, 0
	s_mov_b32 m0, s48
	s_nop 0
	global_load_lds_dwordx4 v150, s[26:27]
	s_nop 0
	s_mov_b32 m0, s49
	s_nop 0
	global_load_lds_dwordx4 v152, s[26:27]
	s_mov_b32 m0, s10
	s_nop 0
	global_load_lds_dwordx4 v149, s[42:43]
	s_nop 0
	s_mov_b32 m0, s50
	s_nop 0
	global_load_lds_dwordx4 v151, s[42:43]
	s_waitcnt vmcnt(8)
	s_waitcnt lgkmcnt(0)
	s_barrier
	v_mfma_f32_16x16x32_bf16 v[62:65], v[156:159], v[188:191], v[62:65]
	v_mfma_f32_16x16x32_bf16 v[62:65], v[160:163], v[192:195], v[62:65]
	v_mfma_f32_16x16x32_bf16 v[58:61], v[164:167], v[188:191], v[58:61]
	v_mfma_f32_16x16x32_bf16 v[58:61], v[168:171], v[192:195], v[58:61]
	v_mfma_f32_16x16x32_bf16 v[46:49], v[156:159], v[196:199], v[46:49]
	v_mfma_f32_16x16x32_bf16 v[46:49], v[160:163], v[200:203], v[46:49]
	v_mfma_f32_16x16x32_bf16 v[42:45], v[164:167], v[196:199], v[42:45]
	v_mfma_f32_16x16x32_bf16 v[42:45], v[168:171], v[200:203], v[42:45]
	v_mfma_f32_16x16x32_bf16 v[30:33], v[156:159], v[204:207], v[30:33]
	v_mfma_f32_16x16x32_bf16 v[30:33], v[160:163], v[208:211], v[30:33]
	v_mfma_f32_16x16x32_bf16 v[26:29], v[164:167], v[204:207], v[26:29]
	v_mfma_f32_16x16x32_bf16 v[26:29], v[168:171], v[208:211], v[26:29]
	v_mfma_f32_16x16x32_bf16 v[14:17], v[156:159], v[212:215], v[14:17]
	v_mfma_f32_16x16x32_bf16 v[14:17], v[160:163], v[216:219], v[14:17]
	v_mfma_f32_16x16x32_bf16 v[10:13], v[164:167], v[212:215], v[10:13]
	v_mfma_f32_16x16x32_bf16 v[10:13], v[168:171], v[216:219], v[10:13]
	v_mfma_f32_16x16x32_bf16 v[54:57], v[172:175], v[188:191], v[54:57]
	v_mfma_f32_16x16x32_bf16 v[54:57], v[176:179], v[192:195], v[54:57]
	v_mfma_f32_16x16x32_bf16 v[50:53], v[180:183], v[188:191], v[50:53]
	v_mfma_f32_16x16x32_bf16 v[50:53], v[184:187], v[192:195], v[50:53]
	v_mfma_f32_16x16x32_bf16 v[38:41], v[172:175], v[196:199], v[38:41]
	v_mfma_f32_16x16x32_bf16 v[38:41], v[176:179], v[200:203], v[38:41]
	v_mfma_f32_16x16x32_bf16 v[34:37], v[180:183], v[196:199], v[34:37]
	v_mfma_f32_16x16x32_bf16 v[34:37], v[184:187], v[200:203], v[34:37]
	v_mfma_f32_16x16x32_bf16 v[22:25], v[172:175], v[204:207], v[22:25]
	v_mfma_f32_16x16x32_bf16 v[22:25], v[176:179], v[208:211], v[22:25]
	v_mfma_f32_16x16x32_bf16 v[18:21], v[180:183], v[204:207], v[18:21]
	v_mfma_f32_16x16x32_bf16 v[18:21], v[184:187], v[208:211], v[18:21]
	v_mfma_f32_16x16x32_bf16 v[6:9], v[172:175], v[212:215], v[6:9]
	v_mfma_f32_16x16x32_bf16 v[6:9], v[176:179], v[216:219], v[6:9]
	v_mfma_f32_16x16x32_bf16 v[2:5], v[180:183], v[212:215], v[2:5]
	v_mfma_f32_16x16x32_bf16 v[2:5], v[184:187], v[216:219], v[2:5]
	s_barrier
; #define PG8_LDA(dst, b, h) do { _Pragma("unroll") for (int m = 0; m < 4; ++m) _Pragma("unroll") for (int k = 0; k < 2; ++k) dst[m][k] = *(const PG8_LAS bf16x8*)(lds + PG8_SA(b, h) + aoff + m * 2048 + k * 1024); } while (0)
; #define PG8_LDB(dst, b, h) do { _Pragma("unroll") for (int n = 0; n < 2; ++n) _Pragma("unroll") for (int k = 0; k < 2; ++k) dst[n][k] = *(const PG8_LAS bf16x8*)(lds + PG8_SB(b, h) + boff + n * 2048 + k * 1024); } while (0)
; #define PG8_MMA(ai, bj, At, Bt) do { __builtin_amdgcn_s_setprio(1); _Pragma("unroll") for (int m = 0; m < 4; ++m) _Pragma("unroll") for (int n = 0; n < 2; ++n) _Pragma("unroll") for (int k = 0; k < 2; ++k) \
;         acc[ai][bj][m][n] = __builtin_amdgcn_mfma_f32_16x16x32_bf16(Bt[n][k], At[m][k], acc[ai][bj][m][n], 0, 0, 0); __builtin_amdgcn_s_setprio(0); } while (0)
; #define PG8_WAIT_V(n) asm volatile("s_waitcnt vmcnt(" #n ")" ::: "memory")
; #define PG8_WAIT_L(n) asm volatile("s_waitcnt lgkmcnt(" #n ")" ::: "memory")
; #define PG8_BAR __builtin_amdgcn_s_barrier()
; #define PG8_SCHED __builtin_amdgcn_sched_barrier(0)
; template <class Epi, class Sched, bool ALIGN_EPI = false, bool SP2 = false>
; __device__ __forceinline__ void gemm_phase(PG8_LAS unsigned char* lds, const Gemm g, const Sched& S, const Epi& E, const int tid) {
;     ...
;             PG8_LDB(B0, 1, 0); PG8_LDB(B1, 1, 1); PG8_SCHED; PG8_LDA(At, 1, 0); PG8_STAGE(PG8_SA(0, 1), a2 + hstepA, voffA);
;             PG8_WAIT_V(8); PG8_WAIT_L(0); PG8_BAR; PG8_MMA(0, 0, At, B0); PG8_MMA(0, 1, At, B1); PG8_BAR; PG8_SCHED;
;             PG8_LDA(At, 1, 1); PG8_STAGE(PG8_SB(1, 0), b3, voffB); PG8_STAGE(PG8_SB(1, 1), b3 + hstepB, voffB); PG8_STAGE(PG8_SA(1, 0), a3, voffA);
;             PG8_WAIT_V(8); PG8_WAIT_L(0); PG8_BAR; PG8_MMA(1, 0, At, B0); PG8_MMA(1, 1, At, B1); PG8_BAR; PG8_SCHED;
	v_add_u32_e32 v145, 0x18000, v154
	ds_read_b128 v[156:159], v145
	ds_read_b128 v[160:163], v145 offset:1024
	ds_read_b128 v[164:167], v145 offset:2048
	ds_read_b128 v[168:171], v145 offset:3072
	v_add_u32_e32 v145, 0x1c000, v154
	ds_read_b128 v[172:175], v145
	ds_read_b128 v[176:179], v145 offset:1024
	ds_read_b128 v[180:183], v145 offset:2048
	ds_read_b128 v[184:187], v145 offset:3072
	ds_read_b128 v[188:191], v155 offset:32768
	ds_read_b128 v[192:195], v155 offset:33792
	ds_read_b128 v[196:199], v155 offset:34816
	ds_read_b128 v[200:203], v155 offset:35840
	ds_read_b128 v[204:207], v155 offset:36864
	ds_read_b128 v[208:211], v155 offset:37888
	ds_read_b128 v[212:215], v155 offset:38912
	ds_read_b128 v[216:219], v155 offset:39936
	s_add_u32 s26, s42, 0x80000
	s_addc_u32 s27, s43, 0
	s_mov_b32 m0, s51
	s_nop 0
	global_load_lds_dwordx4 v149, s[26:27]
	s_nop 0
	s_mov_b32 m0, s54
	s_nop 0
	global_load_lds_dwordx4 v151, s[26:27]
	s_waitcnt vmcnt(8)
	s_waitcnt lgkmcnt(0)
	s_barrier
	v_mfma_f32_16x16x32_bf16 v[126:129], v[156:159], v[188:191], v[126:129]
	v_mfma_f32_16x16x32_bf16 v[126:129], v[160:163], v[192:195], v[126:129]
	v_mfma_f32_16x16x32_bf16 v[122:125], v[164:167], v[188:191], v[122:125]
	v_mfma_f32_16x16x32_bf16 v[122:125], v[168:171], v[192:195], v[122:125]
	v_mfma_f32_16x16x32_bf16 v[110:113], v[156:159], v[196:199], v[110:113]
	v_mfma_f32_16x16x32_bf16 v[110:113], v[160:163], v[200:203], v[110:113]
	v_mfma_f32_16x16x32_bf16 v[106:109], v[164:167], v[196:199], v[106:109]
	v_mfma_f32_16x16x32_bf16 v[106:109], v[168:171], v[200:203], v[106:109]
	v_mfma_f32_16x16x32_bf16 v[94:97], v[156:159], v[204:207], v[94:97]
	v_mfma_f32_16x16x32_bf16 v[94:97], v[160:163], v[208:211], v[94:97]
	v_mfma_f32_16x16x32_bf16 v[90:93], v[164:167], v[204:207], v[90:93]
	v_mfma_f32_16x16x32_bf16 v[90:93], v[168:171], v[208:211], v[90:93]
	v_mfma_f32_16x16x32_bf16 v[78:81], v[156:159], v[212:215], v[78:81]
	v_mfma_f32_16x16x32_bf16 v[78:81], v[160:163], v[216:219], v[78:81]
	v_mfma_f32_16x16x32_bf16 v[74:77], v[164:167], v[212:215], v[74:77]
	v_mfma_f32_16x16x32_bf16 v[74:77], v[168:171], v[216:219], v[74:77]
	v_mfma_f32_16x16x32_bf16 v[118:121], v[172:175], v[188:191], v[118:121]
	v_mfma_f32_16x16x32_bf16 v[118:121], v[176:179], v[192:195], v[118:121]
	v_mfma_f32_16x16x32_bf16 v[114:117], v[180:183], v[188:191], v[114:117]
	v_mfma_f32_16x16x32_bf16 v[114:117], v[184:187], v[192:195], v[114:117]
	v_mfma_f32_16x16x32_bf16 v[102:105], v[172:175], v[196:199], v[102:105]
	v_mfma_f32_16x16x32_bf16 v[102:105], v[176:179], v[200:203], v[102:105]
	v_mfma_f32_16x16x32_bf16 v[98:101], v[180:183], v[196:199], v[98:101]
	v_mfma_f32_16x16x32_bf16 v[98:101], v[184:187], v[200:203], v[98:101]
	v_mfma_f32_16x16x32_bf16 v[86:89], v[172:175], v[204:207], v[86:89]
	v_mfma_f32_16x16x32_bf16 v[86:89], v[176:179], v[208:211], v[86:89]
	v_mfma_f32_16x16x32_bf16 v[82:85], v[180:183], v[204:207], v[82:85]
	v_mfma_f32_16x16x32_bf16 v[82:85], v[184:187], v[208:211], v[82:85]
	v_mfma_f32_16x16x32_bf16 v[70:73], v[172:175], v[212:215], v[70:73]
	v_mfma_f32_16x16x32_bf16 v[70:73], v[176:179], v[216:219], v[70:73]
	v_mfma_f32_16x16x32_bf16 v[66:69], v[180:183], v[212:215], v[66:69]
	v_mfma_f32_16x16x32_bf16 v[66:69], v[184:187], v[216:219], v[66:69]
	s_barrier
	ds_read_b128 v[188:191], v155 offset:49152
	ds_read_b128 v[192:195], v155 offset:50176
	ds_read_b128 v[196:199], v155 offset:51200
	ds_read_b128 v[200:203], v155 offset:52224
	ds_read_b128 v[204:207], v155 offset:53248
	ds_read_b128 v[208:211], v155 offset:54272
	ds_read_b128 v[212:215], v155 offset:55296
	ds_read_b128 v[216:219], v155 offset:56320
	s_mov_b32 m0, s55
	s_nop 0
	global_load_lds_dwordx4 v150, s[40:41]
	s_nop 0
	s_mov_b32 m0, s56
	s_nop 0
	global_load_lds_dwordx4 v152, s[40:41]
	s_add_u32 s26, s30, 0x80080
	s_addc_u32 s27, s31, 0
	s_mov_b32 m0, s64
	s_nop 0
	global_load_lds_dwordx4 v150, s[26:27]
	s_nop 0
	s_mov_b32 m0, s65
	s_nop 0
	global_load_lds_dwordx4 v152, s[26:27]
	s_mov_b32 m0, s57
	s_nop 0
	global_load_lds_dwordx4 v149, s[38:39]
	s_nop 0
	s_mov_b32 m0, s61
	s_nop 0
	global_load_lds_dwordx4 v151, s[38:39]
	s_waitcnt vmcnt(8)
	s_waitcnt lgkmcnt(0)
	s_barrier
	v_mfma_f32_16x16x32_bf16 v[62:65], v[156:159], v[188:191], v[62:65]
	v_mfma_f32_16x16x32_bf16 v[62:65], v[160:163], v[192:195], v[62:65]
	v_mfma_f32_16x16x32_bf16 v[58:61], v[164:167], v[188:191], v[58:61]
	v_mfma_f32_16x16x32_bf16 v[58:61], v[168:171], v[192:195], v[58:61]
	v_mfma_f32_16x16x32_bf16 v[46:49], v[156:159], v[196:199], v[46:49]
	v_mfma_f32_16x16x32_bf16 v[46:49], v[160:163], v[200:203], v[46:49]
	v_mfma_f32_16x16x32_bf16 v[42:45], v[164:167], v[196:199], v[42:45]
	v_mfma_f32_16x16x32_bf16 v[42:45], v[168:171], v[200:203], v[42:45]
	v_mfma_f32_16x16x32_bf16 v[30:33], v[156:159], v[204:207], v[30:33]
	v_mfma_f32_16x16x32_bf16 v[30:33], v[160:163], v[208:211], v[30:33]
	v_mfma_f32_16x16x32_bf16 v[26:29], v[164:167], v[204:207], v[26:29]
	v_mfma_f32_16x16x32_bf16 v[26:29], v[168:171], v[208:211], v[26:29]
	v_mfma_f32_16x16x32_bf16 v[14:17], v[156:159], v[212:215], v[14:17]
	v_mfma_f32_16x16x32_bf16 v[14:17], v[160:163], v[216:219], v[14:17]
	v_mfma_f32_16x16x32_bf16 v[10:13], v[164:167], v[212:215], v[10:13]
	v_mfma_f32_16x16x32_bf16 v[10:13], v[168:171], v[216:219], v[10:13]
	v_mfma_f32_16x16x32_bf16 v[54:57], v[172:175], v[188:191], v[54:57]
	v_mfma_f32_16x16x32_bf16 v[54:57], v[176:179], v[192:195], v[54:57]
	v_mfma_f32_16x16x32_bf16 v[50:53], v[180:183], v[188:191], v[50:53]
	v_mfma_f32_16x16x32_bf16 v[50:53], v[184:187], v[192:195], v[50:53]
	v_mfma_f32_16x16x32_bf16 v[38:41], v[172:175], v[196:199], v[38:41]
	v_mfma_f32_16x16x32_bf16 v[38:41], v[176:179], v[200:203], v[38:41]
	v_mfma_f32_16x16x32_bf16 v[34:37], v[180:183], v[196:199], v[34:37]
	v_mfma_f32_16x16x32_bf16 v[34:37], v[184:187], v[200:203], v[34:37]
	v_mfma_f32_16x16x32_bf16 v[22:25], v[172:175], v[204:207], v[22:25]
	v_mfma_f32_16x16x32_bf16 v[22:25], v[176:179], v[208:211], v[22:25]
	v_mfma_f32_16x16x32_bf16 v[18:21], v[180:183], v[204:207], v[18:21]
	v_mfma_f32_16x16x32_bf16 v[18:21], v[184:187], v[208:211], v[18:21]
	v_mfma_f32_16x16x32_bf16 v[6:9], v[172:175], v[212:215], v[6:9]
	v_mfma_f32_16x16x32_bf16 v[6:9], v[176:179], v[216:219], v[6:9]
	v_mfma_f32_16x16x32_bf16 v[2:5], v[180:183], v[212:215], v[2:5]
	v_mfma_f32_16x16x32_bf16 v[2:5], v[184:187], v[216:219], v[2:5]
	s_barrier
	s_add_i32 s11, s11, 2
	s_add_u32 s59, s59, 0x100
	s_addc_u32 s67, s67, 0
	s_cmp_gt_u32 s11, 29
	s_mov_b64 s[26:27], s[34:35]
	s_cbranch_scc1 .LBB0_1073

; #define PG8_LDA(dst, b, h) do { _Pragma("unroll") for (int m = 0; m < 4; ++m) _Pragma("unroll") for (int k = 0; k < 2; ++k) dst[m][k] = *(const PG8_LAS bf16x8*)(lds + PG8_SA(b, h) + aoff + m * 2048 + k * 1024); } while (0)
; #define PG8_LDB(dst, b, h) do { _Pragma("unroll") for (int n = 0; n < 2; ++n) _Pragma("unroll") for (int k = 0; k < 2; ++k) dst[n][k] = *(const PG8_LAS bf16x8*)(lds + PG8_SB(b, h) + boff + n * 2048 + k * 1024); } while (0)
; #define PG8_MMA(ai, bj, At, Bt) do { __builtin_amdgcn_s_setprio(1); _Pragma("unroll") for (int m = 0; m < 4; ++m) _Pragma("unroll") for (int n = 0; n < 2; ++n) _Pragma("unroll") for (int k = 0; k < 2; ++k) \
;         acc[ai][bj][m][n] = __builtin_amdgcn_mfma_f32_16x16x32_bf16(Bt[n][k], At[m][k], acc[ai][bj][m][n], 0, 0, 0); __builtin_amdgcn_s_setprio(0); } while (0)
; #define PG8_WAIT_V(n) asm volatile("s_waitcnt vmcnt(" #n ")" ::: "memory")
; #define PG8_WAIT_L(n) asm volatile("s_waitcnt lgkmcnt(" #n ")" ::: "memory")
; #define PG8_BAR __builtin_amdgcn_s_barrier()
; #define PG8_SCHED __builtin_amdgcn_sched_barrier(0)
; template <class Epi, class Sched, bool ALIGN_EPI = false, bool SP2 = false>
; __device__ __forceinline__ void gemm_phase(PG8_LAS unsigned char* lds, const Gemm g, const Sched& S, const Epi& E, const int tid) {
;     ...
;             PG8_LDB(B0, 0, 0); PG8_LDB(B1, 0, 1); PG8_SCHED; PG8_LDA(At, 0, 0); PG8_STAGE(PG8_SA(1, 1), a1 + hstepA, voffA);
;             PG8_WAIT_V(8); PG8_WAIT_L(0); PG8_BAR; PG8_MMA(0, 0, At, B0); PG8_MMA(0, 1, At, B1); PG8_BAR; PG8_SCHED;
;             PG8_LDA(At, 0, 1); PG8_STAGE(PG8_SB(0, 0), b2, voffB); PG8_STAGE(PG8_SB(0, 1), b2 + hstepB, voffB); PG8_STAGE(PG8_SA(0, 0), a2, voffA);
;             PG8_WAIT_V(8); PG8_WAIT_L(0); PG8_BAR; PG8_MMA(1, 0, At, B0); PG8_MMA(1, 1, At, B1); PG8_BAR; PG8_SCHED;
.LBB0_1151:
	v_add_u32_e32 v142, 0x10000, v185
	v_add_u32_e32 v158, 0x14000, v185
	ds_read_b128 v[122:125], v142
	ds_read_b128 v[130:133], v142 offset:1024
	ds_read_b128 v[138:141], v142 offset:2048
	ds_read_b128 v[142:145], v142 offset:3072
	ds_read_b128 v[146:149], v158
	ds_read_b128 v[150:153], v158 offset:1024
	ds_read_b128 v[154:157], v158 offset:2048
	ds_read_b128 v[158:161], v158 offset:3072
	s_cmpk_eq_i32 s89, 0x54
	s_cselect_b32 s34, s26, s83
	s_cselect_b32 s35, s27, s87
	s_cselect_b32 s30, s28, s59
	s_cselect_b32 s31, s29, s67
	s_add_u32 s8, s34, 0x8000
	s_addc_u32 s9, s35, 0
	ds_read_b128 v[162:165], v186
	ds_read_b128 v[166:169], v186 offset:1024
	ds_read_b128 v[170:173], v186 offset:2048
	ds_read_b128 v[174:177], v186 offset:3072
	ds_read_b128 v[188:191], v186 offset:4096
	ds_read_b128 v[192:195], v186 offset:5120
	ds_read_b128 v[196:199], v186 offset:6144
	ds_read_b128 v[200:203], v186 offset:7168
	s_mov_b32 m0, s61
	s_nop 0
	global_load_lds_dwordx4 v0, s[6:7]
	s_nop 0
	s_mov_b32 m0, s64
	s_nop 0
	global_load_lds_dwordx4 v181, s[6:7]
	s_waitcnt vmcnt(8)
	s_waitcnt lgkmcnt(0)
	s_barrier
	v_mfma_f32_16x16x32_bf16 v[134:137], v[122:125], v[162:165], v[134:137]
	v_mfma_f32_16x16x32_bf16 v[134:137], v[130:133], v[166:169], v[134:137]
	v_mfma_f32_16x16x32_bf16 v[126:129], v[138:141], v[162:165], v[126:129]
	v_mfma_f32_16x16x32_bf16 v[126:129], v[142:145], v[166:169], v[126:129]
	v_mfma_f32_16x16x32_bf16 v[110:113], v[122:125], v[170:173], v[110:113]
	v_mfma_f32_16x16x32_bf16 v[110:113], v[130:133], v[174:177], v[110:113]
	v_mfma_f32_16x16x32_bf16 v[106:109], v[138:141], v[170:173], v[106:109]
	v_mfma_f32_16x16x32_bf16 v[106:109], v[142:145], v[174:177], v[106:109]
	v_mfma_f32_16x16x32_bf16 v[94:97], v[122:125], v[188:191], v[94:97]
	v_mfma_f32_16x16x32_bf16 v[94:97], v[130:133], v[192:195], v[94:97]
	v_mfma_f32_16x16x32_bf16 v[90:93], v[138:141], v[188:191], v[90:93]
	v_mfma_f32_16x16x32_bf16 v[90:93], v[142:145], v[192:195], v[90:93]
	v_mfma_f32_16x16x32_bf16 v[78:81], v[122:125], v[196:199], v[78:81]
	v_mfma_f32_16x16x32_bf16 v[78:81], v[130:133], v[200:203], v[78:81]
	v_mfma_f32_16x16x32_bf16 v[74:77], v[138:141], v[196:199], v[74:77]
	v_mfma_f32_16x16x32_bf16 v[74:77], v[142:145], v[200:203], v[74:77]
	v_mfma_f32_16x16x32_bf16 v[118:121], v[146:149], v[162:165], v[118:121]
	v_mfma_f32_16x16x32_bf16 v[118:121], v[150:153], v[166:169], v[118:121]
	v_mfma_f32_16x16x32_bf16 v[114:117], v[154:157], v[162:165], v[114:117]
	v_mfma_f32_16x16x32_bf16 v[114:117], v[158:161], v[166:169], v[114:117]
	v_mfma_f32_16x16x32_bf16 v[102:105], v[146:149], v[170:173], v[102:105]
	v_mfma_f32_16x16x32_bf16 v[102:105], v[150:153], v[174:177], v[102:105]
	v_mfma_f32_16x16x32_bf16 v[98:101], v[154:157], v[170:173], v[98:101]
	v_mfma_f32_16x16x32_bf16 v[98:101], v[158:161], v[174:177], v[98:101]
	v_mfma_f32_16x16x32_bf16 v[86:89], v[146:149], v[188:191], v[86:89]
	v_mfma_f32_16x16x32_bf16 v[86:89], v[150:153], v[192:195], v[86:89]
	v_mfma_f32_16x16x32_bf16 v[82:85], v[154:157], v[188:191], v[82:85]
	v_mfma_f32_16x16x32_bf16 v[82:85], v[158:161], v[192:195], v[82:85]
	v_mfma_f32_16x16x32_bf16 v[70:73], v[146:149], v[196:199], v[70:73]
	v_mfma_f32_16x16x32_bf16 v[70:73], v[150:153], v[200:203], v[70:73]
	v_mfma_f32_16x16x32_bf16 v[66:69], v[154:157], v[196:199], v[66:69]
	v_mfma_f32_16x16x32_bf16 v[66:69], v[158:161], v[200:203], v[66:69]
	s_barrier
	ds_read_b128 v[162:165], v186 offset:16384
	ds_read_b128 v[166:169], v186 offset:17408
	ds_read_b128 v[170:173], v186 offset:18432
	ds_read_b128 v[174:177], v186 offset:19456
	ds_read_b128 v[188:191], v186 offset:20480
	ds_read_b128 v[192:195], v186 offset:21504
	ds_read_b128 v[196:199], v186 offset:22528
	ds_read_b128 v[200:203], v186 offset:23552
	s_mov_b32 m0, s41
	s_nop 0
	global_load_lds_dwordx4 v180, s[30:31]
	s_add_u32 s90, s30, 0x4000
	s_mov_b32 m0, s42
	s_nop 0
	global_load_lds_dwordx4 v182, s[30:31]
	s_addc_u32 s91, s31, 0
	s_mov_b32 m0, s43
	s_nop 0
	global_load_lds_dwordx4 v180, s[90:91]
	s_nop 0
	s_mov_b32 m0, s44
	s_nop 0
	global_load_lds_dwordx4 v182, s[90:91]
	s_nop 0
	s_mov_b32 m0, s10
	s_nop 0
	global_load_lds_dwordx4 v0, s[34:35]
	s_nop 0
	s_mov_b32 m0, s45
	s_nop 0
	global_load_lds_dwordx4 v181, s[34:35]
	s_waitcnt vmcnt(8)
	s_waitcnt lgkmcnt(0)
	s_barrier
	v_mfma_f32_16x16x32_bf16 v[62:65], v[122:125], v[162:165], v[62:65]
	v_mfma_f32_16x16x32_bf16 v[62:65], v[130:133], v[166:169], v[62:65]
	v_mfma_f32_16x16x32_bf16 v[58:61], v[138:141], v[162:165], v[58:61]
	v_mfma_f32_16x16x32_bf16 v[58:61], v[142:145], v[166:169], v[58:61]
	v_mfma_f32_16x16x32_bf16 v[46:49], v[122:125], v[170:173], v[46:49]
	v_mfma_f32_16x16x32_bf16 v[46:49], v[130:133], v[174:177], v[46:49]
	v_mfma_f32_16x16x32_bf16 v[42:45], v[138:141], v[170:173], v[42:45]
	v_mfma_f32_16x16x32_bf16 v[42:45], v[142:145], v[174:177], v[42:45]
	v_mfma_f32_16x16x32_bf16 v[30:33], v[122:125], v[188:191], v[30:33]
	v_mfma_f32_16x16x32_bf16 v[30:33], v[130:133], v[192:195], v[30:33]
	v_mfma_f32_16x16x32_bf16 v[26:29], v[138:141], v[188:191], v[26:29]
	v_mfma_f32_16x16x32_bf16 v[26:29], v[142:145], v[192:195], v[26:29]
	v_mfma_f32_16x16x32_bf16 v[14:17], v[122:125], v[196:199], v[14:17]
	v_mfma_f32_16x16x32_bf16 v[14:17], v[130:133], v[200:203], v[14:17]
	v_mfma_f32_16x16x32_bf16 v[10:13], v[138:141], v[196:199], v[10:13]
	v_mfma_f32_16x16x32_bf16 v[10:13], v[142:145], v[200:203], v[10:13]
	v_mfma_f32_16x16x32_bf16 v[54:57], v[146:149], v[162:165], v[54:57]
	v_mfma_f32_16x16x32_bf16 v[54:57], v[150:153], v[166:169], v[54:57]
	v_mfma_f32_16x16x32_bf16 v[50:53], v[154:157], v[162:165], v[50:53]
	v_mfma_f32_16x16x32_bf16 v[50:53], v[158:161], v[166:169], v[50:53]
	v_mfma_f32_16x16x32_bf16 v[38:41], v[146:149], v[170:173], v[38:41]
	v_mfma_f32_16x16x32_bf16 v[38:41], v[150:153], v[174:177], v[38:41]
	v_mfma_f32_16x16x32_bf16 v[34:37], v[154:157], v[170:173], v[34:37]
	v_mfma_f32_16x16x32_bf16 v[34:37], v[158:161], v[174:177], v[34:37]
	v_mfma_f32_16x16x32_bf16 v[22:25], v[146:149], v[188:191], v[22:25]
	v_mfma_f32_16x16x32_bf16 v[22:25], v[150:153], v[192:195], v[22:25]
	v_mfma_f32_16x16x32_bf16 v[18:21], v[154:157], v[188:191], v[18:21]
	v_mfma_f32_16x16x32_bf16 v[18:21], v[158:161], v[192:195], v[18:21]
	v_mfma_f32_16x16x32_bf16 v[6:9], v[146:149], v[196:199], v[6:9]
	v_mfma_f32_16x16x32_bf16 v[6:9], v[150:153], v[200:203], v[6:9]
	v_mfma_f32_16x16x32_bf16 v[2:5], v[154:157], v[196:199], v[2:5]
	v_mfma_f32_16x16x32_bf16 v[2:5], v[158:161], v[200:203], v[2:5]
	s_barrier
; #define PG8_LDA(dst, b, h) do { _Pragma("unroll") for (int m = 0; m < 4; ++m) _Pragma("unroll") for (int k = 0; k < 2; ++k) dst[m][k] = *(const PG8_LAS bf16x8*)(lds + PG8_SA(b, h) + aoff + m * 2048 + k * 1024); } while (0)
; #define PG8_LDB(dst, b, h) do { _Pragma("unroll") for (int n = 0; n < 2; ++n) _Pragma("unroll") for (int k = 0; k < 2; ++k) dst[n][k] = *(const PG8_LAS bf16x8*)(lds + PG8_SB(b, h) + boff + n * 2048 + k * 1024); } while (0)
; #define PG8_MMA(ai, bj, At, Bt) do { __builtin_amdgcn_s_setprio(1); _Pragma("unroll") for (int m = 0; m < 4; ++m) _Pragma("unroll") for (int n = 0; n < 2; ++n) _Pragma("unroll") for (int k = 0; k < 2; ++k) \
;         acc[ai][bj][m][n] = __builtin_amdgcn_mfma_f32_16x16x32_bf16(Bt[n][k], At[m][k], acc[ai][bj][m][n], 0, 0, 0); __builtin_amdgcn_s_setprio(0); } while (0)
; #define PG8_WAIT_V(n) asm volatile("s_waitcnt vmcnt(" #n ")" ::: "memory")
; #define PG8_WAIT_L(n) asm volatile("s_waitcnt lgkmcnt(" #n ")" ::: "memory")
; #define PG8_BAR __builtin_amdgcn_s_barrier()
; #define PG8_SCHED __builtin_amdgcn_sched_barrier(0)
; template <class Epi, class Sched, bool ALIGN_EPI = false, bool SP2 = false>
; __device__ __forceinline__ void gemm_phase(PG8_LAS unsigned char* lds, const Gemm g, const Sched& S, const Epi& E, const int tid) {
;     ...
;             PG8_LDB(B0, 1, 0); PG8_LDB(B1, 1, 1); PG8_SCHED; PG8_LDA(At, 1, 0); PG8_STAGE(PG8_SA(0, 1), a2 + hstepA, voffA);
;             PG8_WAIT_V(8); PG8_WAIT_L(0); PG8_BAR; PG8_MMA(0, 0, At, B0); PG8_MMA(0, 1, At, B1); PG8_BAR; PG8_SCHED;
;             PG8_LDA(At, 1, 1); PG8_STAGE(PG8_SB(1, 0), b3, voffB); PG8_STAGE(PG8_SB(1, 1), b3 + hstepB, voffB); PG8_STAGE(PG8_SA(1, 0), a3, voffA);
;             PG8_WAIT_V(8); PG8_WAIT_L(0); PG8_BAR; PG8_MMA(1, 0, At, B0); PG8_MMA(1, 1, At, B1); PG8_BAR; PG8_SCHED;
	v_add_u32_e32 v142, 0x18000, v185
	v_add_u32_e32 v158, 0x1c000, v185
	ds_read_b128 v[122:125], v142
	ds_read_b128 v[130:133], v142 offset:1024
	ds_read_b128 v[138:141], v142 offset:2048
	ds_read_b128 v[142:145], v142 offset:3072
	ds_read_b128 v[146:149], v158
	ds_read_b128 v[150:153], v158 offset:1024
	ds_read_b128 v[154:157], v158 offset:2048
	ds_read_b128 v[158:161], v158 offset:3072
	ds_read_b128 v[162:165], v186 offset:32768
	ds_read_b128 v[166:169], v186 offset:33792
	ds_read_b128 v[170:173], v186 offset:34816
	ds_read_b128 v[174:177], v186 offset:35840
	ds_read_b128 v[188:191], v186 offset:36864
	ds_read_b128 v[192:195], v186 offset:37888
	ds_read_b128 v[196:199], v186 offset:38912
	ds_read_b128 v[200:203], v186 offset:39936
	s_add_u32 s34, s34, 0x4000
	s_addc_u32 s35, s35, 0
	s_mov_b32 m0, s46
	s_nop 0
	global_load_lds_dwordx4 v0, s[34:35]
	s_nop 0
	s_mov_b32 m0, s47
	s_nop 0
	global_load_lds_dwordx4 v181, s[34:35]
	s_waitcnt vmcnt(8)
	s_waitcnt lgkmcnt(0)
	s_barrier
	v_mfma_f32_16x16x32_bf16 v[134:137], v[122:125], v[162:165], v[134:137]
	v_mfma_f32_16x16x32_bf16 v[134:137], v[130:133], v[166:169], v[134:137]
	v_mfma_f32_16x16x32_bf16 v[126:129], v[138:141], v[162:165], v[126:129]
	v_mfma_f32_16x16x32_bf16 v[126:129], v[142:145], v[166:169], v[126:129]
	v_mfma_f32_16x16x32_bf16 v[110:113], v[122:125], v[170:173], v[110:113]
	v_mfma_f32_16x16x32_bf16 v[110:113], v[130:133], v[174:177], v[110:113]
	v_mfma_f32_16x16x32_bf16 v[106:109], v[138:141], v[170:173], v[106:109]
	v_mfma_f32_16x16x32_bf16 v[106:109], v[142:145], v[174:177], v[106:109]
	v_mfma_f32_16x16x32_bf16 v[94:97], v[122:125], v[188:191], v[94:97]
	v_mfma_f32_16x16x32_bf16 v[94:97], v[130:133], v[192:195], v[94:97]
	v_mfma_f32_16x16x32_bf16 v[90:93], v[138:141], v[188:191], v[90:93]
	v_mfma_f32_16x16x32_bf16 v[90:93], v[142:145], v[192:195], v[90:93]
	v_mfma_f32_16x16x32_bf16 v[78:81], v[122:125], v[196:199], v[78:81]
	v_mfma_f32_16x16x32_bf16 v[78:81], v[130:133], v[200:203], v[78:81]
	v_mfma_f32_16x16x32_bf16 v[74:77], v[138:141], v[196:199], v[74:77]
	v_mfma_f32_16x16x32_bf16 v[74:77], v[142:145], v[200:203], v[74:77]
	v_mfma_f32_16x16x32_bf16 v[118:121], v[146:149], v[162:165], v[118:121]
	v_mfma_f32_16x16x32_bf16 v[118:121], v[150:153], v[166:169], v[118:121]
	v_mfma_f32_16x16x32_bf16 v[114:117], v[154:157], v[162:165], v[114:117]
	v_mfma_f32_16x16x32_bf16 v[114:117], v[158:161], v[166:169], v[114:117]
	v_mfma_f32_16x16x32_bf16 v[102:105], v[146:149], v[170:173], v[102:105]
	v_mfma_f32_16x16x32_bf16 v[102:105], v[150:153], v[174:177], v[102:105]
	v_mfma_f32_16x16x32_bf16 v[98:101], v[154:157], v[170:173], v[98:101]
	v_mfma_f32_16x16x32_bf16 v[98:101], v[158:161], v[174:177], v[98:101]
	v_mfma_f32_16x16x32_bf16 v[86:89], v[146:149], v[188:191], v[86:89]
	v_mfma_f32_16x16x32_bf16 v[86:89], v[150:153], v[192:195], v[86:89]
	v_mfma_f32_16x16x32_bf16 v[82:85], v[154:157], v[188:191], v[82:85]
	v_mfma_f32_16x16x32_bf16 v[82:85], v[158:161], v[192:195], v[82:85]
	v_mfma_f32_16x16x32_bf16 v[70:73], v[146:149], v[196:199], v[70:73]
	v_mfma_f32_16x16x32_bf16 v[70:73], v[150:153], v[200:203], v[70:73]
	v_mfma_f32_16x16x32_bf16 v[66:69], v[154:157], v[196:199], v[66:69]
	v_mfma_f32_16x16x32_bf16 v[66:69], v[158:161], v[200:203], v[66:69]
	s_barrier
	ds_read_b128 v[162:165], v186 offset:49152
	ds_read_b128 v[166:169], v186 offset:50176
	ds_read_b128 v[170:173], v186 offset:51200
	ds_read_b128 v[174:177], v186 offset:52224
	ds_read_b128 v[188:191], v186 offset:53248
	ds_read_b128 v[192:195], v186 offset:54272
	ds_read_b128 v[196:199], v186 offset:55296
	ds_read_b128 v[200:203], v186 offset:56320
	s_add_u32 s34, s30, 0x8000
	s_addc_u32 s35, s31, 0
	s_mov_b32 m0, s50
	s_nop 0
	global_load_lds_dwordx4 v180, s[34:35]
	s_add_u32 s30, s30, 0xc000
	s_mov_b32 m0, s51
	s_nop 0
	global_load_lds_dwordx4 v182, s[34:35]
	s_addc_u32 s31, s31, 0
	s_mov_b32 m0, s56
	s_nop 0
	global_load_lds_dwordx4 v180, s[30:31]
	s_nop 0
	s_mov_b32 m0, s57
	s_nop 0
	global_load_lds_dwordx4 v182, s[30:31]
	s_mov_b32 m0, s54
	s_nop 0
	global_load_lds_dwordx4 v0, s[8:9]
	s_nop 0
	s_mov_b32 m0, s55
	s_nop 0
	global_load_lds_dwordx4 v181, s[8:9]
	s_waitcnt vmcnt(8)
	s_waitcnt lgkmcnt(0)
	s_barrier
	v_mfma_f32_16x16x32_bf16 v[62:65], v[122:125], v[162:165], v[62:65]
	v_mfma_f32_16x16x32_bf16 v[62:65], v[130:133], v[166:169], v[62:65]
	v_mfma_f32_16x16x32_bf16 v[58:61], v[138:141], v[162:165], v[58:61]
	v_mfma_f32_16x16x32_bf16 v[58:61], v[142:145], v[166:169], v[58:61]
	v_mfma_f32_16x16x32_bf16 v[46:49], v[122:125], v[170:173], v[46:49]
	v_mfma_f32_16x16x32_bf16 v[46:49], v[130:133], v[174:177], v[46:49]
	v_mfma_f32_16x16x32_bf16 v[42:45], v[138:141], v[170:173], v[42:45]
	v_mfma_f32_16x16x32_bf16 v[42:45], v[142:145], v[174:177], v[42:45]
	v_mfma_f32_16x16x32_bf16 v[30:33], v[122:125], v[188:191], v[30:33]
	v_mfma_f32_16x16x32_bf16 v[30:33], v[130:133], v[192:195], v[30:33]
	v_mfma_f32_16x16x32_bf16 v[26:29], v[138:141], v[188:191], v[26:29]
	v_mfma_f32_16x16x32_bf16 v[26:29], v[142:145], v[192:195], v[26:29]
	v_mfma_f32_16x16x32_bf16 v[14:17], v[122:125], v[196:199], v[14:17]
	v_mfma_f32_16x16x32_bf16 v[14:17], v[130:133], v[200:203], v[14:17]
	v_mfma_f32_16x16x32_bf16 v[10:13], v[138:141], v[196:199], v[10:13]
	v_mfma_f32_16x16x32_bf16 v[10:13], v[142:145], v[200:203], v[10:13]
	v_mfma_f32_16x16x32_bf16 v[54:57], v[146:149], v[162:165], v[54:57]
	v_mfma_f32_16x16x32_bf16 v[54:57], v[150:153], v[166:169], v[54:57]
	v_mfma_f32_16x16x32_bf16 v[50:53], v[154:157], v[162:165], v[50:53]
	v_mfma_f32_16x16x32_bf16 v[50:53], v[158:161], v[166:169], v[50:53]
	v_mfma_f32_16x16x32_bf16 v[38:41], v[146:149], v[170:173], v[38:41]
	v_mfma_f32_16x16x32_bf16 v[38:41], v[150:153], v[174:177], v[38:41]
	v_mfma_f32_16x16x32_bf16 v[34:37], v[154:157], v[170:173], v[34:37]
	v_mfma_f32_16x16x32_bf16 v[34:37], v[158:161], v[174:177], v[34:37]
	v_mfma_f32_16x16x32_bf16 v[22:25], v[146:149], v[188:191], v[22:25]
	v_mfma_f32_16x16x32_bf16 v[22:25], v[150:153], v[192:195], v[22:25]
	v_mfma_f32_16x16x32_bf16 v[18:21], v[154:157], v[188:191], v[18:21]
	v_mfma_f32_16x16x32_bf16 v[18:21], v[158:161], v[192:195], v[18:21]
	v_mfma_f32_16x16x32_bf16 v[6:9], v[146:149], v[196:199], v[6:9]
	v_mfma_f32_16x16x32_bf16 v[6:9], v[150:153], v[200:203], v[6:9]
	v_mfma_f32_16x16x32_bf16 v[2:5], v[154:157], v[196:199], v[2:5]
	v_mfma_f32_16x16x32_bf16 v[2:5], v[158:161], v[200:203], v[2:5]
	s_barrier
	s_add_i32 s89, s89, 2
	s_add_u32 s59, s59, 0x10000
	s_addc_u32 s67, s67, 0
	s_add_u32 s83, s83, 0x10000
	s_addc_u32 s87, s87, 0
	s_add_u32 s6, s6, 0x10000
	s_addc_u32 s7, s7, 0
	s_cmpk_gt_u32 s89, 0x55
	s_cbranch_scc0 .LBB0_1151
	s_and_b64 vcc, exec, s[20:21]
	s_cbranch_vccz .LBB0_1154
	s_barrier
